# GEMM K-loops: first K-iteration peeled with C=0 in the first MFMA of each accumulator, 256 zeroing v_mov per unit removed (on top of prep_seg load batching)
# speedup vs baseline: 1.0331x; 1.0109x over previous
; #define PG8_STAGE(bufoff, gbase, voff) do { _Pragma("unroll") for (int _i = 0; _i < 2; ++_i) \
;         __builtin_amdgcn_global_load_lds((const unsigned*)((const char*)(gbase) + (voff)[_i]), (PG8_LAS unsigned*)(lds + (bufoff) + ldsw + _i * 8192), 16, 0, 0); } while (0)
; #define PG8_LDA(dst, b, h) do { _Pragma("unroll") for (int m = 0; m < 4; ++m) _Pragma("unroll") for (int k = 0; k < 2; ++k) dst[m][k] = *(const PG8_LAS bf16x8*)(lds + PG8_SA(b, h) + aoff + m * 2048 + k * 1024); } while (0)
; #define PG8_LDB(dst, b, h) do { _Pragma("unroll") for (int n = 0; n < 2; ++n) _Pragma("unroll") for (int k = 0; k < 2; ++k) dst[n][k] = *(const PG8_LAS bf16x8*)(lds + PG8_SB(b, h) + boff + n * 2048 + k * 1024); } while (0)
; #define PG8_MMA(ai, bj, At, Bt) do { __builtin_amdgcn_s_setprio(1); _Pragma("unroll") for (int m = 0; m < 4; ++m) _Pragma("unroll") for (int n = 0; n < 2; ++n) _Pragma("unroll") for (int k = 0; k < 2; ++k) \
;         acc[ai][bj][m][n] = __builtin_amdgcn_mfma_f32_16x16x32_bf16(Bt[n][k], At[m][k], acc[ai][bj][m][n], 0, 0, 0); __builtin_amdgcn_s_setprio(0); } while (0)
; #define PG8_WAIT_V(n) asm volatile("s_waitcnt vmcnt(" #n ")" ::: "memory")
; #define PG8_WAIT_L(n) asm volatile("s_waitcnt lgkmcnt(" #n ")" ::: "memory")
; #define PG8_BAR __builtin_amdgcn_s_barrier()
; #define PG8_SCHED __builtin_amdgcn_sched_barrier(0)
; template <class Epi, class Sched, bool ALIGN_EPI = false, bool SP2 = false>
; __device__ __forceinline__ void gemm_phase(PG8_LAS unsigned char* lds, const Gemm g, const Sched& S, const Epi& E, const int wave_in) {
;     ...
;     f32x4 acc[2][2][4][2];
; #pragma unroll
;     for (int a = 0; a < 2; ++a)
; #pragma unroll
;         for (int b = 0; b < 2; ++b)
; #pragma unroll
;             for (int m = 0; m < 4; ++m)
; #pragma unroll
;                 for (int n = 0; n < 2; ++n) acc[a][b][m][n] = (f32x4){0.f, 0.f, 0.f, 0.f};
;     ...
;             PG8_LDB(B0, 0, 0); PG8_LDB(B1, 0, 1); PG8_SCHED; PG8_LDA(At, 0, 0); PG8_STAGE(PG8_SA(1, 1), a1 + hstep, voffA);
;             PG8_WAIT_V(8); PG8_WAIT_L(0); PG8_BAR; PG8_MMA(0, 0, At, B0); PG8_MMA(0, 1, At, B1); PG8_BAR; PG8_SCHED;
;             PG8_LDA(At, 0, 1); PG8_STAGE(PG8_SB(0, 0), b2, voffB); PG8_STAGE(PG8_SB(0, 1), b2 + hstep, voffB); PG8_STAGE(PG8_SA(0, 0), a2, voffA);
;             PG8_WAIT_V(8); PG8_WAIT_L(0); PG8_BAR; PG8_MMA(1, 0, At, B0); PG8_MMA(1, 1, At, B1); PG8_BAR; PG8_SCHED;
.LBB0_185:
	v_readlane_b32 s2, v255, 47
	v_readlane_b32 s3, v255, 48
	s_andn2_b64 vcc, exec, s[2:3]
	s_waitcnt lgkmcnt(0)
	s_cbranch_vccnz .Lkz_skip_0
	s_add_u32 s2, s6, 0x80
	s_addc_u32 s3, s7, 0
	s_add_u32 s6, s4, 0x100
	s_addc_u32 s7, s5, 0
	s_mov_b32 s4, 0
	ds_read_b128 v[128:131], v204
	ds_read_b128 v[132:135], v204 offset:1024
	ds_read_b128 v[136:139], v204 offset:2048
	ds_read_b128 v[140:143], v204 offset:3072
	ds_read_b128 v[144:147], v205
	ds_read_b128 v[174:177], v205 offset:1024
	ds_read_b128 v[178:181], v205 offset:2048
	ds_read_b128 v[182:185], v205 offset:3072
	s_add_i32 s28, s4, 2
	s_add_u32 s29, s2, 0x80
	s_addc_u32 s5, s3, 0
	s_cmp_eq_u32 s12, s4
	s_cselect_b32 s4, s40, s29
	s_cselect_b32 s5, s41, s5
	s_cselect_b32 s37, s81, s7
	s_cselect_b32 s36, s80, s6
	v_lshl_add_u64 v[148:149], s[2:3], 0, v[164:165]
	s_add_i32 m0, s35, 0xc000
	ds_read_b128 v[186:189], v206
	ds_read_b128 v[190:193], v206 offset:1024
	ds_read_b128 v[194:197], v206 offset:2048
	ds_read_b128 v[198:201], v206 offset:3072
	ds_read_b128 v[220:223], v206 offset:4096
	ds_read_b128 v[224:227], v206 offset:5120
	ds_read_b128 v[228:231], v206 offset:6144
	ds_read_b128 v[232:235], v206 offset:7168
	global_load_lds_dwordx4 v[148:149], off
	v_lshl_add_u64 v[148:149], s[2:3], 0, v[166:167]
	s_add_i32 m0, s35, 0xe000
	s_nop 0
	global_load_lds_dwordx4 v[148:149], off
	s_waitcnt vmcnt(8)
	s_waitcnt lgkmcnt(0)
	s_barrier
	s_setprio 1
	s_waitcnt lgkmcnt(0)
	v_mfma_f32_16x16x32_bf16 v[112:115], v[128:131], v[186:189], 0
	v_mfma_f32_16x16x32_bf16 v[124:127], v[136:139], v[186:189], 0
	v_mfma_f32_16x16x32_bf16 v[108:111], v[128:131], v[194:197], 0
	v_mfma_f32_16x16x32_bf16 v[104:107], v[136:139], v[194:197], 0
	v_mfma_f32_16x16x32_bf16 v[92:95], v[128:131], v[220:223], 0
	v_mfma_f32_16x16x32_bf16 v[88:91], v[136:139], v[220:223], 0
	v_mfma_f32_16x16x32_bf16 v[76:79], v[128:131], v[228:231], 0
	v_mfma_f32_16x16x32_bf16 v[72:75], v[136:139], v[228:231], 0
	v_mfma_f32_16x16x32_bf16 v[112:115], v[132:135], v[190:193], v[112:115]
	v_mfma_f32_16x16x32_bf16 v[124:127], v[140:143], v[190:193], v[124:127]
	v_mfma_f32_16x16x32_bf16 v[108:111], v[132:135], v[198:201], v[108:111]
	v_mfma_f32_16x16x32_bf16 v[104:107], v[140:143], v[198:201], v[104:107]
	v_mfma_f32_16x16x32_bf16 v[92:95], v[132:135], v[224:227], v[92:95]
	v_mfma_f32_16x16x32_bf16 v[88:91], v[140:143], v[224:227], v[88:91]
	v_mfma_f32_16x16x32_bf16 v[76:79], v[132:135], v[232:235], v[76:79]
	v_mfma_f32_16x16x32_bf16 v[72:75], v[140:143], v[232:235], v[72:75]
	s_setprio 0
	s_setprio 1
	v_mfma_f32_16x16x32_bf16 v[120:123], v[144:147], v[186:189], 0
	v_mfma_f32_16x16x32_bf16 v[116:119], v[178:181], v[186:189], 0
	v_mfma_f32_16x16x32_bf16 v[100:103], v[144:147], v[194:197], 0
	v_mfma_f32_16x16x32_bf16 v[96:99], v[178:181], v[194:197], 0
	v_mfma_f32_16x16x32_bf16 v[84:87], v[144:147], v[220:223], 0
	v_mfma_f32_16x16x32_bf16 v[80:83], v[178:181], v[220:223], 0
	v_mfma_f32_16x16x32_bf16 v[68:71], v[144:147], v[228:231], 0
	v_mfma_f32_16x16x32_bf16 v[64:67], v[178:181], v[228:231], 0
	v_mfma_f32_16x16x32_bf16 v[120:123], v[174:177], v[190:193], v[120:123]
	v_mfma_f32_16x16x32_bf16 v[116:119], v[182:185], v[190:193], v[116:119]
	v_mfma_f32_16x16x32_bf16 v[100:103], v[174:177], v[198:201], v[100:103]
	v_mfma_f32_16x16x32_bf16 v[96:99], v[182:185], v[198:201], v[96:99]
	v_mfma_f32_16x16x32_bf16 v[84:87], v[174:177], v[224:227], v[84:87]
	v_mfma_f32_16x16x32_bf16 v[80:83], v[182:185], v[224:227], v[80:83]
	v_mfma_f32_16x16x32_bf16 v[68:71], v[174:177], v[232:235], v[68:71]
	v_mfma_f32_16x16x32_bf16 v[64:67], v[182:185], v[232:235], v[64:67]
	s_setprio 0
	s_barrier
	s_add_i32 s29, s34, s31
	v_lshl_add_u64 v[148:149], s[36:37], 0, v[152:153]
	s_mov_b32 m0, s29
	ds_read_b128 v[186:189], v206 offset:16384
	ds_read_b128 v[190:193], v206 offset:17408
	ds_read_b128 v[194:197], v206 offset:18432
	ds_read_b128 v[198:201], v206 offset:19456
	ds_read_b128 v[220:223], v206 offset:20480
	ds_read_b128 v[224:227], v206 offset:21504
	ds_read_b128 v[228:231], v206 offset:22528
	ds_read_b128 v[232:235], v206 offset:23552
	global_load_lds_dwordx4 v[148:149], off
	s_add_i32 m0, s29, 0x2000
	v_lshl_add_u64 v[214:215], s[36:37], 0, v[156:157]
	s_add_u32 s36, s36, s16
	s_addc_u32 s37, s37, s17
	s_add_i32 s29, s94, s31
	global_load_lds_dwordx4 v[214:215], off
	v_lshl_add_u64 v[236:237], s[36:37], 0, v[152:153]
	s_mov_b32 m0, s29
	v_lshl_add_u64 v[238:239], s[36:37], 0, v[156:157]
	global_load_lds_dwordx4 v[236:237], off
	s_add_i32 m0, s29, 0x2000
	v_lshl_add_u64 v[240:241], s[4:5], 0, v[150:151]
	global_load_lds_dwordx4 v[238:239], off
	s_mov_b32 m0, s35
	v_lshl_add_u64 v[242:243], s[4:5], 0, v[154:155]
	global_load_lds_dwordx4 v[240:241], off
	s_mov_b32 m0, s33
	s_nop 0
	global_load_lds_dwordx4 v[242:243], off
	s_waitcnt vmcnt(8)
	s_waitcnt lgkmcnt(0)
	s_barrier
; #define PG8_STAGE(bufoff, gbase, voff) do { _Pragma("unroll") for (int _i = 0; _i < 2; ++_i) \
;         __builtin_amdgcn_global_load_lds((const unsigned*)((const char*)(gbase) + (voff)[_i]), (PG8_LAS unsigned*)(lds + (bufoff) + ldsw + _i * 8192), 16, 0, 0); } while (0)
; #define PG8_LDA(dst, b, h) do { _Pragma("unroll") for (int m = 0; m < 4; ++m) _Pragma("unroll") for (int k = 0; k < 2; ++k) dst[m][k] = *(const PG8_LAS bf16x8*)(lds + PG8_SA(b, h) + aoff + m * 2048 + k * 1024); } while (0)
; #define PG8_LDB(dst, b, h) do { _Pragma("unroll") for (int n = 0; n < 2; ++n) _Pragma("unroll") for (int k = 0; k < 2; ++k) dst[n][k] = *(const PG8_LAS bf16x8*)(lds + PG8_SB(b, h) + boff + n * 2048 + k * 1024); } while (0)
; #define PG8_MMA(ai, bj, At, Bt) do { __builtin_amdgcn_s_setprio(1); _Pragma("unroll") for (int m = 0; m < 4; ++m) _Pragma("unroll") for (int n = 0; n < 2; ++n) _Pragma("unroll") for (int k = 0; k < 2; ++k) \
;         acc[ai][bj][m][n] = __builtin_amdgcn_mfma_f32_16x16x32_bf16(Bt[n][k], At[m][k], acc[ai][bj][m][n], 0, 0, 0); __builtin_amdgcn_s_setprio(0); } while (0)
; #define PG8_WAIT_V(n) asm volatile("s_waitcnt vmcnt(" #n ")" ::: "memory")
; #define PG8_WAIT_L(n) asm volatile("s_waitcnt lgkmcnt(" #n ")" ::: "memory")
; #define PG8_BAR __builtin_amdgcn_s_barrier()
; #define PG8_SCHED __builtin_amdgcn_sched_barrier(0)
; template <class Epi, class Sched, bool ALIGN_EPI = false, bool SP2 = false>
; __device__ __forceinline__ void gemm_phase(PG8_LAS unsigned char* lds, const Gemm g, const Sched& S, const Epi& E, const int wave_in) {
;     ...
;             PG8_WAIT_V(8); PG8_WAIT_L(0); PG8_BAR; PG8_MMA(0, 0, At, B0); PG8_MMA(0, 1, At, B1); PG8_BAR; PG8_SCHED;
;             PG8_LDA(At, 0, 1); PG8_STAGE(PG8_SB(0, 0), b2, voffB); PG8_STAGE(PG8_SB(0, 1), b2 + hstep, voffB); PG8_STAGE(PG8_SA(0, 0), a2, voffA);
;             PG8_WAIT_V(8); PG8_WAIT_L(0); PG8_BAR; PG8_MMA(1, 0, At, B0); PG8_MMA(1, 1, At, B1); PG8_BAR; PG8_SCHED;
;             PG8_LDB(B0, 1, 0); PG8_LDB(B1, 1, 1); PG8_SCHED; PG8_LDA(At, 1, 0); PG8_STAGE(PG8_SA(0, 1), a2 + hstep, voffA);
;             PG8_WAIT_V(8); PG8_WAIT_L(0); PG8_BAR; PG8_MMA(0, 0, At, B0); PG8_MMA(0, 1, At, B1); PG8_BAR; PG8_SCHED;
	s_setprio 1
	s_waitcnt lgkmcnt(0)
	v_mfma_f32_16x16x32_bf16 v[60:63], v[128:131], v[186:189], 0
	v_mfma_f32_16x16x32_bf16 v[56:59], v[136:139], v[186:189], 0
	v_mfma_f32_16x16x32_bf16 v[44:47], v[128:131], v[194:197], 0
	v_mfma_f32_16x16x32_bf16 v[40:43], v[136:139], v[194:197], 0
	v_mfma_f32_16x16x32_bf16 v[28:31], v[128:131], v[220:223], 0
	v_mfma_f32_16x16x32_bf16 v[24:27], v[136:139], v[220:223], 0
	v_mfma_f32_16x16x32_bf16 v[12:15], v[128:131], v[228:231], 0
	v_mfma_f32_16x16x32_bf16 v[8:11], v[136:139], v[228:231], 0
	v_mfma_f32_16x16x32_bf16 v[60:63], v[132:135], v[190:193], v[60:63]
	v_mfma_f32_16x16x32_bf16 v[56:59], v[140:143], v[190:193], v[56:59]
	v_mfma_f32_16x16x32_bf16 v[44:47], v[132:135], v[198:201], v[44:47]
	v_mfma_f32_16x16x32_bf16 v[40:43], v[140:143], v[198:201], v[40:43]
	v_mfma_f32_16x16x32_bf16 v[28:31], v[132:135], v[224:227], v[28:31]
	v_mfma_f32_16x16x32_bf16 v[24:27], v[140:143], v[224:227], v[24:27]
	v_mfma_f32_16x16x32_bf16 v[12:15], v[132:135], v[232:235], v[12:15]
	v_mfma_f32_16x16x32_bf16 v[8:11], v[140:143], v[232:235], v[8:11]
	s_setprio 0
	s_setprio 1
	v_mfma_f32_16x16x32_bf16 v[52:55], v[144:147], v[186:189], 0
	v_mfma_f32_16x16x32_bf16 v[48:51], v[178:181], v[186:189], 0
	v_mfma_f32_16x16x32_bf16 v[36:39], v[144:147], v[194:197], 0
	v_mfma_f32_16x16x32_bf16 v[32:35], v[178:181], v[194:197], 0
	v_mfma_f32_16x16x32_bf16 v[20:23], v[144:147], v[220:223], 0
	v_mfma_f32_16x16x32_bf16 v[16:19], v[178:181], v[220:223], 0
	v_mfma_f32_16x16x32_bf16 v[4:7], v[144:147], v[228:231], 0
	v_mfma_f32_16x16x32_bf16 v[0:3], v[178:181], v[228:231], 0
	v_mfma_f32_16x16x32_bf16 v[52:55], v[174:177], v[190:193], v[52:55]
	v_mfma_f32_16x16x32_bf16 v[48:51], v[182:185], v[190:193], v[48:51]
	v_mfma_f32_16x16x32_bf16 v[36:39], v[174:177], v[198:201], v[36:39]
	v_mfma_f32_16x16x32_bf16 v[32:35], v[182:185], v[198:201], v[32:35]
	v_mfma_f32_16x16x32_bf16 v[20:23], v[174:177], v[224:227], v[20:23]
	v_mfma_f32_16x16x32_bf16 v[16:19], v[182:185], v[224:227], v[16:19]
	v_mfma_f32_16x16x32_bf16 v[4:7], v[174:177], v[232:235], v[4:7]
	v_mfma_f32_16x16x32_bf16 v[0:3], v[182:185], v[232:235], v[0:3]
	s_setprio 0
	s_barrier
	s_add_i32 s29, 0, 0x18000
	s_add_i32 s36, 0, 0x1c000
	v_add_u32_e32 v140, s29, v203
	v_add_u32_e32 v158, s36, v203
	ds_read_b128 v[128:131], v140
	ds_read_b128 v[132:135], v140 offset:1024
	ds_read_b128 v[136:139], v140 offset:2048
	ds_read_b128 v[140:143], v140 offset:3072
	ds_read_b128 v[144:147], v158
	ds_read_b128 v[174:177], v158 offset:1024
	ds_read_b128 v[178:181], v158 offset:2048
	ds_read_b128 v[182:185], v158 offset:3072
	s_add_u32 s4, s4, s16
	s_addc_u32 s5, s5, s17
	s_mov_b32 m0, s96
	v_lshl_add_u64 v[244:245], s[4:5], 0, v[150:151]
	ds_read_b128 v[186:189], v206 offset:32768
	ds_read_b128 v[190:193], v206 offset:33792
	ds_read_b128 v[194:197], v206 offset:34816
	ds_read_b128 v[198:201], v206 offset:35840
	ds_read_b128 v[220:223], v206 offset:36864
	ds_read_b128 v[224:227], v206 offset:37888
	ds_read_b128 v[228:231], v206 offset:38912
	ds_read_b128 v[232:235], v206 offset:39936
	global_load_lds_dwordx4 v[244:245], off
	v_lshl_add_u64 v[244:245], s[4:5], 0, v[154:155]
	s_mov_b32 m0, s97
	s_nop 0
	global_load_lds_dwordx4 v[244:245], off
	s_waitcnt vmcnt(8)
	s_waitcnt lgkmcnt(0)
	s_barrier
	s_setprio 1
	s_waitcnt lgkmcnt(0)
	v_mfma_f32_16x16x32_bf16 v[112:115], v[128:131], v[186:189], v[112:115]
	v_mfma_f32_16x16x32_bf16 v[124:127], v[136:139], v[186:189], v[124:127]
	v_mfma_f32_16x16x32_bf16 v[108:111], v[128:131], v[194:197], v[108:111]
	v_mfma_f32_16x16x32_bf16 v[104:107], v[136:139], v[194:197], v[104:107]
	v_mfma_f32_16x16x32_bf16 v[92:95], v[128:131], v[220:223], v[92:95]
	v_mfma_f32_16x16x32_bf16 v[88:91], v[136:139], v[220:223], v[88:91]
	v_mfma_f32_16x16x32_bf16 v[76:79], v[128:131], v[228:231], v[76:79]
	v_mfma_f32_16x16x32_bf16 v[72:75], v[136:139], v[228:231], v[72:75]
	v_mfma_f32_16x16x32_bf16 v[112:115], v[132:135], v[190:193], v[112:115]
	v_mfma_f32_16x16x32_bf16 v[124:127], v[140:143], v[190:193], v[124:127]
	v_mfma_f32_16x16x32_bf16 v[108:111], v[132:135], v[198:201], v[108:111]
	v_mfma_f32_16x16x32_bf16 v[104:107], v[140:143], v[198:201], v[104:107]
	v_mfma_f32_16x16x32_bf16 v[92:95], v[132:135], v[224:227], v[92:95]
	v_mfma_f32_16x16x32_bf16 v[88:91], v[140:143], v[224:227], v[88:91]
	v_mfma_f32_16x16x32_bf16 v[76:79], v[132:135], v[232:235], v[76:79]
	v_mfma_f32_16x16x32_bf16 v[72:75], v[140:143], v[232:235], v[72:75]
	s_setprio 0
	s_setprio 1
	v_mfma_f32_16x16x32_bf16 v[120:123], v[144:147], v[186:189], v[120:123]
	v_mfma_f32_16x16x32_bf16 v[116:119], v[178:181], v[186:189], v[116:119]
	v_mfma_f32_16x16x32_bf16 v[100:103], v[144:147], v[194:197], v[100:103]
	v_mfma_f32_16x16x32_bf16 v[96:99], v[178:181], v[194:197], v[96:99]
	v_mfma_f32_16x16x32_bf16 v[84:87], v[144:147], v[220:223], v[84:87]
	v_mfma_f32_16x16x32_bf16 v[80:83], v[178:181], v[220:223], v[80:83]
	v_mfma_f32_16x16x32_bf16 v[68:71], v[144:147], v[228:231], v[68:71]
	v_mfma_f32_16x16x32_bf16 v[64:67], v[178:181], v[228:231], v[64:67]
	v_mfma_f32_16x16x32_bf16 v[120:123], v[174:177], v[190:193], v[120:123]
	v_mfma_f32_16x16x32_bf16 v[116:119], v[182:185], v[190:193], v[116:119]
	v_mfma_f32_16x16x32_bf16 v[100:103], v[174:177], v[198:201], v[100:103]
	v_mfma_f32_16x16x32_bf16 v[96:99], v[182:185], v[198:201], v[96:99]
	v_mfma_f32_16x16x32_bf16 v[84:87], v[174:177], v[224:227], v[84:87]
	v_mfma_f32_16x16x32_bf16 v[80:83], v[182:185], v[224:227], v[80:83]
	v_mfma_f32_16x16x32_bf16 v[68:71], v[174:177], v[232:235], v[68:71]
	v_mfma_f32_16x16x32_bf16 v[64:67], v[182:185], v[232:235], v[64:67]
	s_setprio 0
	s_barrier
; #define PG8_STAGE(bufoff, gbase, voff) do { _Pragma("unroll") for (int _i = 0; _i < 2; ++_i) \
;         __builtin_amdgcn_global_load_lds((const unsigned*)((const char*)(gbase) + (voff)[_i]), (PG8_LAS unsigned*)(lds + (bufoff) + ldsw + _i * 8192), 16, 0, 0); } while (0)
; #define PG8_LDA(dst, b, h) do { _Pragma("unroll") for (int m = 0; m < 4; ++m) _Pragma("unroll") for (int k = 0; k < 2; ++k) dst[m][k] = *(const PG8_LAS bf16x8*)(lds + PG8_SA(b, h) + aoff + m * 2048 + k * 1024); } while (0)
; #define PG8_LDB(dst, b, h) do { _Pragma("unroll") for (int n = 0; n < 2; ++n) _Pragma("unroll") for (int k = 0; k < 2; ++k) dst[n][k] = *(const PG8_LAS bf16x8*)(lds + PG8_SB(b, h) + boff + n * 2048 + k * 1024); } while (0)
; #define PG8_MMA(ai, bj, At, Bt) do { __builtin_amdgcn_s_setprio(1); _Pragma("unroll") for (int m = 0; m < 4; ++m) _Pragma("unroll") for (int n = 0; n < 2; ++n) _Pragma("unroll") for (int k = 0; k < 2; ++k) \
;         acc[ai][bj][m][n] = __builtin_amdgcn_mfma_f32_16x16x32_bf16(Bt[n][k], At[m][k], acc[ai][bj][m][n], 0, 0, 0); __builtin_amdgcn_s_setprio(0); } while (0)
; #define PG8_WAIT_V(n) asm volatile("s_waitcnt vmcnt(" #n ")" ::: "memory")
; #define PG8_BAR __builtin_amdgcn_s_barrier()
; template <class Epi, class Sched, bool ALIGN_EPI = false, bool SP2 = false>
; __device__ __forceinline__ void gemm_phase(PG8_LAS unsigned char* lds, const Gemm g, const Sched& S, const Epi& E, const int wave_in) {
;     ...
;         for (int t = 0; t < nt; t += 2) {
;             const bool last = (t == nt - 2);
;             const char* a1 = cA + (size_t)(t + 1) * kstep;
;             const char* a2 = last ? nA : cA + (size_t)(t + 2) * kstep; const char* b2 = last ? nB : cB + (size_t)(t + 2) * kstep;
;             const char* a3 = a2 + kstep; const char* b3 = b2 + kstep;
;             if (last && has_next) S.a_ready(nxt);
;             if constexpr (SP2) {
;             PG8_LDB(B0, 0, 0); PG8_LDB(B1, 0, 1); PG8_SCHED; PG8_LDA(At, 0, 0); PG8_STAGE(PG8_SA(1, 1), a1 + hstep, voffA);
;     ...
;             PG8_WAIT_V(8); PG8_WAIT_L(0); PG8_BAR; PG8_MMA(0, 0, At, B0); PG8_MMA(0, 1, At, B1); PG8_BAR; PG8_SCHED;
;             PG8_LDA(At, 1, 1); PG8_STAGE(PG8_SB(1, 0), b3, voffB); PG8_STAGE(PG8_SB(1, 1), b3 + hstep, voffB); PG8_STAGE(PG8_SA(1, 0), a3, voffA);
;             PG8_WAIT_V(8); PG8_WAIT_L(0); PG8_BAR; PG8_MMA(1, 0, At, B0); PG8_MMA(1, 1, At, B1); PG8_BAR; PG8_SCHED;
	s_add_i32 s4, s29, s31
	v_lshl_add_u64 v[148:149], v[148:149], 0, s[52:53]
	s_mov_b32 m0, s4
	ds_read_b128 v[186:189], v206 offset:49152
	ds_read_b128 v[190:193], v206 offset:50176
	ds_read_b128 v[194:197], v206 offset:51200
	ds_read_b128 v[198:201], v206 offset:52224
	ds_read_b128 v[220:223], v206 offset:53248
	ds_read_b128 v[224:227], v206 offset:54272
	ds_read_b128 v[228:231], v206 offset:55296
	ds_read_b128 v[232:235], v206 offset:56320
	global_load_lds_dwordx4 v[148:149], off
	v_lshl_add_u64 v[148:149], v[214:215], 0, s[52:53]
	s_add_i32 m0, s4, 0x2000
	s_add_i32 s4, s36, s31
	global_load_lds_dwordx4 v[148:149], off
	v_lshl_add_u64 v[148:149], v[236:237], 0, s[52:53]
	s_mov_b32 m0, s4
	s_nop 0
	global_load_lds_dwordx4 v[148:149], off
	v_lshl_add_u64 v[148:149], v[238:239], 0, s[52:53]
	s_add_i32 m0, s4, 0x2000
	s_nop 0
	global_load_lds_dwordx4 v[148:149], off
	v_lshl_add_u64 v[148:149], v[240:241], 0, s[52:53]
	s_mov_b32 m0, s13
	s_nop 0
	global_load_lds_dwordx4 v[148:149], off
	v_lshl_add_u64 v[148:149], v[242:243], 0, s[52:53]
	s_mov_b32 m0, s14
	s_nop 0
	global_load_lds_dwordx4 v[148:149], off
	s_waitcnt vmcnt(8)
	s_waitcnt lgkmcnt(0)
	s_barrier
	s_setprio 1
	s_waitcnt lgkmcnt(0)
	v_mfma_f32_16x16x32_bf16 v[60:63], v[128:131], v[186:189], v[60:63]
	v_mfma_f32_16x16x32_bf16 v[56:59], v[136:139], v[186:189], v[56:59]
	v_mfma_f32_16x16x32_bf16 v[44:47], v[128:131], v[194:197], v[44:47]
	v_mfma_f32_16x16x32_bf16 v[40:43], v[136:139], v[194:197], v[40:43]
	v_mfma_f32_16x16x32_bf16 v[28:31], v[128:131], v[220:223], v[28:31]
	v_mfma_f32_16x16x32_bf16 v[24:27], v[136:139], v[220:223], v[24:27]
	v_mfma_f32_16x16x32_bf16 v[12:15], v[128:131], v[228:231], v[12:15]
	v_mfma_f32_16x16x32_bf16 v[8:11], v[136:139], v[228:231], v[8:11]
	v_mfma_f32_16x16x32_bf16 v[60:63], v[132:135], v[190:193], v[60:63]
	v_mfma_f32_16x16x32_bf16 v[56:59], v[140:143], v[190:193], v[56:59]
	v_mfma_f32_16x16x32_bf16 v[44:47], v[132:135], v[198:201], v[44:47]
	v_mfma_f32_16x16x32_bf16 v[40:43], v[140:143], v[198:201], v[40:43]
	v_mfma_f32_16x16x32_bf16 v[28:31], v[132:135], v[224:227], v[28:31]
	v_mfma_f32_16x16x32_bf16 v[24:27], v[140:143], v[224:227], v[24:27]
	v_mfma_f32_16x16x32_bf16 v[12:15], v[132:135], v[232:235], v[12:15]
	v_mfma_f32_16x16x32_bf16 v[8:11], v[140:143], v[232:235], v[8:11]
	s_setprio 0
	s_setprio 1
	v_mfma_f32_16x16x32_bf16 v[52:55], v[144:147], v[186:189], v[52:55]
	v_mfma_f32_16x16x32_bf16 v[48:51], v[178:181], v[186:189], v[48:51]
	v_mfma_f32_16x16x32_bf16 v[36:39], v[144:147], v[194:197], v[36:39]
	v_mfma_f32_16x16x32_bf16 v[32:35], v[178:181], v[194:197], v[32:35]
	v_mfma_f32_16x16x32_bf16 v[20:23], v[144:147], v[220:223], v[20:23]
	v_mfma_f32_16x16x32_bf16 v[16:19], v[178:181], v[220:223], v[16:19]
	v_mfma_f32_16x16x32_bf16 v[4:7], v[144:147], v[228:231], v[4:7]
	v_mfma_f32_16x16x32_bf16 v[0:3], v[178:181], v[228:231], v[0:3]
	v_mfma_f32_16x16x32_bf16 v[52:55], v[174:177], v[190:193], v[52:55]
	v_mfma_f32_16x16x32_bf16 v[48:51], v[182:185], v[190:193], v[48:51]
	v_mfma_f32_16x16x32_bf16 v[36:39], v[174:177], v[198:201], v[36:39]
	v_mfma_f32_16x16x32_bf16 v[32:35], v[182:185], v[198:201], v[32:35]
	v_mfma_f32_16x16x32_bf16 v[20:23], v[174:177], v[224:227], v[20:23]
	v_mfma_f32_16x16x32_bf16 v[16:19], v[182:185], v[224:227], v[16:19]
	v_mfma_f32_16x16x32_bf16 v[4:7], v[174:177], v[232:235], v[4:7]
	v_mfma_f32_16x16x32_bf16 v[0:3], v[182:185], v[232:235], v[0:3]
	s_setprio 0
	s_barrier
	s_add_u32 s2, s2, 0x100
	s_addc_u32 s3, s3, 0
	s_add_u32 s6, s6, 0x100
	s_addc_u32 s7, s7, 0
	s_cmp_ge_i32 s28, s15
	s_mov_b32 s4, s28
	s_cbranch_scc1 .Lkz_exit_0
.LBB0_187:
	ds_read_b128 v[128:131], v204
	ds_read_b128 v[132:135], v204 offset:1024
	ds_read_b128 v[136:139], v204 offset:2048
	ds_read_b128 v[140:143], v204 offset:3072
	ds_read_b128 v[144:147], v205
	ds_read_b128 v[174:177], v205 offset:1024
	ds_read_b128 v[178:181], v205 offset:2048
	ds_read_b128 v[182:185], v205 offset:3072
	s_add_i32 s28, s4, 2
	s_add_u32 s29, s2, 0x80
	s_addc_u32 s5, s3, 0
	s_cmp_eq_u32 s12, s4
	s_cselect_b32 s4, s40, s29
	s_cselect_b32 s5, s41, s5
	s_cselect_b32 s37, s81, s7
	s_cselect_b32 s36, s80, s6
	v_lshl_add_u64 v[148:149], s[2:3], 0, v[164:165]
	s_add_i32 m0, s35, 0xc000
	ds_read_b128 v[186:189], v206
	ds_read_b128 v[190:193], v206 offset:1024
	ds_read_b128 v[194:197], v206 offset:2048
	ds_read_b128 v[198:201], v206 offset:3072
	ds_read_b128 v[220:223], v206 offset:4096
	ds_read_b128 v[224:227], v206 offset:5120
	ds_read_b128 v[228:231], v206 offset:6144
	ds_read_b128 v[232:235], v206 offset:7168
	global_load_lds_dwordx4 v[148:149], off
	v_lshl_add_u64 v[148:149], s[2:3], 0, v[166:167]
	s_add_i32 m0, s35, 0xe000
	s_nop 0
	global_load_lds_dwordx4 v[148:149], off
	s_waitcnt vmcnt(8)
	s_waitcnt lgkmcnt(0)
	s_barrier
; #define PG8_STAGE(bufoff, gbase, voff) do { _Pragma("unroll") for (int _i = 0; _i < 2; ++_i) \
;         __builtin_amdgcn_global_load_lds((const unsigned*)((const char*)(gbase) + (voff)[_i]), (PG8_LAS unsigned*)(lds + (bufoff) + ldsw + _i * 8192), 16, 0, 0); } while (0)
; #define PG8_LDA(dst, b, h) do { _Pragma("unroll") for (int m = 0; m < 4; ++m) _Pragma("unroll") for (int k = 0; k < 2; ++k) dst[m][k] = *(const PG8_LAS bf16x8*)(lds + PG8_SA(b, h) + aoff + m * 2048 + k * 1024); } while (0)
; #define PG8_LDB(dst, b, h) do { _Pragma("unroll") for (int n = 0; n < 2; ++n) _Pragma("unroll") for (int k = 0; k < 2; ++k) dst[n][k] = *(const PG8_LAS bf16x8*)(lds + PG8_SB(b, h) + boff + n * 2048 + k * 1024); } while (0)
; #define PG8_MMA(ai, bj, At, Bt) do { __builtin_amdgcn_s_setprio(1); _Pragma("unroll") for (int m = 0; m < 4; ++m) _Pragma("unroll") for (int n = 0; n < 2; ++n) _Pragma("unroll") for (int k = 0; k < 2; ++k) \
;         acc[ai][bj][m][n] = __builtin_amdgcn_mfma_f32_16x16x32_bf16(Bt[n][k], At[m][k], acc[ai][bj][m][n], 0, 0, 0); __builtin_amdgcn_s_setprio(0); } while (0)
; #define PG8_WAIT_V(n) asm volatile("s_waitcnt vmcnt(" #n ")" ::: "memory")
; #define PG8_WAIT_L(n) asm volatile("s_waitcnt lgkmcnt(" #n ")" ::: "memory")
; #define PG8_BAR __builtin_amdgcn_s_barrier()
; #define PG8_SCHED __builtin_amdgcn_sched_barrier(0)
; template <class Epi, class Sched, bool ALIGN_EPI = false, bool SP2 = false>
; __device__ __forceinline__ void gemm_phase(PG8_LAS unsigned char* lds, const Gemm g, const Sched& S, const Epi& E, const int wave_in) {
;     ...
;             PG8_WAIT_V(8); PG8_WAIT_L(0); PG8_BAR; PG8_MMA(0, 0, At, B0); PG8_MMA(0, 1, At, B1); PG8_BAR; PG8_SCHED;
;             PG8_LDA(At, 0, 1); PG8_STAGE(PG8_SB(0, 0), b2, voffB); PG8_STAGE(PG8_SB(0, 1), b2 + hstep, voffB); PG8_STAGE(PG8_SA(0, 0), a2, voffA);
;             PG8_WAIT_V(8); PG8_WAIT_L(0); PG8_BAR; PG8_MMA(1, 0, At, B0); PG8_MMA(1, 1, At, B1); PG8_BAR; PG8_SCHED;
;             PG8_LDB(B0, 1, 0); PG8_LDB(B1, 1, 1); PG8_SCHED; PG8_LDA(At, 1, 0); PG8_STAGE(PG8_SA(0, 1), a2 + hstep, voffA);
;             PG8_WAIT_V(8); PG8_WAIT_L(0); PG8_BAR; PG8_MMA(0, 0, At, B0); PG8_MMA(0, 1, At, B1); PG8_BAR; PG8_SCHED;
	s_setprio 1
	s_waitcnt lgkmcnt(0)
	v_mfma_f32_16x16x32_bf16 v[112:115], v[128:131], v[186:189], v[112:115]
	v_mfma_f32_16x16x32_bf16 v[124:127], v[136:139], v[186:189], v[124:127]
	v_mfma_f32_16x16x32_bf16 v[108:111], v[128:131], v[194:197], v[108:111]
	v_mfma_f32_16x16x32_bf16 v[104:107], v[136:139], v[194:197], v[104:107]
	v_mfma_f32_16x16x32_bf16 v[92:95], v[128:131], v[220:223], v[92:95]
	v_mfma_f32_16x16x32_bf16 v[88:91], v[136:139], v[220:223], v[88:91]
	v_mfma_f32_16x16x32_bf16 v[76:79], v[128:131], v[228:231], v[76:79]
	v_mfma_f32_16x16x32_bf16 v[72:75], v[136:139], v[228:231], v[72:75]
	v_mfma_f32_16x16x32_bf16 v[112:115], v[132:135], v[190:193], v[112:115]
	v_mfma_f32_16x16x32_bf16 v[124:127], v[140:143], v[190:193], v[124:127]
	v_mfma_f32_16x16x32_bf16 v[108:111], v[132:135], v[198:201], v[108:111]
	v_mfma_f32_16x16x32_bf16 v[104:107], v[140:143], v[198:201], v[104:107]
	v_mfma_f32_16x16x32_bf16 v[92:95], v[132:135], v[224:227], v[92:95]
	v_mfma_f32_16x16x32_bf16 v[88:91], v[140:143], v[224:227], v[88:91]
	v_mfma_f32_16x16x32_bf16 v[76:79], v[132:135], v[232:235], v[76:79]
	v_mfma_f32_16x16x32_bf16 v[72:75], v[140:143], v[232:235], v[72:75]
	s_setprio 0
	s_setprio 1
	v_mfma_f32_16x16x32_bf16 v[120:123], v[144:147], v[186:189], v[120:123]
	v_mfma_f32_16x16x32_bf16 v[116:119], v[178:181], v[186:189], v[116:119]
	v_mfma_f32_16x16x32_bf16 v[100:103], v[144:147], v[194:197], v[100:103]
	v_mfma_f32_16x16x32_bf16 v[96:99], v[178:181], v[194:197], v[96:99]
	v_mfma_f32_16x16x32_bf16 v[84:87], v[144:147], v[220:223], v[84:87]
	v_mfma_f32_16x16x32_bf16 v[80:83], v[178:181], v[220:223], v[80:83]
	v_mfma_f32_16x16x32_bf16 v[68:71], v[144:147], v[228:231], v[68:71]
	v_mfma_f32_16x16x32_bf16 v[64:67], v[178:181], v[228:231], v[64:67]
	v_mfma_f32_16x16x32_bf16 v[120:123], v[174:177], v[190:193], v[120:123]
	v_mfma_f32_16x16x32_bf16 v[116:119], v[182:185], v[190:193], v[116:119]
	v_mfma_f32_16x16x32_bf16 v[100:103], v[174:177], v[198:201], v[100:103]
	v_mfma_f32_16x16x32_bf16 v[96:99], v[182:185], v[198:201], v[96:99]
	v_mfma_f32_16x16x32_bf16 v[84:87], v[174:177], v[224:227], v[84:87]
	v_mfma_f32_16x16x32_bf16 v[80:83], v[182:185], v[224:227], v[80:83]
	v_mfma_f32_16x16x32_bf16 v[68:71], v[174:177], v[232:235], v[68:71]
	v_mfma_f32_16x16x32_bf16 v[64:67], v[182:185], v[232:235], v[64:67]
	s_setprio 0
	s_barrier
	s_add_i32 s29, s34, s31
	v_lshl_add_u64 v[148:149], s[36:37], 0, v[152:153]
	s_mov_b32 m0, s29
	ds_read_b128 v[186:189], v206 offset:16384
	ds_read_b128 v[190:193], v206 offset:17408
	ds_read_b128 v[194:197], v206 offset:18432
	ds_read_b128 v[198:201], v206 offset:19456
	ds_read_b128 v[220:223], v206 offset:20480
	ds_read_b128 v[224:227], v206 offset:21504
	ds_read_b128 v[228:231], v206 offset:22528
	ds_read_b128 v[232:235], v206 offset:23552
	global_load_lds_dwordx4 v[148:149], off
	s_add_i32 m0, s29, 0x2000
	v_lshl_add_u64 v[214:215], s[36:37], 0, v[156:157]
	s_add_u32 s36, s36, s16
	s_addc_u32 s37, s37, s17
	s_add_i32 s29, s94, s31
	global_load_lds_dwordx4 v[214:215], off
	v_lshl_add_u64 v[236:237], s[36:37], 0, v[152:153]
	s_mov_b32 m0, s29
	v_lshl_add_u64 v[238:239], s[36:37], 0, v[156:157]
	global_load_lds_dwordx4 v[236:237], off
	s_add_i32 m0, s29, 0x2000
	v_lshl_add_u64 v[240:241], s[4:5], 0, v[150:151]
	global_load_lds_dwordx4 v[238:239], off
	s_mov_b32 m0, s35
	v_lshl_add_u64 v[242:243], s[4:5], 0, v[154:155]
	global_load_lds_dwordx4 v[240:241], off
	s_mov_b32 m0, s33
	s_nop 0
	global_load_lds_dwordx4 v[242:243], off
	s_waitcnt vmcnt(8)
	s_waitcnt lgkmcnt(0)
	s_barrier
	s_setprio 1
	s_waitcnt lgkmcnt(0)
	v_mfma_f32_16x16x32_bf16 v[60:63], v[128:131], v[186:189], v[60:63]
	v_mfma_f32_16x16x32_bf16 v[56:59], v[136:139], v[186:189], v[56:59]
	v_mfma_f32_16x16x32_bf16 v[44:47], v[128:131], v[194:197], v[44:47]
	v_mfma_f32_16x16x32_bf16 v[40:43], v[136:139], v[194:197], v[40:43]
	v_mfma_f32_16x16x32_bf16 v[28:31], v[128:131], v[220:223], v[28:31]
	v_mfma_f32_16x16x32_bf16 v[24:27], v[136:139], v[220:223], v[24:27]
	v_mfma_f32_16x16x32_bf16 v[12:15], v[128:131], v[228:231], v[12:15]
	v_mfma_f32_16x16x32_bf16 v[8:11], v[136:139], v[228:231], v[8:11]
	v_mfma_f32_16x16x32_bf16 v[60:63], v[132:135], v[190:193], v[60:63]
	v_mfma_f32_16x16x32_bf16 v[56:59], v[140:143], v[190:193], v[56:59]
	v_mfma_f32_16x16x32_bf16 v[44:47], v[132:135], v[198:201], v[44:47]
	v_mfma_f32_16x16x32_bf16 v[40:43], v[140:143], v[198:201], v[40:43]
	v_mfma_f32_16x16x32_bf16 v[28:31], v[132:135], v[224:227], v[28:31]
	v_mfma_f32_16x16x32_bf16 v[24:27], v[140:143], v[224:227], v[24:27]
	v_mfma_f32_16x16x32_bf16 v[12:15], v[132:135], v[232:235], v[12:15]
	v_mfma_f32_16x16x32_bf16 v[8:11], v[140:143], v[232:235], v[8:11]
	s_setprio 0
	s_setprio 1
	v_mfma_f32_16x16x32_bf16 v[52:55], v[144:147], v[186:189], v[52:55]
	v_mfma_f32_16x16x32_bf16 v[48:51], v[178:181], v[186:189], v[48:51]
	v_mfma_f32_16x16x32_bf16 v[36:39], v[144:147], v[194:197], v[36:39]
	v_mfma_f32_16x16x32_bf16 v[32:35], v[178:181], v[194:197], v[32:35]
	v_mfma_f32_16x16x32_bf16 v[20:23], v[144:147], v[220:223], v[20:23]
	v_mfma_f32_16x16x32_bf16 v[16:19], v[178:181], v[220:223], v[16:19]
	v_mfma_f32_16x16x32_bf16 v[4:7], v[144:147], v[228:231], v[4:7]
	v_mfma_f32_16x16x32_bf16 v[0:3], v[178:181], v[228:231], v[0:3]
	v_mfma_f32_16x16x32_bf16 v[52:55], v[174:177], v[190:193], v[52:55]
	v_mfma_f32_16x16x32_bf16 v[48:51], v[182:185], v[190:193], v[48:51]
	v_mfma_f32_16x16x32_bf16 v[36:39], v[174:177], v[198:201], v[36:39]
	v_mfma_f32_16x16x32_bf16 v[32:35], v[182:185], v[198:201], v[32:35]
	v_mfma_f32_16x16x32_bf16 v[20:23], v[174:177], v[224:227], v[20:23]
	v_mfma_f32_16x16x32_bf16 v[16:19], v[182:185], v[224:227], v[16:19]
	v_mfma_f32_16x16x32_bf16 v[4:7], v[174:177], v[232:235], v[4:7]
	v_mfma_f32_16x16x32_bf16 v[0:3], v[182:185], v[232:235], v[0:3]
	s_setprio 0
	s_barrier
; #define PG8_STAGE(bufoff, gbase, voff) do { _Pragma("unroll") for (int _i = 0; _i < 2; ++_i) \
;         __builtin_amdgcn_global_load_lds((const unsigned*)((const char*)(gbase) + (voff)[_i]), (PG8_LAS unsigned*)(lds + (bufoff) + ldsw + _i * 8192), 16, 0, 0); } while (0)
; #define PG8_LDA(dst, b, h) do { _Pragma("unroll") for (int m = 0; m < 4; ++m) _Pragma("unroll") for (int k = 0; k < 2; ++k) dst[m][k] = *(const PG8_LAS bf16x8*)(lds + PG8_SA(b, h) + aoff + m * 2048 + k * 1024); } while (0)
; #define PG8_LDB(dst, b, h) do { _Pragma("unroll") for (int n = 0; n < 2; ++n) _Pragma("unroll") for (int k = 0; k < 2; ++k) dst[n][k] = *(const PG8_LAS bf16x8*)(lds + PG8_SB(b, h) + boff + n * 2048 + k * 1024); } while (0)
; #define PG8_MMA(ai, bj, At, Bt) do { __builtin_amdgcn_s_setprio(1); _Pragma("unroll") for (int m = 0; m < 4; ++m) _Pragma("unroll") for (int n = 0; n < 2; ++n) _Pragma("unroll") for (int k = 0; k < 2; ++k) \
;         acc[ai][bj][m][n] = __builtin_amdgcn_mfma_f32_16x16x32_bf16(Bt[n][k], At[m][k], acc[ai][bj][m][n], 0, 0, 0); __builtin_amdgcn_s_setprio(0); } while (0)
; #define PG8_WAIT_V(n) asm volatile("s_waitcnt vmcnt(" #n ")" ::: "memory")
; #define PG8_WAIT_L(n) asm volatile("s_waitcnt lgkmcnt(" #n ")" ::: "memory")
; #define PG8_BAR __builtin_amdgcn_s_barrier()
; #define PG8_SCHED __builtin_amdgcn_sched_barrier(0)
; template <class Epi, class Sched, bool ALIGN_EPI = false, bool SP2 = false>
; __device__ __forceinline__ void gemm_phase(PG8_LAS unsigned char* lds, const Gemm g, const Sched& S, const Epi& E, const int wave_in) {
;     ...
;             PG8_LDB(B0, 1, 0); PG8_LDB(B1, 1, 1); PG8_SCHED; PG8_LDA(At, 1, 0); PG8_STAGE(PG8_SA(0, 1), a2 + hstep, voffA);
;             PG8_WAIT_V(8); PG8_WAIT_L(0); PG8_BAR; PG8_MMA(0, 0, At, B0); PG8_MMA(0, 1, At, B1); PG8_BAR; PG8_SCHED;
;             PG8_LDA(At, 1, 1); PG8_STAGE(PG8_SB(1, 0), b3, voffB); PG8_STAGE(PG8_SB(1, 1), b3 + hstep, voffB); PG8_STAGE(PG8_SA(1, 0), a3, voffA);
	s_add_i32 s29, 0, 0x18000
	s_add_i32 s36, 0, 0x1c000
	v_add_u32_e32 v140, s29, v203
	v_add_u32_e32 v158, s36, v203
	ds_read_b128 v[128:131], v140
	ds_read_b128 v[132:135], v140 offset:1024
	ds_read_b128 v[136:139], v140 offset:2048
	ds_read_b128 v[140:143], v140 offset:3072
	ds_read_b128 v[144:147], v158
	ds_read_b128 v[174:177], v158 offset:1024
	ds_read_b128 v[178:181], v158 offset:2048
	ds_read_b128 v[182:185], v158 offset:3072
	s_add_u32 s4, s4, s16
	s_addc_u32 s5, s5, s17
	s_mov_b32 m0, s96
	v_lshl_add_u64 v[244:245], s[4:5], 0, v[150:151]
	ds_read_b128 v[186:189], v206 offset:32768
	ds_read_b128 v[190:193], v206 offset:33792
	ds_read_b128 v[194:197], v206 offset:34816
	ds_read_b128 v[198:201], v206 offset:35840
	ds_read_b128 v[220:223], v206 offset:36864
	ds_read_b128 v[224:227], v206 offset:37888
	ds_read_b128 v[228:231], v206 offset:38912
	ds_read_b128 v[232:235], v206 offset:39936
	global_load_lds_dwordx4 v[244:245], off
	v_lshl_add_u64 v[244:245], s[4:5], 0, v[154:155]
	s_mov_b32 m0, s97
	s_nop 0
	global_load_lds_dwordx4 v[244:245], off
	s_waitcnt vmcnt(8)
	s_waitcnt lgkmcnt(0)
	s_barrier
	s_setprio 1
	s_waitcnt lgkmcnt(0)
	v_mfma_f32_16x16x32_bf16 v[112:115], v[128:131], v[186:189], v[112:115]
	v_mfma_f32_16x16x32_bf16 v[124:127], v[136:139], v[186:189], v[124:127]
	v_mfma_f32_16x16x32_bf16 v[108:111], v[128:131], v[194:197], v[108:111]
	v_mfma_f32_16x16x32_bf16 v[104:107], v[136:139], v[194:197], v[104:107]
	v_mfma_f32_16x16x32_bf16 v[92:95], v[128:131], v[220:223], v[92:95]
	v_mfma_f32_16x16x32_bf16 v[88:91], v[136:139], v[220:223], v[88:91]
	v_mfma_f32_16x16x32_bf16 v[76:79], v[128:131], v[228:231], v[76:79]
	v_mfma_f32_16x16x32_bf16 v[72:75], v[136:139], v[228:231], v[72:75]
	v_mfma_f32_16x16x32_bf16 v[112:115], v[132:135], v[190:193], v[112:115]
	v_mfma_f32_16x16x32_bf16 v[124:127], v[140:143], v[190:193], v[124:127]
	v_mfma_f32_16x16x32_bf16 v[108:111], v[132:135], v[198:201], v[108:111]
	v_mfma_f32_16x16x32_bf16 v[104:107], v[140:143], v[198:201], v[104:107]
	v_mfma_f32_16x16x32_bf16 v[92:95], v[132:135], v[224:227], v[92:95]
	v_mfma_f32_16x16x32_bf16 v[88:91], v[140:143], v[224:227], v[88:91]
	v_mfma_f32_16x16x32_bf16 v[76:79], v[132:135], v[232:235], v[76:79]
	v_mfma_f32_16x16x32_bf16 v[72:75], v[140:143], v[232:235], v[72:75]
	s_setprio 0
	s_setprio 1
	v_mfma_f32_16x16x32_bf16 v[120:123], v[144:147], v[186:189], v[120:123]
	v_mfma_f32_16x16x32_bf16 v[116:119], v[178:181], v[186:189], v[116:119]
	v_mfma_f32_16x16x32_bf16 v[100:103], v[144:147], v[194:197], v[100:103]
	v_mfma_f32_16x16x32_bf16 v[96:99], v[178:181], v[194:197], v[96:99]
	v_mfma_f32_16x16x32_bf16 v[84:87], v[144:147], v[220:223], v[84:87]
	v_mfma_f32_16x16x32_bf16 v[80:83], v[178:181], v[220:223], v[80:83]
	v_mfma_f32_16x16x32_bf16 v[68:71], v[144:147], v[228:231], v[68:71]
	v_mfma_f32_16x16x32_bf16 v[64:67], v[178:181], v[228:231], v[64:67]
	v_mfma_f32_16x16x32_bf16 v[120:123], v[174:177], v[190:193], v[120:123]
	v_mfma_f32_16x16x32_bf16 v[116:119], v[182:185], v[190:193], v[116:119]
	v_mfma_f32_16x16x32_bf16 v[100:103], v[174:177], v[198:201], v[100:103]
	v_mfma_f32_16x16x32_bf16 v[96:99], v[182:185], v[198:201], v[96:99]
	v_mfma_f32_16x16x32_bf16 v[84:87], v[174:177], v[224:227], v[84:87]
	v_mfma_f32_16x16x32_bf16 v[80:83], v[182:185], v[224:227], v[80:83]
	v_mfma_f32_16x16x32_bf16 v[68:71], v[174:177], v[232:235], v[68:71]
	v_mfma_f32_16x16x32_bf16 v[64:67], v[182:185], v[232:235], v[64:67]
	s_setprio 0
	s_barrier
	s_add_i32 s4, s29, s31
	v_lshl_add_u64 v[148:149], v[148:149], 0, s[52:53]
	s_mov_b32 m0, s4
	ds_read_b128 v[186:189], v206 offset:49152
	ds_read_b128 v[190:193], v206 offset:50176
	ds_read_b128 v[194:197], v206 offset:51200
	ds_read_b128 v[198:201], v206 offset:52224
	ds_read_b128 v[220:223], v206 offset:53248
	ds_read_b128 v[224:227], v206 offset:54272
	ds_read_b128 v[228:231], v206 offset:55296
	ds_read_b128 v[232:235], v206 offset:56320
	global_load_lds_dwordx4 v[148:149], off
	v_lshl_add_u64 v[148:149], v[214:215], 0, s[52:53]
	s_add_i32 m0, s4, 0x2000
	s_add_i32 s4, s36, s31
	global_load_lds_dwordx4 v[148:149], off
	v_lshl_add_u64 v[148:149], v[236:237], 0, s[52:53]
	s_mov_b32 m0, s4
	s_nop 0
	global_load_lds_dwordx4 v[148:149], off
	v_lshl_add_u64 v[148:149], v[238:239], 0, s[52:53]
	s_add_i32 m0, s4, 0x2000
	s_nop 0
	global_load_lds_dwordx4 v[148:149], off
	v_lshl_add_u64 v[148:149], v[240:241], 0, s[52:53]
	s_mov_b32 m0, s13
	s_nop 0
	global_load_lds_dwordx4 v[148:149], off
	v_lshl_add_u64 v[148:149], v[242:243], 0, s[52:53]
	s_mov_b32 m0, s14
	s_nop 0
	global_load_lds_dwordx4 v[148:149], off
	s_waitcnt vmcnt(8)
	s_waitcnt lgkmcnt(0)
	s_barrier
; #define PG8_STAGE(bufoff, gbase, voff) do { _Pragma("unroll") for (int _i = 0; _i < 2; ++_i) \
;         __builtin_amdgcn_global_load_lds((const unsigned*)((const char*)(gbase) + (voff)[_i]), (PG8_LAS unsigned*)(lds + (bufoff) + ldsw + _i * 8192), 16, 0, 0); } while (0)
; #define PG8_LDA(dst, b, h) do { _Pragma("unroll") for (int m = 0; m < 4; ++m) _Pragma("unroll") for (int k = 0; k < 2; ++k) dst[m][k] = *(const PG8_LAS bf16x8*)(lds + PG8_SA(b, h) + aoff + m * 2048 + k * 1024); } while (0)
; #define PG8_LDB(dst, b, h) do { _Pragma("unroll") for (int n = 0; n < 2; ++n) _Pragma("unroll") for (int k = 0; k < 2; ++k) dst[n][k] = *(const PG8_LAS bf16x8*)(lds + PG8_SB(b, h) + boff + n * 2048 + k * 1024); } while (0)
; #define PG8_MMA(ai, bj, At, Bt) do { __builtin_amdgcn_s_setprio(1); _Pragma("unroll") for (int m = 0; m < 4; ++m) _Pragma("unroll") for (int n = 0; n < 2; ++n) _Pragma("unroll") for (int k = 0; k < 2; ++k) \
;         acc[ai][bj][m][n] = __builtin_amdgcn_mfma_f32_16x16x32_bf16(Bt[n][k], At[m][k], acc[ai][bj][m][n], 0, 0, 0); __builtin_amdgcn_s_setprio(0); } while (0)
; #define PG8_WAIT_V(n) asm volatile("s_waitcnt vmcnt(" #n ")" ::: "memory")
; #define PG8_WAIT_L(n) asm volatile("s_waitcnt lgkmcnt(" #n ")" ::: "memory")
; template <class Epi, class Sched, bool ALIGN_EPI = false, bool SP2 = false>
; __device__ __forceinline__ void gemm_phase(PG8_LAS unsigned char* lds, const Gemm g, const Sched& S, const Epi& E, const int wave_in) {
;     ...
; #pragma unroll
;     for (int a = 0; a < 2; ++a)
; #pragma unroll
;         for (int b = 0; b < 2; ++b)
; #pragma unroll
;             for (int m = 0; m < 4; ++m)
; #pragma unroll
;                 for (int n = 0; n < 2; ++n) acc[a][b][m][n] = (f32x4){0.f, 0.f, 0.f, 0.f};
;     ...
;             PG8_WAIT_V(8); PG8_WAIT_L(0); PG8_BAR; PG8_MMA(1, 0, At, B0); PG8_MMA(1, 1, At, B1); PG8_BAR; PG8_SCHED;
;             PG8_LDB(B0, 1, 0); PG8_LDB(B1, 1, 1); PG8_SCHED; PG8_LDA(At, 1, 0); PG8_STAGE(PG8_SA(0, 1), a2 + hstep, voffA);
;             PG8_WAIT_V(8); PG8_WAIT_L(0); PG8_BAR; PG8_MMA(0, 0, At, B0); PG8_MMA(0, 1, At, B1); PG8_BAR; PG8_SCHED;
;             PG8_LDA(At, 1, 1); PG8_STAGE(PG8_SB(1, 0), b3, voffB); PG8_STAGE(PG8_SB(1, 1), b3 + hstep, voffB); PG8_STAGE(PG8_SA(1, 0), a3, voffA);
;             PG8_WAIT_V(8); PG8_WAIT_L(0); PG8_BAR; PG8_MMA(1, 0, At, B0); PG8_MMA(1, 1, At, B1); PG8_BAR; PG8_SCHED;
	s_setprio 1
	s_waitcnt lgkmcnt(0)
	v_mfma_f32_16x16x32_bf16 v[60:63], v[128:131], v[186:189], v[60:63]
	v_mfma_f32_16x16x32_bf16 v[56:59], v[136:139], v[186:189], v[56:59]
	v_mfma_f32_16x16x32_bf16 v[44:47], v[128:131], v[194:197], v[44:47]
	v_mfma_f32_16x16x32_bf16 v[40:43], v[136:139], v[194:197], v[40:43]
	v_mfma_f32_16x16x32_bf16 v[28:31], v[128:131], v[220:223], v[28:31]
	v_mfma_f32_16x16x32_bf16 v[24:27], v[136:139], v[220:223], v[24:27]
	v_mfma_f32_16x16x32_bf16 v[12:15], v[128:131], v[228:231], v[12:15]
	v_mfma_f32_16x16x32_bf16 v[8:11], v[136:139], v[228:231], v[8:11]
	v_mfma_f32_16x16x32_bf16 v[60:63], v[132:135], v[190:193], v[60:63]
	v_mfma_f32_16x16x32_bf16 v[56:59], v[140:143], v[190:193], v[56:59]
	v_mfma_f32_16x16x32_bf16 v[44:47], v[132:135], v[198:201], v[44:47]
	v_mfma_f32_16x16x32_bf16 v[40:43], v[140:143], v[198:201], v[40:43]
	v_mfma_f32_16x16x32_bf16 v[28:31], v[132:135], v[224:227], v[28:31]
	v_mfma_f32_16x16x32_bf16 v[24:27], v[140:143], v[224:227], v[24:27]
	v_mfma_f32_16x16x32_bf16 v[12:15], v[132:135], v[232:235], v[12:15]
	v_mfma_f32_16x16x32_bf16 v[8:11], v[140:143], v[232:235], v[8:11]
	s_setprio 0
	s_setprio 1
	v_mfma_f32_16x16x32_bf16 v[52:55], v[144:147], v[186:189], v[52:55]
	v_mfma_f32_16x16x32_bf16 v[48:51], v[178:181], v[186:189], v[48:51]
	v_mfma_f32_16x16x32_bf16 v[36:39], v[144:147], v[194:197], v[36:39]
	v_mfma_f32_16x16x32_bf16 v[32:35], v[178:181], v[194:197], v[32:35]
	v_mfma_f32_16x16x32_bf16 v[20:23], v[144:147], v[220:223], v[20:23]
	v_mfma_f32_16x16x32_bf16 v[16:19], v[178:181], v[220:223], v[16:19]
	v_mfma_f32_16x16x32_bf16 v[4:7], v[144:147], v[228:231], v[4:7]
	v_mfma_f32_16x16x32_bf16 v[0:3], v[178:181], v[228:231], v[0:3]
	v_mfma_f32_16x16x32_bf16 v[52:55], v[174:177], v[190:193], v[52:55]
	v_mfma_f32_16x16x32_bf16 v[48:51], v[182:185], v[190:193], v[48:51]
	v_mfma_f32_16x16x32_bf16 v[36:39], v[174:177], v[198:201], v[36:39]
	v_mfma_f32_16x16x32_bf16 v[32:35], v[182:185], v[198:201], v[32:35]
	v_mfma_f32_16x16x32_bf16 v[20:23], v[174:177], v[224:227], v[20:23]
	v_mfma_f32_16x16x32_bf16 v[16:19], v[182:185], v[224:227], v[16:19]
	v_mfma_f32_16x16x32_bf16 v[4:7], v[174:177], v[232:235], v[4:7]
	v_mfma_f32_16x16x32_bf16 v[0:3], v[182:185], v[232:235], v[0:3]
	s_setprio 0
	s_barrier
	s_add_u32 s2, s2, 0x100
	s_addc_u32 s3, s3, 0
	s_add_u32 s6, s6, 0x100
	s_addc_u32 s7, s7, 0
	s_cmp_ge_i32 s28, s15
	s_mov_b32 s4, s28
	s_cbranch_scc0 .LBB0_187
.Lkz_exit_0:
	s_branch .LBB0_188
.Lkz_skip_0:
	v_mov_b32_e32 v115, 0
	v_mov_b32_e32 v114, v115
	v_mov_b32_e32 v113, v115
	v_mov_b32_e32 v112, v115
	v_mov_b32_e32 v127, v115
	v_mov_b32_e32 v126, v115
	v_mov_b32_e32 v125, v115
	v_mov_b32_e32 v124, v115
	v_mov_b32_e32 v111, v115
	v_mov_b32_e32 v110, v115
	v_mov_b32_e32 v109, v115
	v_mov_b32_e32 v108, v115
	v_mov_b32_e32 v107, v115
	v_mov_b32_e32 v106, v115
	v_mov_b32_e32 v105, v115
	v_mov_b32_e32 v104, v115
	v_mov_b32_e32 v95, v115
	v_mov_b32_e32 v94, v115
	v_mov_b32_e32 v93, v115
	v_mov_b32_e32 v92, v115
	v_mov_b32_e32 v91, v115
	v_mov_b32_e32 v90, v115
	v_mov_b32_e32 v89, v115
	v_mov_b32_e32 v88, v115
	v_mov_b32_e32 v79, v115
	v_mov_b32_e32 v78, v115
	v_mov_b32_e32 v77, v115
	v_mov_b32_e32 v76, v115
	v_mov_b32_e32 v75, v115
	v_mov_b32_e32 v74, v115
	v_mov_b32_e32 v73, v115
	v_mov_b32_e32 v72, v115
	v_mov_b32_e32 v123, v115
	v_mov_b32_e32 v122, v115
	v_mov_b32_e32 v121, v115
	v_mov_b32_e32 v120, v115
	v_mov_b32_e32 v119, v115
	v_mov_b32_e32 v118, v115
	v_mov_b32_e32 v117, v115
	v_mov_b32_e32 v116, v115
	v_mov_b32_e32 v103, v115
	v_mov_b32_e32 v102, v115
	v_mov_b32_e32 v101, v115
	v_mov_b32_e32 v100, v115
	v_mov_b32_e32 v99, v115
	v_mov_b32_e32 v98, v115
	v_mov_b32_e32 v97, v115
	v_mov_b32_e32 v96, v115
	v_mov_b32_e32 v87, v115
	v_mov_b32_e32 v86, v115
	v_mov_b32_e32 v85, v115
	v_mov_b32_e32 v84, v115
	v_mov_b32_e32 v83, v115
	v_mov_b32_e32 v82, v115
	v_mov_b32_e32 v81, v115
	v_mov_b32_e32 v80, v115
	v_mov_b32_e32 v71, v115
	v_mov_b32_e32 v70, v115
	v_mov_b32_e32 v69, v115
	v_mov_b32_e32 v68, v115
	v_mov_b32_e32 v67, v115
	v_mov_b32_e32 v66, v115
	v_mov_b32_e32 v65, v115
	v_mov_b32_e32 v64, v115
	v_mov_b32_e32 v63, v115
	v_mov_b32_e32 v62, v115
	v_mov_b32_e32 v61, v115
	v_mov_b32_e32 v60, v115
	v_mov_b32_e32 v59, v115
	v_mov_b32_e32 v58, v115
	v_mov_b32_e32 v57, v115
	v_mov_b32_e32 v56, v115
	v_mov_b32_e32 v47, v115
	v_mov_b32_e32 v46, v115
	v_mov_b32_e32 v45, v115
	v_mov_b32_e32 v44, v115
	v_mov_b32_e32 v43, v115
	v_mov_b32_e32 v42, v115
	v_mov_b32_e32 v41, v115
	v_mov_b32_e32 v40, v115
	v_mov_b32_e32 v31, v115
	v_mov_b32_e32 v30, v115
	v_mov_b32_e32 v29, v115
	v_mov_b32_e32 v28, v115
	v_mov_b32_e32 v27, v115
	v_mov_b32_e32 v26, v115
	v_mov_b32_e32 v25, v115
	v_mov_b32_e32 v24, v115
	v_mov_b32_e32 v15, v115
	v_mov_b32_e32 v14, v115
	v_mov_b32_e32 v13, v115
	v_mov_b32_e32 v12, v115
	v_mov_b32_e32 v11, v115
	v_mov_b32_e32 v10, v115
	v_mov_b32_e32 v9, v115
	v_mov_b32_e32 v8, v115
	v_mov_b32_e32 v55, v115
	v_mov_b32_e32 v54, v115
	v_mov_b32_e32 v53, v115
	v_mov_b32_e32 v52, v115
	v_mov_b32_e32 v51, v115
	v_mov_b32_e32 v50, v115
	v_mov_b32_e32 v49, v115
	v_mov_b32_e32 v48, v115
	v_mov_b32_e32 v39, v115
	v_mov_b32_e32 v38, v115
	v_mov_b32_e32 v37, v115
	v_mov_b32_e32 v36, v115
	v_mov_b32_e32 v35, v115
	v_mov_b32_e32 v34, v115
	v_mov_b32_e32 v33, v115
	v_mov_b32_e32 v32, v115
	v_mov_b32_e32 v23, v115
	v_mov_b32_e32 v22, v115
	v_mov_b32_e32 v21, v115
	v_mov_b32_e32 v20, v115
	v_mov_b32_e32 v19, v115
	v_mov_b32_e32 v18, v115
	v_mov_b32_e32 v17, v115
	v_mov_b32_e32 v16, v115
	v_mov_b32_e32 v7, v115
	v_mov_b32_e32 v6, v115
	v_mov_b32_e32 v5, v115
	v_mov_b32_e32 v4, v115
	v_mov_b32_e32 v3, v115
	v_mov_b32_e32 v2, v115
	v_mov_b32_e32 v1, v115
	v_mov_b32_e32 v0, v115

; #define PG8_STAGE(bufoff, gbase, voff) do { _Pragma("unroll") for (int _i = 0; _i < 2; ++_i) \
;         __builtin_amdgcn_global_load_lds((const unsigned*)((const char*)(gbase) + (voff)[_i]), (PG8_LAS unsigned*)(lds + (bufoff) + ldsw + _i * 8192), 16, 0, 0); } while (0)
; #define PG8_LDA(dst, b, h) do { _Pragma("unroll") for (int m = 0; m < 4; ++m) _Pragma("unroll") for (int k = 0; k < 2; ++k) dst[m][k] = *(const PG8_LAS bf16x8*)(lds + PG8_SA(b, h) + aoff + m * 2048 + k * 1024); } while (0)
; #define PG8_LDB(dst, b, h) do { _Pragma("unroll") for (int n = 0; n < 2; ++n) _Pragma("unroll") for (int k = 0; k < 2; ++k) dst[n][k] = *(const PG8_LAS bf16x8*)(lds + PG8_SB(b, h) + boff + n * 2048 + k * 1024); } while (0)
; #define PG8_MMA(ai, bj, At, Bt) do { __builtin_amdgcn_s_setprio(1); _Pragma("unroll") for (int m = 0; m < 4; ++m) _Pragma("unroll") for (int n = 0; n < 2; ++n) _Pragma("unroll") for (int k = 0; k < 2; ++k) \
;         acc[ai][bj][m][n] = __builtin_amdgcn_mfma_f32_16x16x32_bf16(Bt[n][k], At[m][k], acc[ai][bj][m][n], 0, 0, 0); __builtin_amdgcn_s_setprio(0); } while (0)
; #define PG8_WAIT_V(n) asm volatile("s_waitcnt vmcnt(" #n ")" ::: "memory")
; #define PG8_WAIT_L(n) asm volatile("s_waitcnt lgkmcnt(" #n ")" ::: "memory")
; #define PG8_BAR __builtin_amdgcn_s_barrier()
; #define PG8_SCHED __builtin_amdgcn_sched_barrier(0)
; template <class Epi, class Sched, bool ALIGN_EPI = false, bool SP2 = false>
; __device__ __forceinline__ void gemm_phase(PG8_LAS unsigned char* lds, const Gemm g, const Sched& S, const Epi& E, const int wave_in) {
;     ...
;     f32x4 acc[2][2][4][2];
; #pragma unroll
;     for (int a = 0; a < 2; ++a)
; #pragma unroll
;         for (int b = 0; b < 2; ++b)
; #pragma unroll
;             for (int m = 0; m < 4; ++m)
; #pragma unroll
;                 for (int n = 0; n < 2; ++n) acc[a][b][m][n] = (f32x4){0.f, 0.f, 0.f, 0.f};
;     ...
;             PG8_LDB(B0, 0, 0); PG8_LDB(B1, 0, 1); PG8_SCHED; PG8_LDA(At, 0, 0); PG8_STAGE(PG8_SA(1, 1), a1 + hstep, voffA);
;             PG8_WAIT_V(8); PG8_WAIT_L(0); PG8_BAR; PG8_MMA(0, 0, At, B0); PG8_MMA(0, 1, At, B1); PG8_BAR; PG8_SCHED;
;             PG8_LDA(At, 0, 1); PG8_STAGE(PG8_SB(0, 0), b2, voffB); PG8_STAGE(PG8_SB(0, 1), b2 + hstep, voffB); PG8_STAGE(PG8_SA(0, 0), a2, voffA);
;             PG8_WAIT_V(8); PG8_WAIT_L(0); PG8_BAR; PG8_MMA(1, 0, At, B0); PG8_MMA(1, 1, At, B1); PG8_BAR; PG8_SCHED;
.LBB0_706:
	s_andn2_b64 vcc, exec, s[14:15]
	s_waitcnt vmcnt(0)
	s_waitcnt lgkmcnt(0)
	s_cbranch_vccnz .Lkz_skip_1
	s_add_u32 s2, s26, 0x80
	s_addc_u32 s3, s27, 0
	s_add_u32 s26, s24, 0x100
	s_addc_u32 s27, s25, 0
	s_mov_b32 s24, 0
	ds_read_b128 v[128:131], v169
	ds_read_b128 v[132:135], v169 offset:1024
	ds_read_b128 v[136:139], v169 offset:2048
	ds_read_b128 v[140:143], v169 offset:3072
	ds_read_b128 v[172:175], v170
	ds_read_b128 v[176:179], v170 offset:1024
	ds_read_b128 v[180:183], v170 offset:2048
	ds_read_b128 v[184:187], v170 offset:3072
	s_add_i32 s28, s24, 2
	s_add_u32 s29, s2, 0x80
	s_addc_u32 s25, s3, 0
	s_cmp_eq_u32 s75, s24
	s_cselect_b32 s24, s20, s29
	s_cselect_b32 s25, s21, s25
	s_cselect_b32 s37, s23, s27
	s_cselect_b32 s36, s22, s26
	v_lshl_add_u64 v[220:221], s[2:3], 0, v[158:159]
	s_add_i32 m0, s50, 0xc000
	ds_read_b128 v[188:191], v171
	ds_read_b128 v[192:195], v171 offset:1024
	ds_read_b128 v[196:199], v171 offset:2048
	ds_read_b128 v[200:203], v171 offset:3072
	ds_read_b128 v[204:207], v171 offset:4096
	ds_read_b128 v[208:211], v171 offset:5120
	ds_read_b128 v[212:215], v171 offset:6144
	ds_read_b128 v[216:219], v171 offset:7168
	global_load_lds_dwordx4 v[220:221], off
	v_lshl_add_u64 v[220:221], s[2:3], 0, v[160:161]
	s_add_i32 m0, s50, 0xe000
	s_nop 0
	global_load_lds_dwordx4 v[220:221], off
	s_waitcnt vmcnt(8)
	s_waitcnt lgkmcnt(0)
	s_barrier
	s_setprio 1
	s_waitcnt lgkmcnt(0)
	v_mfma_f32_16x16x32_bf16 v[124:127], v[128:131], v[188:191], 0
	v_mfma_f32_16x16x32_bf16 v[120:123], v[136:139], v[188:191], 0
	v_mfma_f32_16x16x32_bf16 v[108:111], v[128:131], v[196:199], 0
	v_mfma_f32_16x16x32_bf16 v[104:107], v[136:139], v[196:199], 0
	v_mfma_f32_16x16x32_bf16 v[92:95], v[128:131], v[204:207], 0
	v_mfma_f32_16x16x32_bf16 v[88:91], v[136:139], v[204:207], 0
	v_mfma_f32_16x16x32_bf16 v[76:79], v[128:131], v[212:215], 0
	v_mfma_f32_16x16x32_bf16 v[72:75], v[136:139], v[212:215], 0
	v_mfma_f32_16x16x32_bf16 v[124:127], v[132:135], v[192:195], v[124:127]
	v_mfma_f32_16x16x32_bf16 v[120:123], v[140:143], v[192:195], v[120:123]
	v_mfma_f32_16x16x32_bf16 v[108:111], v[132:135], v[200:203], v[108:111]
	v_mfma_f32_16x16x32_bf16 v[104:107], v[140:143], v[200:203], v[104:107]
	v_mfma_f32_16x16x32_bf16 v[92:95], v[132:135], v[208:211], v[92:95]
	v_mfma_f32_16x16x32_bf16 v[88:91], v[140:143], v[208:211], v[88:91]
	v_mfma_f32_16x16x32_bf16 v[76:79], v[132:135], v[216:219], v[76:79]
	v_mfma_f32_16x16x32_bf16 v[72:75], v[140:143], v[216:219], v[72:75]
	s_setprio 0
	s_setprio 1
	v_mfma_f32_16x16x32_bf16 v[112:115], v[172:175], v[188:191], 0
	v_mfma_f32_16x16x32_bf16 v[116:119], v[180:183], v[188:191], 0
	v_mfma_f32_16x16x32_bf16 v[96:99], v[172:175], v[196:199], 0
	v_mfma_f32_16x16x32_bf16 v[100:103], v[180:183], v[196:199], 0
	v_mfma_f32_16x16x32_bf16 v[80:83], v[172:175], v[204:207], 0
	v_mfma_f32_16x16x32_bf16 v[84:87], v[180:183], v[204:207], 0
	v_mfma_f32_16x16x32_bf16 v[64:67], v[172:175], v[212:215], 0
	v_mfma_f32_16x16x32_bf16 v[68:71], v[180:183], v[212:215], 0
	v_mfma_f32_16x16x32_bf16 v[112:115], v[176:179], v[192:195], v[112:115]
	v_mfma_f32_16x16x32_bf16 v[116:119], v[184:187], v[192:195], v[116:119]
	v_mfma_f32_16x16x32_bf16 v[96:99], v[176:179], v[200:203], v[96:99]
	v_mfma_f32_16x16x32_bf16 v[100:103], v[184:187], v[200:203], v[100:103]
	v_mfma_f32_16x16x32_bf16 v[80:83], v[176:179], v[208:211], v[80:83]
	v_mfma_f32_16x16x32_bf16 v[84:87], v[184:187], v[208:211], v[84:87]
	v_mfma_f32_16x16x32_bf16 v[64:67], v[176:179], v[216:219], v[64:67]
	v_mfma_f32_16x16x32_bf16 v[68:71], v[184:187], v[216:219], v[68:71]
	s_setprio 0
	s_barrier
	s_add_i32 s29, s80, s30
	v_lshl_add_u64 v[220:221], s[36:37], 0, v[146:147]
	s_mov_b32 m0, s29
	ds_read_b128 v[188:191], v171 offset:16384
	ds_read_b128 v[192:195], v171 offset:17408
	ds_read_b128 v[196:199], v171 offset:18432
	ds_read_b128 v[200:203], v171 offset:19456
	ds_read_b128 v[204:207], v171 offset:20480
	ds_read_b128 v[208:211], v171 offset:21504
	ds_read_b128 v[212:215], v171 offset:22528
	ds_read_b128 v[216:219], v171 offset:23552
	global_load_lds_dwordx4 v[220:221], off
	s_add_i32 m0, s29, 0x2000
	v_lshl_add_u64 v[222:223], s[36:37], 0, v[150:151]
	s_add_u32 s36, s36, s4
	s_addc_u32 s37, s37, s5
	s_add_i32 s29, s81, s30
	global_load_lds_dwordx4 v[222:223], off
	v_lshl_add_u64 v[224:225], s[36:37], 0, v[146:147]
	s_mov_b32 m0, s29
	v_lshl_add_u64 v[226:227], s[36:37], 0, v[150:151]
	global_load_lds_dwordx4 v[224:225], off
	s_add_i32 m0, s29, 0x2000
	v_lshl_add_u64 v[228:229], s[24:25], 0, v[144:145]
	global_load_lds_dwordx4 v[226:227], off
	s_mov_b32 m0, s50
	v_lshl_add_u64 v[230:231], s[24:25], 0, v[148:149]
	global_load_lds_dwordx4 v[228:229], off
	s_mov_b32 m0, s51
	s_nop 0
	global_load_lds_dwordx4 v[230:231], off
	s_waitcnt vmcnt(8)
	s_waitcnt lgkmcnt(0)
	s_barrier
; #define PG8_STAGE(bufoff, gbase, voff) do { _Pragma("unroll") for (int _i = 0; _i < 2; ++_i) \
;         __builtin_amdgcn_global_load_lds((const unsigned*)((const char*)(gbase) + (voff)[_i]), (PG8_LAS unsigned*)(lds + (bufoff) + ldsw + _i * 8192), 16, 0, 0); } while (0)
; #define PG8_LDA(dst, b, h) do { _Pragma("unroll") for (int m = 0; m < 4; ++m) _Pragma("unroll") for (int k = 0; k < 2; ++k) dst[m][k] = *(const PG8_LAS bf16x8*)(lds + PG8_SA(b, h) + aoff + m * 2048 + k * 1024); } while (0)
; #define PG8_LDB(dst, b, h) do { _Pragma("unroll") for (int n = 0; n < 2; ++n) _Pragma("unroll") for (int k = 0; k < 2; ++k) dst[n][k] = *(const PG8_LAS bf16x8*)(lds + PG8_SB(b, h) + boff + n * 2048 + k * 1024); } while (0)
; #define PG8_MMA(ai, bj, At, Bt) do { __builtin_amdgcn_s_setprio(1); _Pragma("unroll") for (int m = 0; m < 4; ++m) _Pragma("unroll") for (int n = 0; n < 2; ++n) _Pragma("unroll") for (int k = 0; k < 2; ++k) \
;         acc[ai][bj][m][n] = __builtin_amdgcn_mfma_f32_16x16x32_bf16(Bt[n][k], At[m][k], acc[ai][bj][m][n], 0, 0, 0); __builtin_amdgcn_s_setprio(0); } while (0)
; #define PG8_WAIT_V(n) asm volatile("s_waitcnt vmcnt(" #n ")" ::: "memory")
; #define PG8_WAIT_L(n) asm volatile("s_waitcnt lgkmcnt(" #n ")" ::: "memory")
; #define PG8_BAR __builtin_amdgcn_s_barrier()
; #define PG8_SCHED __builtin_amdgcn_sched_barrier(0)
; template <class Epi, class Sched, bool ALIGN_EPI = false, bool SP2 = false>
; __device__ __forceinline__ void gemm_phase(PG8_LAS unsigned char* lds, const Gemm g, const Sched& S, const Epi& E, const int wave_in) {
;     ...
;             PG8_WAIT_V(8); PG8_WAIT_L(0); PG8_BAR; PG8_MMA(0, 0, At, B0); PG8_MMA(0, 1, At, B1); PG8_BAR; PG8_SCHED;
;             PG8_LDA(At, 0, 1); PG8_STAGE(PG8_SB(0, 0), b2, voffB); PG8_STAGE(PG8_SB(0, 1), b2 + hstep, voffB); PG8_STAGE(PG8_SA(0, 0), a2, voffA);
;             PG8_WAIT_V(8); PG8_WAIT_L(0); PG8_BAR; PG8_MMA(1, 0, At, B0); PG8_MMA(1, 1, At, B1); PG8_BAR; PG8_SCHED;
;             PG8_LDB(B0, 1, 0); PG8_LDB(B1, 1, 1); PG8_SCHED; PG8_LDA(At, 1, 0); PG8_STAGE(PG8_SA(0, 1), a2 + hstep, voffA);
;             PG8_WAIT_V(8); PG8_WAIT_L(0); PG8_BAR; PG8_MMA(0, 0, At, B0); PG8_MMA(0, 1, At, B1); PG8_BAR; PG8_SCHED;
	s_setprio 1
	s_waitcnt lgkmcnt(0)
	v_mfma_f32_16x16x32_bf16 v[60:63], v[128:131], v[188:191], 0
	v_mfma_f32_16x16x32_bf16 v[56:59], v[136:139], v[188:191], 0
	v_mfma_f32_16x16x32_bf16 v[44:47], v[128:131], v[196:199], 0
	v_mfma_f32_16x16x32_bf16 v[40:43], v[136:139], v[196:199], 0
	v_mfma_f32_16x16x32_bf16 v[28:31], v[128:131], v[204:207], 0
	v_mfma_f32_16x16x32_bf16 v[24:27], v[136:139], v[204:207], 0
	v_mfma_f32_16x16x32_bf16 v[12:15], v[128:131], v[212:215], 0
	v_mfma_f32_16x16x32_bf16 v[8:11], v[136:139], v[212:215], 0
	v_mfma_f32_16x16x32_bf16 v[60:63], v[132:135], v[192:195], v[60:63]
	v_mfma_f32_16x16x32_bf16 v[56:59], v[140:143], v[192:195], v[56:59]
	v_mfma_f32_16x16x32_bf16 v[44:47], v[132:135], v[200:203], v[44:47]
	v_mfma_f32_16x16x32_bf16 v[40:43], v[140:143], v[200:203], v[40:43]
	v_mfma_f32_16x16x32_bf16 v[28:31], v[132:135], v[208:211], v[28:31]
	v_mfma_f32_16x16x32_bf16 v[24:27], v[140:143], v[208:211], v[24:27]
	v_mfma_f32_16x16x32_bf16 v[12:15], v[132:135], v[216:219], v[12:15]
	v_mfma_f32_16x16x32_bf16 v[8:11], v[140:143], v[216:219], v[8:11]
	s_setprio 0
	s_setprio 1
	v_mfma_f32_16x16x32_bf16 v[48:51], v[172:175], v[188:191], 0
	v_mfma_f32_16x16x32_bf16 v[52:55], v[180:183], v[188:191], 0
	v_mfma_f32_16x16x32_bf16 v[32:35], v[172:175], v[196:199], 0
	v_mfma_f32_16x16x32_bf16 v[36:39], v[180:183], v[196:199], 0
	v_mfma_f32_16x16x32_bf16 v[16:19], v[172:175], v[204:207], 0
	v_mfma_f32_16x16x32_bf16 v[20:23], v[180:183], v[204:207], 0
	v_mfma_f32_16x16x32_bf16 v[4:7], v[172:175], v[212:215], 0
	v_mfma_f32_16x16x32_bf16 v[0:3], v[180:183], v[212:215], 0
	v_mfma_f32_16x16x32_bf16 v[48:51], v[176:179], v[192:195], v[48:51]
	v_mfma_f32_16x16x32_bf16 v[52:55], v[184:187], v[192:195], v[52:55]
	v_mfma_f32_16x16x32_bf16 v[32:35], v[176:179], v[200:203], v[32:35]
	v_mfma_f32_16x16x32_bf16 v[36:39], v[184:187], v[200:203], v[36:39]
	v_mfma_f32_16x16x32_bf16 v[16:19], v[176:179], v[208:211], v[16:19]
	v_mfma_f32_16x16x32_bf16 v[20:23], v[184:187], v[208:211], v[20:23]
	v_mfma_f32_16x16x32_bf16 v[4:7], v[176:179], v[216:219], v[4:7]
	v_mfma_f32_16x16x32_bf16 v[0:3], v[184:187], v[216:219], v[0:3]
	s_setprio 0
	s_barrier
	s_add_i32 s29, 0, 0x18000
	s_add_i32 s36, 0, 0x1c000
	v_add_u32_e32 v140, s29, v167
	v_add_u32_e32 v152, s36, v167
	ds_read_b128 v[128:131], v140
	ds_read_b128 v[132:135], v140 offset:1024
	ds_read_b128 v[136:139], v140 offset:2048
	ds_read_b128 v[140:143], v140 offset:3072
	ds_read_b128 v[172:175], v152
	ds_read_b128 v[176:179], v152 offset:1024
	ds_read_b128 v[180:183], v152 offset:2048
	ds_read_b128 v[184:187], v152 offset:3072
	s_add_u32 s24, s24, s4
	s_addc_u32 s25, s25, s5
	s_mov_b32 m0, s52
	v_lshl_add_u64 v[232:233], s[24:25], 0, v[144:145]
	ds_read_b128 v[188:191], v171 offset:32768
	ds_read_b128 v[192:195], v171 offset:33792
	ds_read_b128 v[196:199], v171 offset:34816
	ds_read_b128 v[200:203], v171 offset:35840
	ds_read_b128 v[204:207], v171 offset:36864
	ds_read_b128 v[208:211], v171 offset:37888
	ds_read_b128 v[212:215], v171 offset:38912
	ds_read_b128 v[216:219], v171 offset:39936
	global_load_lds_dwordx4 v[232:233], off
	v_lshl_add_u64 v[232:233], s[24:25], 0, v[148:149]
	s_mov_b32 m0, s53
	s_nop 0
	global_load_lds_dwordx4 v[232:233], off
	s_waitcnt vmcnt(8)
	s_waitcnt lgkmcnt(0)
	s_barrier
	s_setprio 1
	s_waitcnt lgkmcnt(0)
	v_mfma_f32_16x16x32_bf16 v[124:127], v[128:131], v[188:191], v[124:127]
	v_mfma_f32_16x16x32_bf16 v[120:123], v[136:139], v[188:191], v[120:123]
	v_mfma_f32_16x16x32_bf16 v[108:111], v[128:131], v[196:199], v[108:111]
	v_mfma_f32_16x16x32_bf16 v[104:107], v[136:139], v[196:199], v[104:107]
	v_mfma_f32_16x16x32_bf16 v[92:95], v[128:131], v[204:207], v[92:95]
	v_mfma_f32_16x16x32_bf16 v[88:91], v[136:139], v[204:207], v[88:91]
	v_mfma_f32_16x16x32_bf16 v[76:79], v[128:131], v[212:215], v[76:79]
	v_mfma_f32_16x16x32_bf16 v[72:75], v[136:139], v[212:215], v[72:75]
	v_mfma_f32_16x16x32_bf16 v[124:127], v[132:135], v[192:195], v[124:127]
	v_mfma_f32_16x16x32_bf16 v[120:123], v[140:143], v[192:195], v[120:123]
	v_mfma_f32_16x16x32_bf16 v[108:111], v[132:135], v[200:203], v[108:111]
	v_mfma_f32_16x16x32_bf16 v[104:107], v[140:143], v[200:203], v[104:107]
	v_mfma_f32_16x16x32_bf16 v[92:95], v[132:135], v[208:211], v[92:95]
	v_mfma_f32_16x16x32_bf16 v[88:91], v[140:143], v[208:211], v[88:91]
	v_mfma_f32_16x16x32_bf16 v[76:79], v[132:135], v[216:219], v[76:79]
	v_mfma_f32_16x16x32_bf16 v[72:75], v[140:143], v[216:219], v[72:75]
	s_setprio 0
	s_setprio 1
	v_mfma_f32_16x16x32_bf16 v[112:115], v[172:175], v[188:191], v[112:115]
	v_mfma_f32_16x16x32_bf16 v[116:119], v[180:183], v[188:191], v[116:119]
	v_mfma_f32_16x16x32_bf16 v[96:99], v[172:175], v[196:199], v[96:99]
	v_mfma_f32_16x16x32_bf16 v[100:103], v[180:183], v[196:199], v[100:103]
	v_mfma_f32_16x16x32_bf16 v[80:83], v[172:175], v[204:207], v[80:83]
	v_mfma_f32_16x16x32_bf16 v[84:87], v[180:183], v[204:207], v[84:87]
	v_mfma_f32_16x16x32_bf16 v[64:67], v[172:175], v[212:215], v[64:67]
	v_mfma_f32_16x16x32_bf16 v[68:71], v[180:183], v[212:215], v[68:71]
	v_mfma_f32_16x16x32_bf16 v[112:115], v[176:179], v[192:195], v[112:115]
	v_mfma_f32_16x16x32_bf16 v[116:119], v[184:187], v[192:195], v[116:119]
	v_mfma_f32_16x16x32_bf16 v[96:99], v[176:179], v[200:203], v[96:99]
	v_mfma_f32_16x16x32_bf16 v[100:103], v[184:187], v[200:203], v[100:103]
	v_mfma_f32_16x16x32_bf16 v[80:83], v[176:179], v[208:211], v[80:83]
	v_mfma_f32_16x16x32_bf16 v[84:87], v[184:187], v[208:211], v[84:87]
	v_mfma_f32_16x16x32_bf16 v[64:67], v[176:179], v[216:219], v[64:67]
	v_mfma_f32_16x16x32_bf16 v[68:71], v[184:187], v[216:219], v[68:71]
	s_setprio 0
	s_barrier
; #define PG8_STAGE(bufoff, gbase, voff) do { _Pragma("unroll") for (int _i = 0; _i < 2; ++_i) \
;         __builtin_amdgcn_global_load_lds((const unsigned*)((const char*)(gbase) + (voff)[_i]), (PG8_LAS unsigned*)(lds + (bufoff) + ldsw + _i * 8192), 16, 0, 0); } while (0)
; #define PG8_LDA(dst, b, h) do { _Pragma("unroll") for (int m = 0; m < 4; ++m) _Pragma("unroll") for (int k = 0; k < 2; ++k) dst[m][k] = *(const PG8_LAS bf16x8*)(lds + PG8_SA(b, h) + aoff + m * 2048 + k * 1024); } while (0)
; #define PG8_LDB(dst, b, h) do { _Pragma("unroll") for (int n = 0; n < 2; ++n) _Pragma("unroll") for (int k = 0; k < 2; ++k) dst[n][k] = *(const PG8_LAS bf16x8*)(lds + PG8_SB(b, h) + boff + n * 2048 + k * 1024); } while (0)
; #define PG8_MMA(ai, bj, At, Bt) do { __builtin_amdgcn_s_setprio(1); _Pragma("unroll") for (int m = 0; m < 4; ++m) _Pragma("unroll") for (int n = 0; n < 2; ++n) _Pragma("unroll") for (int k = 0; k < 2; ++k) \
;         acc[ai][bj][m][n] = __builtin_amdgcn_mfma_f32_16x16x32_bf16(Bt[n][k], At[m][k], acc[ai][bj][m][n], 0, 0, 0); __builtin_amdgcn_s_setprio(0); } while (0)
; #define PG8_WAIT_V(n) asm volatile("s_waitcnt vmcnt(" #n ")" ::: "memory")
; #define PG8_BAR __builtin_amdgcn_s_barrier()
; template <class Epi, class Sched, bool ALIGN_EPI = false, bool SP2 = false>
; __device__ __forceinline__ void gemm_phase(PG8_LAS unsigned char* lds, const Gemm g, const Sched& S, const Epi& E, const int wave_in) {
;     ...
;         for (int t = 0; t < nt; t += 2) {
;             const bool last = (t == nt - 2);
;             const char* a1 = cA + (size_t)(t + 1) * kstep;
;             const char* a2 = last ? nA : cA + (size_t)(t + 2) * kstep; const char* b2 = last ? nB : cB + (size_t)(t + 2) * kstep;
;             const char* a3 = a2 + kstep; const char* b3 = b2 + kstep;
;             if (last && has_next) S.a_ready(nxt);
;             if constexpr (SP2) {
;             PG8_LDB(B0, 0, 0); PG8_LDB(B1, 0, 1); PG8_SCHED; PG8_LDA(At, 0, 0); PG8_STAGE(PG8_SA(1, 1), a1 + hstep, voffA);
;     ...
;             PG8_WAIT_V(8); PG8_WAIT_L(0); PG8_BAR; PG8_MMA(0, 0, At, B0); PG8_MMA(0, 1, At, B1); PG8_BAR; PG8_SCHED;
;             PG8_LDA(At, 1, 1); PG8_STAGE(PG8_SB(1, 0), b3, voffB); PG8_STAGE(PG8_SB(1, 1), b3 + hstep, voffB); PG8_STAGE(PG8_SA(1, 0), a3, voffA);
;             PG8_WAIT_V(8); PG8_WAIT_L(0); PG8_BAR; PG8_MMA(1, 0, At, B0); PG8_MMA(1, 1, At, B1); PG8_BAR; PG8_SCHED;
	s_add_i32 s24, s29, s30
	v_lshl_add_u64 v[220:221], v[220:221], 0, s[12:13]
	s_mov_b32 m0, s24
	ds_read_b128 v[188:191], v171 offset:49152
	ds_read_b128 v[192:195], v171 offset:50176
	ds_read_b128 v[196:199], v171 offset:51200
	ds_read_b128 v[200:203], v171 offset:52224
	ds_read_b128 v[204:207], v171 offset:53248
	ds_read_b128 v[208:211], v171 offset:54272
	ds_read_b128 v[212:215], v171 offset:55296
	ds_read_b128 v[216:219], v171 offset:56320
	global_load_lds_dwordx4 v[220:221], off
	v_lshl_add_u64 v[220:221], v[222:223], 0, s[12:13]
	s_add_i32 m0, s24, 0x2000
	s_add_i32 s24, s36, s30
	global_load_lds_dwordx4 v[220:221], off
	v_lshl_add_u64 v[220:221], v[224:225], 0, s[12:13]
	s_mov_b32 m0, s24
	s_nop 0
	global_load_lds_dwordx4 v[220:221], off
	v_lshl_add_u64 v[220:221], v[226:227], 0, s[12:13]
	s_add_i32 m0, s24, 0x2000
	s_nop 0
	global_load_lds_dwordx4 v[220:221], off
	v_lshl_add_u64 v[220:221], v[228:229], 0, s[12:13]
	s_mov_b32 m0, s72
	s_nop 0
	global_load_lds_dwordx4 v[220:221], off
	v_lshl_add_u64 v[220:221], v[230:231], 0, s[12:13]
	s_mov_b32 m0, s73
	s_nop 0
	global_load_lds_dwordx4 v[220:221], off
	s_waitcnt vmcnt(8)
	s_waitcnt lgkmcnt(0)
	s_barrier
	s_setprio 1
	s_waitcnt lgkmcnt(0)
	v_mfma_f32_16x16x32_bf16 v[60:63], v[128:131], v[188:191], v[60:63]
	v_mfma_f32_16x16x32_bf16 v[56:59], v[136:139], v[188:191], v[56:59]
	v_mfma_f32_16x16x32_bf16 v[44:47], v[128:131], v[196:199], v[44:47]
	v_mfma_f32_16x16x32_bf16 v[40:43], v[136:139], v[196:199], v[40:43]
	v_mfma_f32_16x16x32_bf16 v[28:31], v[128:131], v[204:207], v[28:31]
	v_mfma_f32_16x16x32_bf16 v[24:27], v[136:139], v[204:207], v[24:27]
	v_mfma_f32_16x16x32_bf16 v[12:15], v[128:131], v[212:215], v[12:15]
	v_mfma_f32_16x16x32_bf16 v[8:11], v[136:139], v[212:215], v[8:11]
	v_mfma_f32_16x16x32_bf16 v[60:63], v[132:135], v[192:195], v[60:63]
	v_mfma_f32_16x16x32_bf16 v[56:59], v[140:143], v[192:195], v[56:59]
	v_mfma_f32_16x16x32_bf16 v[44:47], v[132:135], v[200:203], v[44:47]
	v_mfma_f32_16x16x32_bf16 v[40:43], v[140:143], v[200:203], v[40:43]
	v_mfma_f32_16x16x32_bf16 v[28:31], v[132:135], v[208:211], v[28:31]
	v_mfma_f32_16x16x32_bf16 v[24:27], v[140:143], v[208:211], v[24:27]
	v_mfma_f32_16x16x32_bf16 v[12:15], v[132:135], v[216:219], v[12:15]
	v_mfma_f32_16x16x32_bf16 v[8:11], v[140:143], v[216:219], v[8:11]
	s_setprio 0
	s_setprio 1
	v_mfma_f32_16x16x32_bf16 v[48:51], v[172:175], v[188:191], v[48:51]
	v_mfma_f32_16x16x32_bf16 v[52:55], v[180:183], v[188:191], v[52:55]
	v_mfma_f32_16x16x32_bf16 v[32:35], v[172:175], v[196:199], v[32:35]
	v_mfma_f32_16x16x32_bf16 v[36:39], v[180:183], v[196:199], v[36:39]
	v_mfma_f32_16x16x32_bf16 v[16:19], v[172:175], v[204:207], v[16:19]
	v_mfma_f32_16x16x32_bf16 v[20:23], v[180:183], v[204:207], v[20:23]
	v_mfma_f32_16x16x32_bf16 v[4:7], v[172:175], v[212:215], v[4:7]
	v_mfma_f32_16x16x32_bf16 v[0:3], v[180:183], v[212:215], v[0:3]
	v_mfma_f32_16x16x32_bf16 v[48:51], v[176:179], v[192:195], v[48:51]
	v_mfma_f32_16x16x32_bf16 v[52:55], v[184:187], v[192:195], v[52:55]
	v_mfma_f32_16x16x32_bf16 v[32:35], v[176:179], v[200:203], v[32:35]
	v_mfma_f32_16x16x32_bf16 v[36:39], v[184:187], v[200:203], v[36:39]
	v_mfma_f32_16x16x32_bf16 v[16:19], v[176:179], v[208:211], v[16:19]
	v_mfma_f32_16x16x32_bf16 v[20:23], v[184:187], v[208:211], v[20:23]
	v_mfma_f32_16x16x32_bf16 v[4:7], v[176:179], v[216:219], v[4:7]
	v_mfma_f32_16x16x32_bf16 v[0:3], v[184:187], v[216:219], v[0:3]
	s_setprio 0
	s_barrier
	s_add_u32 s2, s2, 0x100
	s_addc_u32 s3, s3, 0
	s_add_u32 s26, s26, 0x100
	s_addc_u32 s27, s27, 0
	s_cmp_ge_i32 s28, s74
	s_mov_b32 s24, s28
	s_cbranch_scc1 .Lkz_exit_1
.LBB0_708:
	ds_read_b128 v[128:131], v169
	ds_read_b128 v[132:135], v169 offset:1024
	ds_read_b128 v[136:139], v169 offset:2048
	ds_read_b128 v[140:143], v169 offset:3072
	ds_read_b128 v[172:175], v170
	ds_read_b128 v[176:179], v170 offset:1024
	ds_read_b128 v[180:183], v170 offset:2048
	ds_read_b128 v[184:187], v170 offset:3072
	s_add_i32 s28, s24, 2
	s_add_u32 s29, s2, 0x80
	s_addc_u32 s25, s3, 0
	s_cmp_eq_u32 s75, s24
	s_cselect_b32 s24, s20, s29
	s_cselect_b32 s25, s21, s25
	s_cselect_b32 s37, s23, s27
	s_cselect_b32 s36, s22, s26
	v_lshl_add_u64 v[220:221], s[2:3], 0, v[158:159]
	s_add_i32 m0, s50, 0xc000
	ds_read_b128 v[188:191], v171
	ds_read_b128 v[192:195], v171 offset:1024
	ds_read_b128 v[196:199], v171 offset:2048
	ds_read_b128 v[200:203], v171 offset:3072
	ds_read_b128 v[204:207], v171 offset:4096
	ds_read_b128 v[208:211], v171 offset:5120
	ds_read_b128 v[212:215], v171 offset:6144
	ds_read_b128 v[216:219], v171 offset:7168
	global_load_lds_dwordx4 v[220:221], off
	v_lshl_add_u64 v[220:221], s[2:3], 0, v[160:161]
	s_add_i32 m0, s50, 0xe000
	s_nop 0
	global_load_lds_dwordx4 v[220:221], off
	s_waitcnt vmcnt(8)
	s_waitcnt lgkmcnt(0)
	s_barrier
; #define PG8_STAGE(bufoff, gbase, voff) do { _Pragma("unroll") for (int _i = 0; _i < 2; ++_i) \
;         __builtin_amdgcn_global_load_lds((const unsigned*)((const char*)(gbase) + (voff)[_i]), (PG8_LAS unsigned*)(lds + (bufoff) + ldsw + _i * 8192), 16, 0, 0); } while (0)
; #define PG8_LDA(dst, b, h) do { _Pragma("unroll") for (int m = 0; m < 4; ++m) _Pragma("unroll") for (int k = 0; k < 2; ++k) dst[m][k] = *(const PG8_LAS bf16x8*)(lds + PG8_SA(b, h) + aoff + m * 2048 + k * 1024); } while (0)
; #define PG8_LDB(dst, b, h) do { _Pragma("unroll") for (int n = 0; n < 2; ++n) _Pragma("unroll") for (int k = 0; k < 2; ++k) dst[n][k] = *(const PG8_LAS bf16x8*)(lds + PG8_SB(b, h) + boff + n * 2048 + k * 1024); } while (0)
; #define PG8_MMA(ai, bj, At, Bt) do { __builtin_amdgcn_s_setprio(1); _Pragma("unroll") for (int m = 0; m < 4; ++m) _Pragma("unroll") for (int n = 0; n < 2; ++n) _Pragma("unroll") for (int k = 0; k < 2; ++k) \
;         acc[ai][bj][m][n] = __builtin_amdgcn_mfma_f32_16x16x32_bf16(Bt[n][k], At[m][k], acc[ai][bj][m][n], 0, 0, 0); __builtin_amdgcn_s_setprio(0); } while (0)
; #define PG8_WAIT_V(n) asm volatile("s_waitcnt vmcnt(" #n ")" ::: "memory")
; #define PG8_WAIT_L(n) asm volatile("s_waitcnt lgkmcnt(" #n ")" ::: "memory")
; #define PG8_BAR __builtin_amdgcn_s_barrier()
; #define PG8_SCHED __builtin_amdgcn_sched_barrier(0)
; template <class Epi, class Sched, bool ALIGN_EPI = false, bool SP2 = false>
; __device__ __forceinline__ void gemm_phase(PG8_LAS unsigned char* lds, const Gemm g, const Sched& S, const Epi& E, const int wave_in) {
;     ...
;             PG8_WAIT_V(8); PG8_WAIT_L(0); PG8_BAR; PG8_MMA(0, 0, At, B0); PG8_MMA(0, 1, At, B1); PG8_BAR; PG8_SCHED;
;             PG8_LDA(At, 0, 1); PG8_STAGE(PG8_SB(0, 0), b2, voffB); PG8_STAGE(PG8_SB(0, 1), b2 + hstep, voffB); PG8_STAGE(PG8_SA(0, 0), a2, voffA);
;             PG8_WAIT_V(8); PG8_WAIT_L(0); PG8_BAR; PG8_MMA(1, 0, At, B0); PG8_MMA(1, 1, At, B1); PG8_BAR; PG8_SCHED;
;             PG8_LDB(B0, 1, 0); PG8_LDB(B1, 1, 1); PG8_SCHED; PG8_LDA(At, 1, 0); PG8_STAGE(PG8_SA(0, 1), a2 + hstep, voffA);
;             PG8_WAIT_V(8); PG8_WAIT_L(0); PG8_BAR; PG8_MMA(0, 0, At, B0); PG8_MMA(0, 1, At, B1); PG8_BAR; PG8_SCHED;
	s_setprio 1
	s_waitcnt lgkmcnt(0)
	v_mfma_f32_16x16x32_bf16 v[124:127], v[128:131], v[188:191], v[124:127]
	v_mfma_f32_16x16x32_bf16 v[120:123], v[136:139], v[188:191], v[120:123]
	v_mfma_f32_16x16x32_bf16 v[108:111], v[128:131], v[196:199], v[108:111]
	v_mfma_f32_16x16x32_bf16 v[104:107], v[136:139], v[196:199], v[104:107]
	v_mfma_f32_16x16x32_bf16 v[92:95], v[128:131], v[204:207], v[92:95]
	v_mfma_f32_16x16x32_bf16 v[88:91], v[136:139], v[204:207], v[88:91]
	v_mfma_f32_16x16x32_bf16 v[76:79], v[128:131], v[212:215], v[76:79]
	v_mfma_f32_16x16x32_bf16 v[72:75], v[136:139], v[212:215], v[72:75]
	v_mfma_f32_16x16x32_bf16 v[124:127], v[132:135], v[192:195], v[124:127]
	v_mfma_f32_16x16x32_bf16 v[120:123], v[140:143], v[192:195], v[120:123]
	v_mfma_f32_16x16x32_bf16 v[108:111], v[132:135], v[200:203], v[108:111]
	v_mfma_f32_16x16x32_bf16 v[104:107], v[140:143], v[200:203], v[104:107]
	v_mfma_f32_16x16x32_bf16 v[92:95], v[132:135], v[208:211], v[92:95]
	v_mfma_f32_16x16x32_bf16 v[88:91], v[140:143], v[208:211], v[88:91]
	v_mfma_f32_16x16x32_bf16 v[76:79], v[132:135], v[216:219], v[76:79]
	v_mfma_f32_16x16x32_bf16 v[72:75], v[140:143], v[216:219], v[72:75]
	s_setprio 0
	s_setprio 1
	v_mfma_f32_16x16x32_bf16 v[112:115], v[172:175], v[188:191], v[112:115]
	v_mfma_f32_16x16x32_bf16 v[116:119], v[180:183], v[188:191], v[116:119]
	v_mfma_f32_16x16x32_bf16 v[96:99], v[172:175], v[196:199], v[96:99]
	v_mfma_f32_16x16x32_bf16 v[100:103], v[180:183], v[196:199], v[100:103]
	v_mfma_f32_16x16x32_bf16 v[80:83], v[172:175], v[204:207], v[80:83]
	v_mfma_f32_16x16x32_bf16 v[84:87], v[180:183], v[204:207], v[84:87]
	v_mfma_f32_16x16x32_bf16 v[64:67], v[172:175], v[212:215], v[64:67]
	v_mfma_f32_16x16x32_bf16 v[68:71], v[180:183], v[212:215], v[68:71]
	v_mfma_f32_16x16x32_bf16 v[112:115], v[176:179], v[192:195], v[112:115]
	v_mfma_f32_16x16x32_bf16 v[116:119], v[184:187], v[192:195], v[116:119]
	v_mfma_f32_16x16x32_bf16 v[96:99], v[176:179], v[200:203], v[96:99]
	v_mfma_f32_16x16x32_bf16 v[100:103], v[184:187], v[200:203], v[100:103]
	v_mfma_f32_16x16x32_bf16 v[80:83], v[176:179], v[208:211], v[80:83]
	v_mfma_f32_16x16x32_bf16 v[84:87], v[184:187], v[208:211], v[84:87]
	v_mfma_f32_16x16x32_bf16 v[64:67], v[176:179], v[216:219], v[64:67]
	v_mfma_f32_16x16x32_bf16 v[68:71], v[184:187], v[216:219], v[68:71]
	s_setprio 0
	s_barrier
	s_add_i32 s29, s80, s30
	v_lshl_add_u64 v[220:221], s[36:37], 0, v[146:147]
	s_mov_b32 m0, s29
	ds_read_b128 v[188:191], v171 offset:16384
	ds_read_b128 v[192:195], v171 offset:17408
	ds_read_b128 v[196:199], v171 offset:18432
	ds_read_b128 v[200:203], v171 offset:19456
	ds_read_b128 v[204:207], v171 offset:20480
	ds_read_b128 v[208:211], v171 offset:21504
	ds_read_b128 v[212:215], v171 offset:22528
	ds_read_b128 v[216:219], v171 offset:23552
	global_load_lds_dwordx4 v[220:221], off
	s_add_i32 m0, s29, 0x2000
	v_lshl_add_u64 v[222:223], s[36:37], 0, v[150:151]
	s_add_u32 s36, s36, s4
	s_addc_u32 s37, s37, s5
	s_add_i32 s29, s81, s30
	global_load_lds_dwordx4 v[222:223], off
	v_lshl_add_u64 v[224:225], s[36:37], 0, v[146:147]
	s_mov_b32 m0, s29
	v_lshl_add_u64 v[226:227], s[36:37], 0, v[150:151]
	global_load_lds_dwordx4 v[224:225], off
	s_add_i32 m0, s29, 0x2000
	v_lshl_add_u64 v[228:229], s[24:25], 0, v[144:145]
	global_load_lds_dwordx4 v[226:227], off
	s_mov_b32 m0, s50
	v_lshl_add_u64 v[230:231], s[24:25], 0, v[148:149]
	global_load_lds_dwordx4 v[228:229], off
	s_mov_b32 m0, s51
	s_nop 0
	global_load_lds_dwordx4 v[230:231], off
	s_waitcnt vmcnt(8)
	s_waitcnt lgkmcnt(0)
	s_barrier
	s_setprio 1
	s_waitcnt lgkmcnt(0)
	v_mfma_f32_16x16x32_bf16 v[60:63], v[128:131], v[188:191], v[60:63]
	v_mfma_f32_16x16x32_bf16 v[56:59], v[136:139], v[188:191], v[56:59]
	v_mfma_f32_16x16x32_bf16 v[44:47], v[128:131], v[196:199], v[44:47]
	v_mfma_f32_16x16x32_bf16 v[40:43], v[136:139], v[196:199], v[40:43]
	v_mfma_f32_16x16x32_bf16 v[28:31], v[128:131], v[204:207], v[28:31]
	v_mfma_f32_16x16x32_bf16 v[24:27], v[136:139], v[204:207], v[24:27]
	v_mfma_f32_16x16x32_bf16 v[12:15], v[128:131], v[212:215], v[12:15]
	v_mfma_f32_16x16x32_bf16 v[8:11], v[136:139], v[212:215], v[8:11]
	v_mfma_f32_16x16x32_bf16 v[60:63], v[132:135], v[192:195], v[60:63]
	v_mfma_f32_16x16x32_bf16 v[56:59], v[140:143], v[192:195], v[56:59]
	v_mfma_f32_16x16x32_bf16 v[44:47], v[132:135], v[200:203], v[44:47]
	v_mfma_f32_16x16x32_bf16 v[40:43], v[140:143], v[200:203], v[40:43]
	v_mfma_f32_16x16x32_bf16 v[28:31], v[132:135], v[208:211], v[28:31]
	v_mfma_f32_16x16x32_bf16 v[24:27], v[140:143], v[208:211], v[24:27]
	v_mfma_f32_16x16x32_bf16 v[12:15], v[132:135], v[216:219], v[12:15]
	v_mfma_f32_16x16x32_bf16 v[8:11], v[140:143], v[216:219], v[8:11]
	s_setprio 0
	s_setprio 1
	v_mfma_f32_16x16x32_bf16 v[48:51], v[172:175], v[188:191], v[48:51]
	v_mfma_f32_16x16x32_bf16 v[52:55], v[180:183], v[188:191], v[52:55]
	v_mfma_f32_16x16x32_bf16 v[32:35], v[172:175], v[196:199], v[32:35]
	v_mfma_f32_16x16x32_bf16 v[36:39], v[180:183], v[196:199], v[36:39]
	v_mfma_f32_16x16x32_bf16 v[16:19], v[172:175], v[204:207], v[16:19]
	v_mfma_f32_16x16x32_bf16 v[20:23], v[180:183], v[204:207], v[20:23]
	v_mfma_f32_16x16x32_bf16 v[4:7], v[172:175], v[212:215], v[4:7]
	v_mfma_f32_16x16x32_bf16 v[0:3], v[180:183], v[212:215], v[0:3]
	v_mfma_f32_16x16x32_bf16 v[48:51], v[176:179], v[192:195], v[48:51]
	v_mfma_f32_16x16x32_bf16 v[52:55], v[184:187], v[192:195], v[52:55]
	v_mfma_f32_16x16x32_bf16 v[32:35], v[176:179], v[200:203], v[32:35]
	v_mfma_f32_16x16x32_bf16 v[36:39], v[184:187], v[200:203], v[36:39]
	v_mfma_f32_16x16x32_bf16 v[16:19], v[176:179], v[208:211], v[16:19]
	v_mfma_f32_16x16x32_bf16 v[20:23], v[184:187], v[208:211], v[20:23]
	v_mfma_f32_16x16x32_bf16 v[4:7], v[176:179], v[216:219], v[4:7]
	v_mfma_f32_16x16x32_bf16 v[0:3], v[184:187], v[216:219], v[0:3]
	s_setprio 0
	s_barrier
; #define PG8_STAGE(bufoff, gbase, voff) do { _Pragma("unroll") for (int _i = 0; _i < 2; ++_i) \
;         __builtin_amdgcn_global_load_lds((const unsigned*)((const char*)(gbase) + (voff)[_i]), (PG8_LAS unsigned*)(lds + (bufoff) + ldsw + _i * 8192), 16, 0, 0); } while (0)
; #define PG8_LDA(dst, b, h) do { _Pragma("unroll") for (int m = 0; m < 4; ++m) _Pragma("unroll") for (int k = 0; k < 2; ++k) dst[m][k] = *(const PG8_LAS bf16x8*)(lds + PG8_SA(b, h) + aoff + m * 2048 + k * 1024); } while (0)
; #define PG8_LDB(dst, b, h) do { _Pragma("unroll") for (int n = 0; n < 2; ++n) _Pragma("unroll") for (int k = 0; k < 2; ++k) dst[n][k] = *(const PG8_LAS bf16x8*)(lds + PG8_SB(b, h) + boff + n * 2048 + k * 1024); } while (0)
; #define PG8_MMA(ai, bj, At, Bt) do { __builtin_amdgcn_s_setprio(1); _Pragma("unroll") for (int m = 0; m < 4; ++m) _Pragma("unroll") for (int n = 0; n < 2; ++n) _Pragma("unroll") for (int k = 0; k < 2; ++k) \
;         acc[ai][bj][m][n] = __builtin_amdgcn_mfma_f32_16x16x32_bf16(Bt[n][k], At[m][k], acc[ai][bj][m][n], 0, 0, 0); __builtin_amdgcn_s_setprio(0); } while (0)
; #define PG8_WAIT_V(n) asm volatile("s_waitcnt vmcnt(" #n ")" ::: "memory")
; #define PG8_WAIT_L(n) asm volatile("s_waitcnt lgkmcnt(" #n ")" ::: "memory")
; #define PG8_BAR __builtin_amdgcn_s_barrier()
; #define PG8_SCHED __builtin_amdgcn_sched_barrier(0)
; template <class Epi, class Sched, bool ALIGN_EPI = false, bool SP2 = false>
; __device__ __forceinline__ void gemm_phase(PG8_LAS unsigned char* lds, const Gemm g, const Sched& S, const Epi& E, const int wave_in) {
;     ...
;             PG8_LDB(B0, 1, 0); PG8_LDB(B1, 1, 1); PG8_SCHED; PG8_LDA(At, 1, 0); PG8_STAGE(PG8_SA(0, 1), a2 + hstep, voffA);
;             PG8_WAIT_V(8); PG8_WAIT_L(0); PG8_BAR; PG8_MMA(0, 0, At, B0); PG8_MMA(0, 1, At, B1); PG8_BAR; PG8_SCHED;
;             PG8_LDA(At, 1, 1); PG8_STAGE(PG8_SB(1, 0), b3, voffB); PG8_STAGE(PG8_SB(1, 1), b3 + hstep, voffB); PG8_STAGE(PG8_SA(1, 0), a3, voffA);
	s_add_i32 s29, 0, 0x18000
	s_add_i32 s36, 0, 0x1c000
	v_add_u32_e32 v140, s29, v167
	v_add_u32_e32 v152, s36, v167
	ds_read_b128 v[128:131], v140
	ds_read_b128 v[132:135], v140 offset:1024
	ds_read_b128 v[136:139], v140 offset:2048
	ds_read_b128 v[140:143], v140 offset:3072
	ds_read_b128 v[172:175], v152
	ds_read_b128 v[176:179], v152 offset:1024
	ds_read_b128 v[180:183], v152 offset:2048
	ds_read_b128 v[184:187], v152 offset:3072
	s_add_u32 s24, s24, s4
	s_addc_u32 s25, s25, s5
	s_mov_b32 m0, s52
	v_lshl_add_u64 v[232:233], s[24:25], 0, v[144:145]
	ds_read_b128 v[188:191], v171 offset:32768
	ds_read_b128 v[192:195], v171 offset:33792
	ds_read_b128 v[196:199], v171 offset:34816
	ds_read_b128 v[200:203], v171 offset:35840
	ds_read_b128 v[204:207], v171 offset:36864
	ds_read_b128 v[208:211], v171 offset:37888
	ds_read_b128 v[212:215], v171 offset:38912
	ds_read_b128 v[216:219], v171 offset:39936
	global_load_lds_dwordx4 v[232:233], off
	v_lshl_add_u64 v[232:233], s[24:25], 0, v[148:149]
	s_mov_b32 m0, s53
	s_nop 0
	global_load_lds_dwordx4 v[232:233], off
	s_waitcnt vmcnt(8)
	s_waitcnt lgkmcnt(0)
	s_barrier
	s_setprio 1
	s_waitcnt lgkmcnt(0)
	v_mfma_f32_16x16x32_bf16 v[124:127], v[128:131], v[188:191], v[124:127]
	v_mfma_f32_16x16x32_bf16 v[120:123], v[136:139], v[188:191], v[120:123]
	v_mfma_f32_16x16x32_bf16 v[108:111], v[128:131], v[196:199], v[108:111]
	v_mfma_f32_16x16x32_bf16 v[104:107], v[136:139], v[196:199], v[104:107]
	v_mfma_f32_16x16x32_bf16 v[92:95], v[128:131], v[204:207], v[92:95]
	v_mfma_f32_16x16x32_bf16 v[88:91], v[136:139], v[204:207], v[88:91]
	v_mfma_f32_16x16x32_bf16 v[76:79], v[128:131], v[212:215], v[76:79]
	v_mfma_f32_16x16x32_bf16 v[72:75], v[136:139], v[212:215], v[72:75]
	v_mfma_f32_16x16x32_bf16 v[124:127], v[132:135], v[192:195], v[124:127]
	v_mfma_f32_16x16x32_bf16 v[120:123], v[140:143], v[192:195], v[120:123]
	v_mfma_f32_16x16x32_bf16 v[108:111], v[132:135], v[200:203], v[108:111]
	v_mfma_f32_16x16x32_bf16 v[104:107], v[140:143], v[200:203], v[104:107]
	v_mfma_f32_16x16x32_bf16 v[92:95], v[132:135], v[208:211], v[92:95]
	v_mfma_f32_16x16x32_bf16 v[88:91], v[140:143], v[208:211], v[88:91]
	v_mfma_f32_16x16x32_bf16 v[76:79], v[132:135], v[216:219], v[76:79]
	v_mfma_f32_16x16x32_bf16 v[72:75], v[140:143], v[216:219], v[72:75]
	s_setprio 0
	s_setprio 1
	v_mfma_f32_16x16x32_bf16 v[112:115], v[172:175], v[188:191], v[112:115]
	v_mfma_f32_16x16x32_bf16 v[116:119], v[180:183], v[188:191], v[116:119]
	v_mfma_f32_16x16x32_bf16 v[96:99], v[172:175], v[196:199], v[96:99]
	v_mfma_f32_16x16x32_bf16 v[100:103], v[180:183], v[196:199], v[100:103]
	v_mfma_f32_16x16x32_bf16 v[80:83], v[172:175], v[204:207], v[80:83]
	v_mfma_f32_16x16x32_bf16 v[84:87], v[180:183], v[204:207], v[84:87]
	v_mfma_f32_16x16x32_bf16 v[64:67], v[172:175], v[212:215], v[64:67]
	v_mfma_f32_16x16x32_bf16 v[68:71], v[180:183], v[212:215], v[68:71]
	v_mfma_f32_16x16x32_bf16 v[112:115], v[176:179], v[192:195], v[112:115]
	v_mfma_f32_16x16x32_bf16 v[116:119], v[184:187], v[192:195], v[116:119]
	v_mfma_f32_16x16x32_bf16 v[96:99], v[176:179], v[200:203], v[96:99]
	v_mfma_f32_16x16x32_bf16 v[100:103], v[184:187], v[200:203], v[100:103]
	v_mfma_f32_16x16x32_bf16 v[80:83], v[176:179], v[208:211], v[80:83]
	v_mfma_f32_16x16x32_bf16 v[84:87], v[184:187], v[208:211], v[84:87]
	v_mfma_f32_16x16x32_bf16 v[64:67], v[176:179], v[216:219], v[64:67]
	v_mfma_f32_16x16x32_bf16 v[68:71], v[184:187], v[216:219], v[68:71]
	s_setprio 0
	s_barrier
	s_add_i32 s24, s29, s30
	v_lshl_add_u64 v[220:221], v[220:221], 0, s[12:13]
	s_mov_b32 m0, s24
	ds_read_b128 v[188:191], v171 offset:49152
	ds_read_b128 v[192:195], v171 offset:50176
	ds_read_b128 v[196:199], v171 offset:51200
	ds_read_b128 v[200:203], v171 offset:52224
	ds_read_b128 v[204:207], v171 offset:53248
	ds_read_b128 v[208:211], v171 offset:54272
	ds_read_b128 v[212:215], v171 offset:55296
	ds_read_b128 v[216:219], v171 offset:56320
	global_load_lds_dwordx4 v[220:221], off
	v_lshl_add_u64 v[220:221], v[222:223], 0, s[12:13]
	s_add_i32 m0, s24, 0x2000
	s_add_i32 s24, s36, s30
	global_load_lds_dwordx4 v[220:221], off
	v_lshl_add_u64 v[220:221], v[224:225], 0, s[12:13]
	s_mov_b32 m0, s24
	s_nop 0
	global_load_lds_dwordx4 v[220:221], off
	v_lshl_add_u64 v[220:221], v[226:227], 0, s[12:13]
	s_add_i32 m0, s24, 0x2000
	s_nop 0
	global_load_lds_dwordx4 v[220:221], off
	v_lshl_add_u64 v[220:221], v[228:229], 0, s[12:13]
	s_mov_b32 m0, s72
	s_nop 0
	global_load_lds_dwordx4 v[220:221], off
	v_lshl_add_u64 v[220:221], v[230:231], 0, s[12:13]
	s_mov_b32 m0, s73
	s_nop 0
	global_load_lds_dwordx4 v[220:221], off
	s_waitcnt vmcnt(8)
	s_waitcnt lgkmcnt(0)
	s_barrier
; #define PG8_STAGE(bufoff, gbase, voff) do { _Pragma("unroll") for (int _i = 0; _i < 2; ++_i) \
;         __builtin_amdgcn_global_load_lds((const unsigned*)((const char*)(gbase) + (voff)[_i]), (PG8_LAS unsigned*)(lds + (bufoff) + ldsw + _i * 8192), 16, 0, 0); } while (0)
; #define PG8_LDA(dst, b, h) do { _Pragma("unroll") for (int m = 0; m < 4; ++m) _Pragma("unroll") for (int k = 0; k < 2; ++k) dst[m][k] = *(const PG8_LAS bf16x8*)(lds + PG8_SA(b, h) + aoff + m * 2048 + k * 1024); } while (0)
; #define PG8_LDB(dst, b, h) do { _Pragma("unroll") for (int n = 0; n < 2; ++n) _Pragma("unroll") for (int k = 0; k < 2; ++k) dst[n][k] = *(const PG8_LAS bf16x8*)(lds + PG8_SB(b, h) + boff + n * 2048 + k * 1024); } while (0)
; #define PG8_MMA(ai, bj, At, Bt) do { __builtin_amdgcn_s_setprio(1); _Pragma("unroll") for (int m = 0; m < 4; ++m) _Pragma("unroll") for (int n = 0; n < 2; ++n) _Pragma("unroll") for (int k = 0; k < 2; ++k) \
;         acc[ai][bj][m][n] = __builtin_amdgcn_mfma_f32_16x16x32_bf16(Bt[n][k], At[m][k], acc[ai][bj][m][n], 0, 0, 0); __builtin_amdgcn_s_setprio(0); } while (0)
; #define PG8_WAIT_V(n) asm volatile("s_waitcnt vmcnt(" #n ")" ::: "memory")
; #define PG8_WAIT_L(n) asm volatile("s_waitcnt lgkmcnt(" #n ")" ::: "memory")
; template <class Epi, class Sched, bool ALIGN_EPI = false, bool SP2 = false>
; __device__ __forceinline__ void gemm_phase(PG8_LAS unsigned char* lds, const Gemm g, const Sched& S, const Epi& E, const int wave_in) {
;     ...
; #pragma unroll
;     for (int a = 0; a < 2; ++a)
; #pragma unroll
;         for (int b = 0; b < 2; ++b)
; #pragma unroll
;             for (int m = 0; m < 4; ++m)
; #pragma unroll
;                 for (int n = 0; n < 2; ++n) acc[a][b][m][n] = (f32x4){0.f, 0.f, 0.f, 0.f};
;     ...
;             PG8_WAIT_V(8); PG8_WAIT_L(0); PG8_BAR; PG8_MMA(1, 0, At, B0); PG8_MMA(1, 1, At, B1); PG8_BAR; PG8_SCHED;
;             PG8_LDB(B0, 1, 0); PG8_LDB(B1, 1, 1); PG8_SCHED; PG8_LDA(At, 1, 0); PG8_STAGE(PG8_SA(0, 1), a2 + hstep, voffA);
;             PG8_WAIT_V(8); PG8_WAIT_L(0); PG8_BAR; PG8_MMA(0, 0, At, B0); PG8_MMA(0, 1, At, B1); PG8_BAR; PG8_SCHED;
;             PG8_LDA(At, 1, 1); PG8_STAGE(PG8_SB(1, 0), b3, voffB); PG8_STAGE(PG8_SB(1, 1), b3 + hstep, voffB); PG8_STAGE(PG8_SA(1, 0), a3, voffA);
;             PG8_WAIT_V(8); PG8_WAIT_L(0); PG8_BAR; PG8_MMA(1, 0, At, B0); PG8_MMA(1, 1, At, B1); PG8_BAR; PG8_SCHED;
	s_setprio 1
	s_waitcnt lgkmcnt(0)
	v_mfma_f32_16x16x32_bf16 v[60:63], v[128:131], v[188:191], v[60:63]
	v_mfma_f32_16x16x32_bf16 v[56:59], v[136:139], v[188:191], v[56:59]
	v_mfma_f32_16x16x32_bf16 v[44:47], v[128:131], v[196:199], v[44:47]
	v_mfma_f32_16x16x32_bf16 v[40:43], v[136:139], v[196:199], v[40:43]
	v_mfma_f32_16x16x32_bf16 v[28:31], v[128:131], v[204:207], v[28:31]
	v_mfma_f32_16x16x32_bf16 v[24:27], v[136:139], v[204:207], v[24:27]
	v_mfma_f32_16x16x32_bf16 v[12:15], v[128:131], v[212:215], v[12:15]
	v_mfma_f32_16x16x32_bf16 v[8:11], v[136:139], v[212:215], v[8:11]
	v_mfma_f32_16x16x32_bf16 v[60:63], v[132:135], v[192:195], v[60:63]
	v_mfma_f32_16x16x32_bf16 v[56:59], v[140:143], v[192:195], v[56:59]
	v_mfma_f32_16x16x32_bf16 v[44:47], v[132:135], v[200:203], v[44:47]
	v_mfma_f32_16x16x32_bf16 v[40:43], v[140:143], v[200:203], v[40:43]
	v_mfma_f32_16x16x32_bf16 v[28:31], v[132:135], v[208:211], v[28:31]
	v_mfma_f32_16x16x32_bf16 v[24:27], v[140:143], v[208:211], v[24:27]
	v_mfma_f32_16x16x32_bf16 v[12:15], v[132:135], v[216:219], v[12:15]
	v_mfma_f32_16x16x32_bf16 v[8:11], v[140:143], v[216:219], v[8:11]
	s_setprio 0
	s_setprio 1
	v_mfma_f32_16x16x32_bf16 v[48:51], v[172:175], v[188:191], v[48:51]
	v_mfma_f32_16x16x32_bf16 v[52:55], v[180:183], v[188:191], v[52:55]
	v_mfma_f32_16x16x32_bf16 v[32:35], v[172:175], v[196:199], v[32:35]
	v_mfma_f32_16x16x32_bf16 v[36:39], v[180:183], v[196:199], v[36:39]
	v_mfma_f32_16x16x32_bf16 v[16:19], v[172:175], v[204:207], v[16:19]
	v_mfma_f32_16x16x32_bf16 v[20:23], v[180:183], v[204:207], v[20:23]
	v_mfma_f32_16x16x32_bf16 v[4:7], v[172:175], v[212:215], v[4:7]
	v_mfma_f32_16x16x32_bf16 v[0:3], v[180:183], v[212:215], v[0:3]
	v_mfma_f32_16x16x32_bf16 v[48:51], v[176:179], v[192:195], v[48:51]
	v_mfma_f32_16x16x32_bf16 v[52:55], v[184:187], v[192:195], v[52:55]
	v_mfma_f32_16x16x32_bf16 v[32:35], v[176:179], v[200:203], v[32:35]
	v_mfma_f32_16x16x32_bf16 v[36:39], v[184:187], v[200:203], v[36:39]
	v_mfma_f32_16x16x32_bf16 v[16:19], v[176:179], v[208:211], v[16:19]
	v_mfma_f32_16x16x32_bf16 v[20:23], v[184:187], v[208:211], v[20:23]
	v_mfma_f32_16x16x32_bf16 v[4:7], v[176:179], v[216:219], v[4:7]
	v_mfma_f32_16x16x32_bf16 v[0:3], v[184:187], v[216:219], v[0:3]
	s_setprio 0
	s_barrier
	s_add_u32 s2, s2, 0x100
	s_addc_u32 s3, s3, 0
	s_add_u32 s26, s26, 0x100
	s_addc_u32 s27, s27, 0
	s_cmp_ge_i32 s28, s74
	s_mov_b32 s24, s28
	s_cbranch_scc0 .LBB0_708
.Lkz_exit_1:
	s_branch .LBB0_709
.Lkz_skip_1:
	v_mov_b32_e32 v127, 0
	v_mov_b32_e32 v126, v127
	v_mov_b32_e32 v125, v127
	v_mov_b32_e32 v124, v127
	v_mov_b32_e32 v123, v127
	v_mov_b32_e32 v122, v127
	v_mov_b32_e32 v121, v127
	v_mov_b32_e32 v120, v127
	v_mov_b32_e32 v111, v127
	v_mov_b32_e32 v110, v127
	v_mov_b32_e32 v109, v127
	v_mov_b32_e32 v108, v127
	v_mov_b32_e32 v107, v127
	v_mov_b32_e32 v106, v127
	v_mov_b32_e32 v105, v127
	v_mov_b32_e32 v104, v127
	v_mov_b32_e32 v95, v127
	v_mov_b32_e32 v94, v127
	v_mov_b32_e32 v93, v127
	v_mov_b32_e32 v92, v127
	v_mov_b32_e32 v91, v127
	v_mov_b32_e32 v90, v127
	v_mov_b32_e32 v89, v127
	v_mov_b32_e32 v88, v127
	v_mov_b32_e32 v79, v127
	v_mov_b32_e32 v78, v127
	v_mov_b32_e32 v77, v127
	v_mov_b32_e32 v76, v127
	v_mov_b32_e32 v75, v127
	v_mov_b32_e32 v74, v127
	v_mov_b32_e32 v73, v127
	v_mov_b32_e32 v72, v127
	v_mov_b32_e32 v115, v127
	v_mov_b32_e32 v114, v127
	v_mov_b32_e32 v113, v127
	v_mov_b32_e32 v112, v127
	v_mov_b32_e32 v119, v127
	v_mov_b32_e32 v118, v127
	v_mov_b32_e32 v117, v127
	v_mov_b32_e32 v116, v127
	v_mov_b32_e32 v99, v127
	v_mov_b32_e32 v98, v127
	v_mov_b32_e32 v97, v127
	v_mov_b32_e32 v96, v127
	v_mov_b32_e32 v103, v127
	v_mov_b32_e32 v102, v127
	v_mov_b32_e32 v101, v127
	v_mov_b32_e32 v100, v127
	v_mov_b32_e32 v83, v127
	v_mov_b32_e32 v82, v127
	v_mov_b32_e32 v81, v127
	v_mov_b32_e32 v80, v127
	v_mov_b32_e32 v87, v127
	v_mov_b32_e32 v86, v127
	v_mov_b32_e32 v85, v127
	v_mov_b32_e32 v84, v127
	v_mov_b32_e32 v67, v127
	v_mov_b32_e32 v66, v127
	v_mov_b32_e32 v65, v127
	v_mov_b32_e32 v64, v127
	v_mov_b32_e32 v71, v127
	v_mov_b32_e32 v70, v127
	v_mov_b32_e32 v69, v127
	v_mov_b32_e32 v68, v127
	v_mov_b32_e32 v63, v127
	v_mov_b32_e32 v62, v127
	v_mov_b32_e32 v61, v127
	v_mov_b32_e32 v60, v127
	v_mov_b32_e32 v59, v127
	v_mov_b32_e32 v58, v127
	v_mov_b32_e32 v57, v127
	v_mov_b32_e32 v56, v127
	v_mov_b32_e32 v47, v127
	v_mov_b32_e32 v46, v127
	v_mov_b32_e32 v45, v127
	v_mov_b32_e32 v44, v127
	v_mov_b32_e32 v43, v127
	v_mov_b32_e32 v42, v127
	v_mov_b32_e32 v41, v127
	v_mov_b32_e32 v40, v127
	v_mov_b32_e32 v31, v127
	v_mov_b32_e32 v30, v127
	v_mov_b32_e32 v29, v127
	v_mov_b32_e32 v28, v127
	v_mov_b32_e32 v27, v127
	v_mov_b32_e32 v26, v127
	v_mov_b32_e32 v25, v127
	v_mov_b32_e32 v24, v127
	v_mov_b32_e32 v15, v127
	v_mov_b32_e32 v14, v127
	v_mov_b32_e32 v13, v127
	v_mov_b32_e32 v12, v127
	v_mov_b32_e32 v11, v127
	v_mov_b32_e32 v10, v127
	v_mov_b32_e32 v9, v127
	v_mov_b32_e32 v8, v127
	v_mov_b32_e32 v51, v127
	v_mov_b32_e32 v50, v127
	v_mov_b32_e32 v49, v127
	v_mov_b32_e32 v48, v127
	v_mov_b32_e32 v55, v127
	v_mov_b32_e32 v54, v127
	v_mov_b32_e32 v53, v127
	v_mov_b32_e32 v52, v127
	v_mov_b32_e32 v35, v127
	v_mov_b32_e32 v34, v127
	v_mov_b32_e32 v33, v127
	v_mov_b32_e32 v32, v127
	v_mov_b32_e32 v39, v127
	v_mov_b32_e32 v38, v127
	v_mov_b32_e32 v37, v127
	v_mov_b32_e32 v36, v127
	v_mov_b32_e32 v19, v127
	v_mov_b32_e32 v18, v127
	v_mov_b32_e32 v17, v127
	v_mov_b32_e32 v16, v127
	v_mov_b32_e32 v23, v127
	v_mov_b32_e32 v22, v127
	v_mov_b32_e32 v21, v127
	v_mov_b32_e32 v20, v127
	v_mov_b32_e32 v7, v127
	v_mov_b32_e32 v6, v127
	v_mov_b32_e32 v5, v127
	v_mov_b32_e32 v4, v127
	v_mov_b32_e32 v3, v127
	v_mov_b32_e32 v2, v127
	v_mov_b32_e32 v1, v127
	v_mov_b32_e32 v0, v127

; #define PG8_STAGE(bufoff, gbase, voff) do { _Pragma("unroll") for (int _i = 0; _i < 2; ++_i) \
;         __builtin_amdgcn_global_load_lds((const unsigned*)((const char*)(gbase) + (voff)[_i]), (PG8_LAS unsigned*)(lds + (bufoff) + ldsw + _i * 8192), 16, 0, 0); } while (0)
; #define PG8_LDA(dst, b, h) do { _Pragma("unroll") for (int m = 0; m < 4; ++m) _Pragma("unroll") for (int k = 0; k < 2; ++k) dst[m][k] = *(const PG8_LAS bf16x8*)(lds + PG8_SA(b, h) + aoff + m * 2048 + k * 1024); } while (0)
; #define PG8_LDB(dst, b, h) do { _Pragma("unroll") for (int n = 0; n < 2; ++n) _Pragma("unroll") for (int k = 0; k < 2; ++k) dst[n][k] = *(const PG8_LAS bf16x8*)(lds + PG8_SB(b, h) + boff + n * 2048 + k * 1024); } while (0)
; #define PG8_MMA(ai, bj, At, Bt) do { __builtin_amdgcn_s_setprio(1); _Pragma("unroll") for (int m = 0; m < 4; ++m) _Pragma("unroll") for (int n = 0; n < 2; ++n) _Pragma("unroll") for (int k = 0; k < 2; ++k) \
;         acc[ai][bj][m][n] = __builtin_amdgcn_mfma_f32_16x16x32_bf16(Bt[n][k], At[m][k], acc[ai][bj][m][n], 0, 0, 0); __builtin_amdgcn_s_setprio(0); } while (0)
; #define PG8_WAIT_V(n) asm volatile("s_waitcnt vmcnt(" #n ")" ::: "memory")
; #define PG8_WAIT_L(n) asm volatile("s_waitcnt lgkmcnt(" #n ")" ::: "memory")
; #define PG8_BAR __builtin_amdgcn_s_barrier()
; #define PG8_SCHED __builtin_amdgcn_sched_barrier(0)
; template <class Epi, class Sched, bool ALIGN_EPI = false, bool SP2 = false>
; __device__ __forceinline__ void gemm_phase(PG8_LAS unsigned char* lds, const Gemm g, const Sched& S, const Epi& E, const int wave_in) {
;     ...
;     f32x4 acc[2][2][4][2];
; #pragma unroll
;     for (int a = 0; a < 2; ++a)
; #pragma unroll
;         for (int b = 0; b < 2; ++b)
; #pragma unroll
;             for (int m = 0; m < 4; ++m)
; #pragma unroll
;                 for (int n = 0; n < 2; ++n) acc[a][b][m][n] = (f32x4){0.f, 0.f, 0.f, 0.f};
;     ...
;             PG8_LDB(B0, 0, 0); PG8_LDB(B1, 0, 1); PG8_SCHED; PG8_LDA(At, 0, 0); PG8_STAGE(PG8_SA(1, 1), a1 + hstep, voffA);
;             PG8_WAIT_V(8); PG8_WAIT_L(0); PG8_BAR; PG8_MMA(0, 0, At, B0); PG8_MMA(0, 1, At, B1); PG8_BAR; PG8_SCHED;
;             PG8_LDA(At, 0, 1); PG8_STAGE(PG8_SB(0, 0), b2, voffB); PG8_STAGE(PG8_SB(0, 1), b2 + hstep, voffB); PG8_STAGE(PG8_SA(0, 0), a2, voffA);
;             PG8_WAIT_V(8); PG8_WAIT_L(0); PG8_BAR; PG8_MMA(1, 0, At, B0); PG8_MMA(1, 1, At, B1); PG8_BAR; PG8_SCHED;
.LBB0_767:
	s_andn2_b64 vcc, exec, s[14:15]
	s_cbranch_vccnz .Lkz_skip_2
	s_add_u32 s20, s20, 0x80
	s_addc_u32 s21, s21, 0
	s_add_u32 s75, s22, 0x100
	s_addc_u32 s78, s23, 0
	s_mov_b32 s22, 0
	ds_read_b128 v[150:153], v147
	ds_read_b128 v[154:157], v147 offset:1024
	ds_read_b128 v[158:161], v147 offset:2048
	ds_read_b128 v[162:165], v147 offset:3072
	ds_read_b128 v[166:169], v148
	ds_read_b128 v[170:173], v148 offset:1024
	ds_read_b128 v[174:177], v148 offset:2048
	ds_read_b128 v[178:181], v148 offset:3072
	s_add_i32 s28, s22, 2
	s_add_u32 s29, s20, 0x80
	s_addc_u32 s23, s21, 0
	s_cmp_eq_u32 s31, s22
	s_cselect_b32 s22, s2, s29
	s_cselect_b32 s23, s3, s23
	s_cselect_b32 s37, s19, s78
	s_cselect_b32 s36, s18, s75
	v_lshl_add_u64 v[214:215], s[20:21], 0, v[136:137]
	s_add_i32 m0, s41, 0xc000
	ds_read_b128 v[182:185], v149
	ds_read_b128 v[186:189], v149 offset:1024
	ds_read_b128 v[190:193], v149 offset:2048
	ds_read_b128 v[194:197], v149 offset:3072
	ds_read_b128 v[198:201], v149 offset:4096
	ds_read_b128 v[202:205], v149 offset:5120
	ds_read_b128 v[206:209], v149 offset:6144
	ds_read_b128 v[210:213], v149 offset:7168
	global_load_lds_dwordx4 v[214:215], off
	v_lshl_add_u64 v[214:215], s[20:21], 0, v[138:139]
	s_add_i32 m0, s41, 0xe000
	s_nop 0
	global_load_lds_dwordx4 v[214:215], off
	s_waitcnt vmcnt(8)
	s_waitcnt lgkmcnt(0)
	s_barrier
	s_setprio 1
	s_waitcnt lgkmcnt(0)
	v_mfma_f32_16x16x32_bf16 v[120:123], v[150:153], v[182:185], 0
	v_mfma_f32_16x16x32_bf16 v[124:127], v[158:161], v[182:185], 0
	v_mfma_f32_16x16x32_bf16 v[108:111], v[150:153], v[190:193], 0
	v_mfma_f32_16x16x32_bf16 v[104:107], v[158:161], v[190:193], 0
	v_mfma_f32_16x16x32_bf16 v[92:95], v[150:153], v[198:201], 0
	v_mfma_f32_16x16x32_bf16 v[88:91], v[158:161], v[198:201], 0
	v_mfma_f32_16x16x32_bf16 v[76:79], v[150:153], v[206:209], 0
	v_mfma_f32_16x16x32_bf16 v[72:75], v[158:161], v[206:209], 0
	v_mfma_f32_16x16x32_bf16 v[120:123], v[154:157], v[186:189], v[120:123]
	v_mfma_f32_16x16x32_bf16 v[124:127], v[162:165], v[186:189], v[124:127]
	v_mfma_f32_16x16x32_bf16 v[108:111], v[154:157], v[194:197], v[108:111]
	v_mfma_f32_16x16x32_bf16 v[104:107], v[162:165], v[194:197], v[104:107]
	v_mfma_f32_16x16x32_bf16 v[92:95], v[154:157], v[202:205], v[92:95]
	v_mfma_f32_16x16x32_bf16 v[88:91], v[162:165], v[202:205], v[88:91]
	v_mfma_f32_16x16x32_bf16 v[76:79], v[154:157], v[210:213], v[76:79]
	v_mfma_f32_16x16x32_bf16 v[72:75], v[162:165], v[210:213], v[72:75]
	s_setprio 0
	s_setprio 1
	v_mfma_f32_16x16x32_bf16 v[116:119], v[166:169], v[182:185], 0
	v_mfma_f32_16x16x32_bf16 v[112:115], v[174:177], v[182:185], 0
	v_mfma_f32_16x16x32_bf16 v[100:103], v[166:169], v[190:193], 0
	v_mfma_f32_16x16x32_bf16 v[96:99], v[174:177], v[190:193], 0
	v_mfma_f32_16x16x32_bf16 v[84:87], v[166:169], v[198:201], 0
	v_mfma_f32_16x16x32_bf16 v[80:83], v[174:177], v[198:201], 0
	v_mfma_f32_16x16x32_bf16 v[68:71], v[166:169], v[206:209], 0
	v_mfma_f32_16x16x32_bf16 v[64:67], v[174:177], v[206:209], 0
	v_mfma_f32_16x16x32_bf16 v[116:119], v[170:173], v[186:189], v[116:119]
	v_mfma_f32_16x16x32_bf16 v[112:115], v[178:181], v[186:189], v[112:115]
	v_mfma_f32_16x16x32_bf16 v[100:103], v[170:173], v[194:197], v[100:103]
	v_mfma_f32_16x16x32_bf16 v[96:99], v[178:181], v[194:197], v[96:99]
	v_mfma_f32_16x16x32_bf16 v[84:87], v[170:173], v[202:205], v[84:87]
	v_mfma_f32_16x16x32_bf16 v[80:83], v[178:181], v[202:205], v[80:83]
	v_mfma_f32_16x16x32_bf16 v[68:71], v[170:173], v[210:213], v[68:71]
	v_mfma_f32_16x16x32_bf16 v[64:67], v[178:181], v[210:213], v[64:67]
	s_setprio 0
	s_barrier
	s_add_i32 s29, s34, s30
	v_lshl_add_u64 v[214:215], s[36:37], 0, v[130:131]
	s_mov_b32 m0, s29
	ds_read_b128 v[182:185], v149 offset:16384
	ds_read_b128 v[186:189], v149 offset:17408
	ds_read_b128 v[190:193], v149 offset:18432
	ds_read_b128 v[194:197], v149 offset:19456
	ds_read_b128 v[198:201], v149 offset:20480
	ds_read_b128 v[202:205], v149 offset:21504
	ds_read_b128 v[206:209], v149 offset:22528
	ds_read_b128 v[210:213], v149 offset:23552
	global_load_lds_dwordx4 v[214:215], off
	s_add_i32 m0, s29, 0x2000
	v_lshl_add_u64 v[216:217], s[36:37], 0, v[134:135]
	s_add_u32 s36, s36, s4
	s_addc_u32 s37, s37, s5
	s_add_i32 s29, s69, s30
	global_load_lds_dwordx4 v[216:217], off
	v_lshl_add_u64 v[218:219], s[36:37], 0, v[130:131]
	s_mov_b32 m0, s29
	v_lshl_add_u64 v[220:221], s[36:37], 0, v[134:135]
	global_load_lds_dwordx4 v[218:219], off
	s_add_i32 m0, s29, 0x2000
	v_lshl_add_u64 v[222:223], s[22:23], 0, v[128:129]
	global_load_lds_dwordx4 v[220:221], off
	s_mov_b32 m0, s41
	v_lshl_add_u64 v[224:225], s[22:23], 0, v[132:133]
	global_load_lds_dwordx4 v[222:223], off
	s_mov_b32 m0, s46
	s_nop 0
	global_load_lds_dwordx4 v[224:225], off
	s_waitcnt vmcnt(8)
	s_waitcnt lgkmcnt(0)
	s_barrier
; #define PG8_STAGE(bufoff, gbase, voff) do { _Pragma("unroll") for (int _i = 0; _i < 2; ++_i) \
;         __builtin_amdgcn_global_load_lds((const unsigned*)((const char*)(gbase) + (voff)[_i]), (PG8_LAS unsigned*)(lds + (bufoff) + ldsw + _i * 8192), 16, 0, 0); } while (0)
; #define PG8_LDA(dst, b, h) do { _Pragma("unroll") for (int m = 0; m < 4; ++m) _Pragma("unroll") for (int k = 0; k < 2; ++k) dst[m][k] = *(const PG8_LAS bf16x8*)(lds + PG8_SA(b, h) + aoff + m * 2048 + k * 1024); } while (0)
; #define PG8_LDB(dst, b, h) do { _Pragma("unroll") for (int n = 0; n < 2; ++n) _Pragma("unroll") for (int k = 0; k < 2; ++k) dst[n][k] = *(const PG8_LAS bf16x8*)(lds + PG8_SB(b, h) + boff + n * 2048 + k * 1024); } while (0)
; #define PG8_MMA(ai, bj, At, Bt) do { __builtin_amdgcn_s_setprio(1); _Pragma("unroll") for (int m = 0; m < 4; ++m) _Pragma("unroll") for (int n = 0; n < 2; ++n) _Pragma("unroll") for (int k = 0; k < 2; ++k) \
;         acc[ai][bj][m][n] = __builtin_amdgcn_mfma_f32_16x16x32_bf16(Bt[n][k], At[m][k], acc[ai][bj][m][n], 0, 0, 0); __builtin_amdgcn_s_setprio(0); } while (0)
; #define PG8_WAIT_V(n) asm volatile("s_waitcnt vmcnt(" #n ")" ::: "memory")
; #define PG8_WAIT_L(n) asm volatile("s_waitcnt lgkmcnt(" #n ")" ::: "memory")
; #define PG8_BAR __builtin_amdgcn_s_barrier()
; #define PG8_SCHED __builtin_amdgcn_sched_barrier(0)
; template <class Epi, class Sched, bool ALIGN_EPI = false, bool SP2 = false>
; __device__ __forceinline__ void gemm_phase(PG8_LAS unsigned char* lds, const Gemm g, const Sched& S, const Epi& E, const int wave_in) {
;     ...
;             PG8_WAIT_V(8); PG8_WAIT_L(0); PG8_BAR; PG8_MMA(0, 0, At, B0); PG8_MMA(0, 1, At, B1); PG8_BAR; PG8_SCHED;
;             PG8_LDA(At, 0, 1); PG8_STAGE(PG8_SB(0, 0), b2, voffB); PG8_STAGE(PG8_SB(0, 1), b2 + hstep, voffB); PG8_STAGE(PG8_SA(0, 0), a2, voffA);
;             PG8_WAIT_V(8); PG8_WAIT_L(0); PG8_BAR; PG8_MMA(1, 0, At, B0); PG8_MMA(1, 1, At, B1); PG8_BAR; PG8_SCHED;
;             PG8_LDB(B0, 1, 0); PG8_LDB(B1, 1, 1); PG8_SCHED; PG8_LDA(At, 1, 0); PG8_STAGE(PG8_SA(0, 1), a2 + hstep, voffA);
;             PG8_WAIT_V(8); PG8_WAIT_L(0); PG8_BAR; PG8_MMA(0, 0, At, B0); PG8_MMA(0, 1, At, B1); PG8_BAR; PG8_SCHED;
	s_setprio 1
	s_waitcnt lgkmcnt(0)
	v_mfma_f32_16x16x32_bf16 v[60:63], v[150:153], v[182:185], 0
	v_mfma_f32_16x16x32_bf16 v[56:59], v[158:161], v[182:185], 0
	v_mfma_f32_16x16x32_bf16 v[44:47], v[150:153], v[190:193], 0
	v_mfma_f32_16x16x32_bf16 v[40:43], v[158:161], v[190:193], 0
	v_mfma_f32_16x16x32_bf16 v[28:31], v[150:153], v[198:201], 0
	v_mfma_f32_16x16x32_bf16 v[24:27], v[158:161], v[198:201], 0
	v_mfma_f32_16x16x32_bf16 v[12:15], v[150:153], v[206:209], 0
	v_mfma_f32_16x16x32_bf16 v[8:11], v[158:161], v[206:209], 0
	v_mfma_f32_16x16x32_bf16 v[60:63], v[154:157], v[186:189], v[60:63]
	v_mfma_f32_16x16x32_bf16 v[56:59], v[162:165], v[186:189], v[56:59]
	v_mfma_f32_16x16x32_bf16 v[44:47], v[154:157], v[194:197], v[44:47]
	v_mfma_f32_16x16x32_bf16 v[40:43], v[162:165], v[194:197], v[40:43]
	v_mfma_f32_16x16x32_bf16 v[28:31], v[154:157], v[202:205], v[28:31]
	v_mfma_f32_16x16x32_bf16 v[24:27], v[162:165], v[202:205], v[24:27]
	v_mfma_f32_16x16x32_bf16 v[12:15], v[154:157], v[210:213], v[12:15]
	v_mfma_f32_16x16x32_bf16 v[8:11], v[162:165], v[210:213], v[8:11]
	s_setprio 0
	s_setprio 1
	v_mfma_f32_16x16x32_bf16 v[52:55], v[166:169], v[182:185], 0
	v_mfma_f32_16x16x32_bf16 v[48:51], v[174:177], v[182:185], 0
	v_mfma_f32_16x16x32_bf16 v[36:39], v[166:169], v[190:193], 0
	v_mfma_f32_16x16x32_bf16 v[32:35], v[174:177], v[190:193], 0
	v_mfma_f32_16x16x32_bf16 v[20:23], v[166:169], v[198:201], 0
	v_mfma_f32_16x16x32_bf16 v[16:19], v[174:177], v[198:201], 0
	v_mfma_f32_16x16x32_bf16 v[4:7], v[166:169], v[206:209], 0
	v_mfma_f32_16x16x32_bf16 v[0:3], v[174:177], v[206:209], 0
	v_mfma_f32_16x16x32_bf16 v[52:55], v[170:173], v[186:189], v[52:55]
	v_mfma_f32_16x16x32_bf16 v[48:51], v[178:181], v[186:189], v[48:51]
	v_mfma_f32_16x16x32_bf16 v[36:39], v[170:173], v[194:197], v[36:39]
	v_mfma_f32_16x16x32_bf16 v[32:35], v[178:181], v[194:197], v[32:35]
	v_mfma_f32_16x16x32_bf16 v[20:23], v[170:173], v[202:205], v[20:23]
	v_mfma_f32_16x16x32_bf16 v[16:19], v[178:181], v[202:205], v[16:19]
	v_mfma_f32_16x16x32_bf16 v[4:7], v[170:173], v[210:213], v[4:7]
	v_mfma_f32_16x16x32_bf16 v[0:3], v[178:181], v[210:213], v[0:3]
	s_setprio 0
	s_barrier
	s_add_i32 s29, 0, 0x18000
	s_add_i32 s36, 0, 0x1c000
	v_add_u32_e32 v162, s29, v145
	v_add_u32_e32 v178, s36, v145
	ds_read_b128 v[150:153], v162
	ds_read_b128 v[154:157], v162 offset:1024
	ds_read_b128 v[158:161], v162 offset:2048
	ds_read_b128 v[162:165], v162 offset:3072
	ds_read_b128 v[166:169], v178
	ds_read_b128 v[170:173], v178 offset:1024
	ds_read_b128 v[174:177], v178 offset:2048
	ds_read_b128 v[178:181], v178 offset:3072
	s_add_u32 s22, s22, s4
	s_addc_u32 s23, s23, s5
	s_mov_b32 m0, s47
	v_lshl_add_u64 v[226:227], s[22:23], 0, v[128:129]
	ds_read_b128 v[182:185], v149 offset:32768
	ds_read_b128 v[186:189], v149 offset:33792
	ds_read_b128 v[190:193], v149 offset:34816
	ds_read_b128 v[194:197], v149 offset:35840
	ds_read_b128 v[198:201], v149 offset:36864
	ds_read_b128 v[202:205], v149 offset:37888
	ds_read_b128 v[206:209], v149 offset:38912
	ds_read_b128 v[210:213], v149 offset:39936
	global_load_lds_dwordx4 v[226:227], off
	v_lshl_add_u64 v[226:227], s[22:23], 0, v[132:133]
	s_mov_b32 m0, s50
	s_nop 0
	global_load_lds_dwordx4 v[226:227], off
	s_waitcnt vmcnt(8)
	s_waitcnt lgkmcnt(0)
	s_barrier
	s_setprio 1
	s_waitcnt lgkmcnt(0)
	v_mfma_f32_16x16x32_bf16 v[120:123], v[150:153], v[182:185], v[120:123]
	v_mfma_f32_16x16x32_bf16 v[124:127], v[158:161], v[182:185], v[124:127]
	v_mfma_f32_16x16x32_bf16 v[108:111], v[150:153], v[190:193], v[108:111]
	v_mfma_f32_16x16x32_bf16 v[104:107], v[158:161], v[190:193], v[104:107]
	v_mfma_f32_16x16x32_bf16 v[92:95], v[150:153], v[198:201], v[92:95]
	v_mfma_f32_16x16x32_bf16 v[88:91], v[158:161], v[198:201], v[88:91]
	v_mfma_f32_16x16x32_bf16 v[76:79], v[150:153], v[206:209], v[76:79]
	v_mfma_f32_16x16x32_bf16 v[72:75], v[158:161], v[206:209], v[72:75]
	v_mfma_f32_16x16x32_bf16 v[120:123], v[154:157], v[186:189], v[120:123]
	v_mfma_f32_16x16x32_bf16 v[124:127], v[162:165], v[186:189], v[124:127]
	v_mfma_f32_16x16x32_bf16 v[108:111], v[154:157], v[194:197], v[108:111]
	v_mfma_f32_16x16x32_bf16 v[104:107], v[162:165], v[194:197], v[104:107]
	v_mfma_f32_16x16x32_bf16 v[92:95], v[154:157], v[202:205], v[92:95]
	v_mfma_f32_16x16x32_bf16 v[88:91], v[162:165], v[202:205], v[88:91]
	v_mfma_f32_16x16x32_bf16 v[76:79], v[154:157], v[210:213], v[76:79]
	v_mfma_f32_16x16x32_bf16 v[72:75], v[162:165], v[210:213], v[72:75]
	s_setprio 0
	s_setprio 1
	v_mfma_f32_16x16x32_bf16 v[116:119], v[166:169], v[182:185], v[116:119]
	v_mfma_f32_16x16x32_bf16 v[112:115], v[174:177], v[182:185], v[112:115]
	v_mfma_f32_16x16x32_bf16 v[100:103], v[166:169], v[190:193], v[100:103]
	v_mfma_f32_16x16x32_bf16 v[96:99], v[174:177], v[190:193], v[96:99]
	v_mfma_f32_16x16x32_bf16 v[84:87], v[166:169], v[198:201], v[84:87]
	v_mfma_f32_16x16x32_bf16 v[80:83], v[174:177], v[198:201], v[80:83]
	v_mfma_f32_16x16x32_bf16 v[68:71], v[166:169], v[206:209], v[68:71]
	v_mfma_f32_16x16x32_bf16 v[64:67], v[174:177], v[206:209], v[64:67]
	v_mfma_f32_16x16x32_bf16 v[116:119], v[170:173], v[186:189], v[116:119]
	v_mfma_f32_16x16x32_bf16 v[112:115], v[178:181], v[186:189], v[112:115]
	v_mfma_f32_16x16x32_bf16 v[100:103], v[170:173], v[194:197], v[100:103]
	v_mfma_f32_16x16x32_bf16 v[96:99], v[178:181], v[194:197], v[96:99]
	v_mfma_f32_16x16x32_bf16 v[84:87], v[170:173], v[202:205], v[84:87]
	v_mfma_f32_16x16x32_bf16 v[80:83], v[178:181], v[202:205], v[80:83]
	v_mfma_f32_16x16x32_bf16 v[68:71], v[170:173], v[210:213], v[68:71]
	v_mfma_f32_16x16x32_bf16 v[64:67], v[178:181], v[210:213], v[64:67]
	s_setprio 0
	s_barrier
; #define PG8_STAGE(bufoff, gbase, voff) do { _Pragma("unroll") for (int _i = 0; _i < 2; ++_i) \
;         __builtin_amdgcn_global_load_lds((const unsigned*)((const char*)(gbase) + (voff)[_i]), (PG8_LAS unsigned*)(lds + (bufoff) + ldsw + _i * 8192), 16, 0, 0); } while (0)
; #define PG8_LDA(dst, b, h) do { _Pragma("unroll") for (int m = 0; m < 4; ++m) _Pragma("unroll") for (int k = 0; k < 2; ++k) dst[m][k] = *(const PG8_LAS bf16x8*)(lds + PG8_SA(b, h) + aoff + m * 2048 + k * 1024); } while (0)
; #define PG8_LDB(dst, b, h) do { _Pragma("unroll") for (int n = 0; n < 2; ++n) _Pragma("unroll") for (int k = 0; k < 2; ++k) dst[n][k] = *(const PG8_LAS bf16x8*)(lds + PG8_SB(b, h) + boff + n * 2048 + k * 1024); } while (0)
; #define PG8_MMA(ai, bj, At, Bt) do { __builtin_amdgcn_s_setprio(1); _Pragma("unroll") for (int m = 0; m < 4; ++m) _Pragma("unroll") for (int n = 0; n < 2; ++n) _Pragma("unroll") for (int k = 0; k < 2; ++k) \
;         acc[ai][bj][m][n] = __builtin_amdgcn_mfma_f32_16x16x32_bf16(Bt[n][k], At[m][k], acc[ai][bj][m][n], 0, 0, 0); __builtin_amdgcn_s_setprio(0); } while (0)
; #define PG8_WAIT_V(n) asm volatile("s_waitcnt vmcnt(" #n ")" ::: "memory")
; #define PG8_BAR __builtin_amdgcn_s_barrier()
; template <class Epi, class Sched, bool ALIGN_EPI = false, bool SP2 = false>
; __device__ __forceinline__ void gemm_phase(PG8_LAS unsigned char* lds, const Gemm g, const Sched& S, const Epi& E, const int wave_in) {
;     ...
;         for (int t = 0; t < nt; t += 2) {
;             const bool last = (t == nt - 2);
;             const char* a1 = cA + (size_t)(t + 1) * kstep;
;             const char* a2 = last ? nA : cA + (size_t)(t + 2) * kstep; const char* b2 = last ? nB : cB + (size_t)(t + 2) * kstep;
;             const char* a3 = a2 + kstep; const char* b3 = b2 + kstep;
;             if (last && has_next) S.a_ready(nxt);
;             if constexpr (SP2) {
;             PG8_LDB(B0, 0, 0); PG8_LDB(B1, 0, 1); PG8_SCHED; PG8_LDA(At, 0, 0); PG8_STAGE(PG8_SA(1, 1), a1 + hstep, voffA);
;     ...
;             PG8_WAIT_V(8); PG8_WAIT_L(0); PG8_BAR; PG8_MMA(0, 0, At, B0); PG8_MMA(0, 1, At, B1); PG8_BAR; PG8_SCHED;
;             PG8_LDA(At, 1, 1); PG8_STAGE(PG8_SB(1, 0), b3, voffB); PG8_STAGE(PG8_SB(1, 1), b3 + hstep, voffB); PG8_STAGE(PG8_SA(1, 0), a3, voffA);
;             PG8_WAIT_V(8); PG8_WAIT_L(0); PG8_BAR; PG8_MMA(1, 0, At, B0); PG8_MMA(1, 1, At, B1); PG8_BAR; PG8_SCHED;
	s_add_i32 s22, s29, s30
	v_lshl_add_u64 v[214:215], v[214:215], 0, s[12:13]
	s_mov_b32 m0, s22
	ds_read_b128 v[182:185], v149 offset:49152
	ds_read_b128 v[186:189], v149 offset:50176
	ds_read_b128 v[190:193], v149 offset:51200
	ds_read_b128 v[194:197], v149 offset:52224
	ds_read_b128 v[198:201], v149 offset:53248
	ds_read_b128 v[202:205], v149 offset:54272
	ds_read_b128 v[206:209], v149 offset:55296
	ds_read_b128 v[210:213], v149 offset:56320
	global_load_lds_dwordx4 v[214:215], off
	v_lshl_add_u64 v[214:215], v[216:217], 0, s[12:13]
	s_add_i32 m0, s22, 0x2000
	s_add_i32 s22, s36, s30
	global_load_lds_dwordx4 v[214:215], off
	v_lshl_add_u64 v[214:215], v[218:219], 0, s[12:13]
	s_mov_b32 m0, s22
	s_nop 0
	global_load_lds_dwordx4 v[214:215], off
	v_lshl_add_u64 v[214:215], v[220:221], 0, s[12:13]
	s_add_i32 m0, s22, 0x2000
	s_nop 0
	global_load_lds_dwordx4 v[214:215], off
	v_lshl_add_u64 v[214:215], v[222:223], 0, s[12:13]
	s_mov_b32 m0, s35
	s_nop 0
	global_load_lds_dwordx4 v[214:215], off
	v_lshl_add_u64 v[214:215], v[224:225], 0, s[12:13]
	s_mov_b32 m0, s52
	s_nop 0
	global_load_lds_dwordx4 v[214:215], off
	s_waitcnt vmcnt(8)
	s_waitcnt lgkmcnt(0)
	s_barrier
	s_setprio 1
	s_waitcnt lgkmcnt(0)
	v_mfma_f32_16x16x32_bf16 v[60:63], v[150:153], v[182:185], v[60:63]
	v_mfma_f32_16x16x32_bf16 v[56:59], v[158:161], v[182:185], v[56:59]
	v_mfma_f32_16x16x32_bf16 v[44:47], v[150:153], v[190:193], v[44:47]
	v_mfma_f32_16x16x32_bf16 v[40:43], v[158:161], v[190:193], v[40:43]
	v_mfma_f32_16x16x32_bf16 v[28:31], v[150:153], v[198:201], v[28:31]
	v_mfma_f32_16x16x32_bf16 v[24:27], v[158:161], v[198:201], v[24:27]
	v_mfma_f32_16x16x32_bf16 v[12:15], v[150:153], v[206:209], v[12:15]
	v_mfma_f32_16x16x32_bf16 v[8:11], v[158:161], v[206:209], v[8:11]
	v_mfma_f32_16x16x32_bf16 v[60:63], v[154:157], v[186:189], v[60:63]
	v_mfma_f32_16x16x32_bf16 v[56:59], v[162:165], v[186:189], v[56:59]
	v_mfma_f32_16x16x32_bf16 v[44:47], v[154:157], v[194:197], v[44:47]
	v_mfma_f32_16x16x32_bf16 v[40:43], v[162:165], v[194:197], v[40:43]
	v_mfma_f32_16x16x32_bf16 v[28:31], v[154:157], v[202:205], v[28:31]
	v_mfma_f32_16x16x32_bf16 v[24:27], v[162:165], v[202:205], v[24:27]
	v_mfma_f32_16x16x32_bf16 v[12:15], v[154:157], v[210:213], v[12:15]
	v_mfma_f32_16x16x32_bf16 v[8:11], v[162:165], v[210:213], v[8:11]
	s_setprio 0
	s_setprio 1
	v_mfma_f32_16x16x32_bf16 v[52:55], v[166:169], v[182:185], v[52:55]
	v_mfma_f32_16x16x32_bf16 v[48:51], v[174:177], v[182:185], v[48:51]
	v_mfma_f32_16x16x32_bf16 v[36:39], v[166:169], v[190:193], v[36:39]
	v_mfma_f32_16x16x32_bf16 v[32:35], v[174:177], v[190:193], v[32:35]
	v_mfma_f32_16x16x32_bf16 v[20:23], v[166:169], v[198:201], v[20:23]
	v_mfma_f32_16x16x32_bf16 v[16:19], v[174:177], v[198:201], v[16:19]
	v_mfma_f32_16x16x32_bf16 v[4:7], v[166:169], v[206:209], v[4:7]
	v_mfma_f32_16x16x32_bf16 v[0:3], v[174:177], v[206:209], v[0:3]
	v_mfma_f32_16x16x32_bf16 v[52:55], v[170:173], v[186:189], v[52:55]
	v_mfma_f32_16x16x32_bf16 v[48:51], v[178:181], v[186:189], v[48:51]
	v_mfma_f32_16x16x32_bf16 v[36:39], v[170:173], v[194:197], v[36:39]
	v_mfma_f32_16x16x32_bf16 v[32:35], v[178:181], v[194:197], v[32:35]
	v_mfma_f32_16x16x32_bf16 v[20:23], v[170:173], v[202:205], v[20:23]
	v_mfma_f32_16x16x32_bf16 v[16:19], v[178:181], v[202:205], v[16:19]
	v_mfma_f32_16x16x32_bf16 v[4:7], v[170:173], v[210:213], v[4:7]
	v_mfma_f32_16x16x32_bf16 v[0:3], v[178:181], v[210:213], v[0:3]
	s_setprio 0
	s_barrier
	s_add_u32 s20, s20, 0x100
	s_addc_u32 s21, s21, 0
	s_add_u32 s75, s75, 0x100
	s_addc_u32 s78, s78, 0
	s_cmp_ge_i32 s28, s53
	s_mov_b32 s22, s28
	s_cbranch_scc1 .Lkz_exit_2
.LBB0_769:
	ds_read_b128 v[150:153], v147
	ds_read_b128 v[154:157], v147 offset:1024
	ds_read_b128 v[158:161], v147 offset:2048
	ds_read_b128 v[162:165], v147 offset:3072
	ds_read_b128 v[166:169], v148
	ds_read_b128 v[170:173], v148 offset:1024
	ds_read_b128 v[174:177], v148 offset:2048
	ds_read_b128 v[178:181], v148 offset:3072
	s_add_i32 s28, s22, 2
	s_add_u32 s29, s20, 0x80
	s_addc_u32 s23, s21, 0
	s_cmp_eq_u32 s31, s22
	s_cselect_b32 s22, s2, s29
	s_cselect_b32 s23, s3, s23
	s_cselect_b32 s37, s19, s78
	s_cselect_b32 s36, s18, s75
	v_lshl_add_u64 v[214:215], s[20:21], 0, v[136:137]
	s_add_i32 m0, s41, 0xc000
	ds_read_b128 v[182:185], v149
	ds_read_b128 v[186:189], v149 offset:1024
	ds_read_b128 v[190:193], v149 offset:2048
	ds_read_b128 v[194:197], v149 offset:3072
	ds_read_b128 v[198:201], v149 offset:4096
	ds_read_b128 v[202:205], v149 offset:5120
	ds_read_b128 v[206:209], v149 offset:6144
	ds_read_b128 v[210:213], v149 offset:7168
	global_load_lds_dwordx4 v[214:215], off
	v_lshl_add_u64 v[214:215], s[20:21], 0, v[138:139]
	s_add_i32 m0, s41, 0xe000
	s_nop 0
	global_load_lds_dwordx4 v[214:215], off
	s_waitcnt vmcnt(8)
	s_waitcnt lgkmcnt(0)
	s_barrier
; #define PG8_STAGE(bufoff, gbase, voff) do { _Pragma("unroll") for (int _i = 0; _i < 2; ++_i) \
;         __builtin_amdgcn_global_load_lds((const unsigned*)((const char*)(gbase) + (voff)[_i]), (PG8_LAS unsigned*)(lds + (bufoff) + ldsw + _i * 8192), 16, 0, 0); } while (0)
; #define PG8_LDA(dst, b, h) do { _Pragma("unroll") for (int m = 0; m < 4; ++m) _Pragma("unroll") for (int k = 0; k < 2; ++k) dst[m][k] = *(const PG8_LAS bf16x8*)(lds + PG8_SA(b, h) + aoff + m * 2048 + k * 1024); } while (0)
; #define PG8_LDB(dst, b, h) do { _Pragma("unroll") for (int n = 0; n < 2; ++n) _Pragma("unroll") for (int k = 0; k < 2; ++k) dst[n][k] = *(const PG8_LAS bf16x8*)(lds + PG8_SB(b, h) + boff + n * 2048 + k * 1024); } while (0)
; #define PG8_MMA(ai, bj, At, Bt) do { __builtin_amdgcn_s_setprio(1); _Pragma("unroll") for (int m = 0; m < 4; ++m) _Pragma("unroll") for (int n = 0; n < 2; ++n) _Pragma("unroll") for (int k = 0; k < 2; ++k) \
;         acc[ai][bj][m][n] = __builtin_amdgcn_mfma_f32_16x16x32_bf16(Bt[n][k], At[m][k], acc[ai][bj][m][n], 0, 0, 0); __builtin_amdgcn_s_setprio(0); } while (0)
; #define PG8_WAIT_V(n) asm volatile("s_waitcnt vmcnt(" #n ")" ::: "memory")
; #define PG8_WAIT_L(n) asm volatile("s_waitcnt lgkmcnt(" #n ")" ::: "memory")
; #define PG8_BAR __builtin_amdgcn_s_barrier()
; #define PG8_SCHED __builtin_amdgcn_sched_barrier(0)
; template <class Epi, class Sched, bool ALIGN_EPI = false, bool SP2 = false>
; __device__ __forceinline__ void gemm_phase(PG8_LAS unsigned char* lds, const Gemm g, const Sched& S, const Epi& E, const int wave_in) {
;     ...
;             PG8_WAIT_V(8); PG8_WAIT_L(0); PG8_BAR; PG8_MMA(0, 0, At, B0); PG8_MMA(0, 1, At, B1); PG8_BAR; PG8_SCHED;
;             PG8_LDA(At, 0, 1); PG8_STAGE(PG8_SB(0, 0), b2, voffB); PG8_STAGE(PG8_SB(0, 1), b2 + hstep, voffB); PG8_STAGE(PG8_SA(0, 0), a2, voffA);
;             PG8_WAIT_V(8); PG8_WAIT_L(0); PG8_BAR; PG8_MMA(1, 0, At, B0); PG8_MMA(1, 1, At, B1); PG8_BAR; PG8_SCHED;
;             PG8_LDB(B0, 1, 0); PG8_LDB(B1, 1, 1); PG8_SCHED; PG8_LDA(At, 1, 0); PG8_STAGE(PG8_SA(0, 1), a2 + hstep, voffA);
;             PG8_WAIT_V(8); PG8_WAIT_L(0); PG8_BAR; PG8_MMA(0, 0, At, B0); PG8_MMA(0, 1, At, B1); PG8_BAR; PG8_SCHED;
	s_setprio 1
	s_waitcnt lgkmcnt(0)
	v_mfma_f32_16x16x32_bf16 v[120:123], v[150:153], v[182:185], v[120:123]
	v_mfma_f32_16x16x32_bf16 v[124:127], v[158:161], v[182:185], v[124:127]
	v_mfma_f32_16x16x32_bf16 v[108:111], v[150:153], v[190:193], v[108:111]
	v_mfma_f32_16x16x32_bf16 v[104:107], v[158:161], v[190:193], v[104:107]
	v_mfma_f32_16x16x32_bf16 v[92:95], v[150:153], v[198:201], v[92:95]
	v_mfma_f32_16x16x32_bf16 v[88:91], v[158:161], v[198:201], v[88:91]
	v_mfma_f32_16x16x32_bf16 v[76:79], v[150:153], v[206:209], v[76:79]
	v_mfma_f32_16x16x32_bf16 v[72:75], v[158:161], v[206:209], v[72:75]
	v_mfma_f32_16x16x32_bf16 v[120:123], v[154:157], v[186:189], v[120:123]
	v_mfma_f32_16x16x32_bf16 v[124:127], v[162:165], v[186:189], v[124:127]
	v_mfma_f32_16x16x32_bf16 v[108:111], v[154:157], v[194:197], v[108:111]
	v_mfma_f32_16x16x32_bf16 v[104:107], v[162:165], v[194:197], v[104:107]
	v_mfma_f32_16x16x32_bf16 v[92:95], v[154:157], v[202:205], v[92:95]
	v_mfma_f32_16x16x32_bf16 v[88:91], v[162:165], v[202:205], v[88:91]
	v_mfma_f32_16x16x32_bf16 v[76:79], v[154:157], v[210:213], v[76:79]
	v_mfma_f32_16x16x32_bf16 v[72:75], v[162:165], v[210:213], v[72:75]
	s_setprio 0
	s_setprio 1
	v_mfma_f32_16x16x32_bf16 v[116:119], v[166:169], v[182:185], v[116:119]
	v_mfma_f32_16x16x32_bf16 v[112:115], v[174:177], v[182:185], v[112:115]
	v_mfma_f32_16x16x32_bf16 v[100:103], v[166:169], v[190:193], v[100:103]
	v_mfma_f32_16x16x32_bf16 v[96:99], v[174:177], v[190:193], v[96:99]
	v_mfma_f32_16x16x32_bf16 v[84:87], v[166:169], v[198:201], v[84:87]
	v_mfma_f32_16x16x32_bf16 v[80:83], v[174:177], v[198:201], v[80:83]
	v_mfma_f32_16x16x32_bf16 v[68:71], v[166:169], v[206:209], v[68:71]
	v_mfma_f32_16x16x32_bf16 v[64:67], v[174:177], v[206:209], v[64:67]
	v_mfma_f32_16x16x32_bf16 v[116:119], v[170:173], v[186:189], v[116:119]
	v_mfma_f32_16x16x32_bf16 v[112:115], v[178:181], v[186:189], v[112:115]
	v_mfma_f32_16x16x32_bf16 v[100:103], v[170:173], v[194:197], v[100:103]
	v_mfma_f32_16x16x32_bf16 v[96:99], v[178:181], v[194:197], v[96:99]
	v_mfma_f32_16x16x32_bf16 v[84:87], v[170:173], v[202:205], v[84:87]
	v_mfma_f32_16x16x32_bf16 v[80:83], v[178:181], v[202:205], v[80:83]
	v_mfma_f32_16x16x32_bf16 v[68:71], v[170:173], v[210:213], v[68:71]
	v_mfma_f32_16x16x32_bf16 v[64:67], v[178:181], v[210:213], v[64:67]
	s_setprio 0
	s_barrier
	s_add_i32 s29, s34, s30
	v_lshl_add_u64 v[214:215], s[36:37], 0, v[130:131]
	s_mov_b32 m0, s29
	ds_read_b128 v[182:185], v149 offset:16384
	ds_read_b128 v[186:189], v149 offset:17408
	ds_read_b128 v[190:193], v149 offset:18432
	ds_read_b128 v[194:197], v149 offset:19456
	ds_read_b128 v[198:201], v149 offset:20480
	ds_read_b128 v[202:205], v149 offset:21504
	ds_read_b128 v[206:209], v149 offset:22528
	ds_read_b128 v[210:213], v149 offset:23552
	global_load_lds_dwordx4 v[214:215], off
	s_add_i32 m0, s29, 0x2000
	v_lshl_add_u64 v[216:217], s[36:37], 0, v[134:135]
	s_add_u32 s36, s36, s4
	s_addc_u32 s37, s37, s5
	s_add_i32 s29, s69, s30
	global_load_lds_dwordx4 v[216:217], off
	v_lshl_add_u64 v[218:219], s[36:37], 0, v[130:131]
	s_mov_b32 m0, s29
	v_lshl_add_u64 v[220:221], s[36:37], 0, v[134:135]
	global_load_lds_dwordx4 v[218:219], off
	s_add_i32 m0, s29, 0x2000
	v_lshl_add_u64 v[222:223], s[22:23], 0, v[128:129]
	global_load_lds_dwordx4 v[220:221], off
	s_mov_b32 m0, s41
	v_lshl_add_u64 v[224:225], s[22:23], 0, v[132:133]
	global_load_lds_dwordx4 v[222:223], off
	s_mov_b32 m0, s46
	s_nop 0
	global_load_lds_dwordx4 v[224:225], off
	s_waitcnt vmcnt(8)
	s_waitcnt lgkmcnt(0)
	s_barrier
	s_setprio 1
	s_waitcnt lgkmcnt(0)
	v_mfma_f32_16x16x32_bf16 v[60:63], v[150:153], v[182:185], v[60:63]
	v_mfma_f32_16x16x32_bf16 v[56:59], v[158:161], v[182:185], v[56:59]
	v_mfma_f32_16x16x32_bf16 v[44:47], v[150:153], v[190:193], v[44:47]
	v_mfma_f32_16x16x32_bf16 v[40:43], v[158:161], v[190:193], v[40:43]
	v_mfma_f32_16x16x32_bf16 v[28:31], v[150:153], v[198:201], v[28:31]
	v_mfma_f32_16x16x32_bf16 v[24:27], v[158:161], v[198:201], v[24:27]
	v_mfma_f32_16x16x32_bf16 v[12:15], v[150:153], v[206:209], v[12:15]
	v_mfma_f32_16x16x32_bf16 v[8:11], v[158:161], v[206:209], v[8:11]
	v_mfma_f32_16x16x32_bf16 v[60:63], v[154:157], v[186:189], v[60:63]
	v_mfma_f32_16x16x32_bf16 v[56:59], v[162:165], v[186:189], v[56:59]
	v_mfma_f32_16x16x32_bf16 v[44:47], v[154:157], v[194:197], v[44:47]
	v_mfma_f32_16x16x32_bf16 v[40:43], v[162:165], v[194:197], v[40:43]
	v_mfma_f32_16x16x32_bf16 v[28:31], v[154:157], v[202:205], v[28:31]
	v_mfma_f32_16x16x32_bf16 v[24:27], v[162:165], v[202:205], v[24:27]
	v_mfma_f32_16x16x32_bf16 v[12:15], v[154:157], v[210:213], v[12:15]
	v_mfma_f32_16x16x32_bf16 v[8:11], v[162:165], v[210:213], v[8:11]
	s_setprio 0
	s_setprio 1
	v_mfma_f32_16x16x32_bf16 v[52:55], v[166:169], v[182:185], v[52:55]
	v_mfma_f32_16x16x32_bf16 v[48:51], v[174:177], v[182:185], v[48:51]
	v_mfma_f32_16x16x32_bf16 v[36:39], v[166:169], v[190:193], v[36:39]
	v_mfma_f32_16x16x32_bf16 v[32:35], v[174:177], v[190:193], v[32:35]
	v_mfma_f32_16x16x32_bf16 v[20:23], v[166:169], v[198:201], v[20:23]
	v_mfma_f32_16x16x32_bf16 v[16:19], v[174:177], v[198:201], v[16:19]
	v_mfma_f32_16x16x32_bf16 v[4:7], v[166:169], v[206:209], v[4:7]
	v_mfma_f32_16x16x32_bf16 v[0:3], v[174:177], v[206:209], v[0:3]
	v_mfma_f32_16x16x32_bf16 v[52:55], v[170:173], v[186:189], v[52:55]
	v_mfma_f32_16x16x32_bf16 v[48:51], v[178:181], v[186:189], v[48:51]
	v_mfma_f32_16x16x32_bf16 v[36:39], v[170:173], v[194:197], v[36:39]
	v_mfma_f32_16x16x32_bf16 v[32:35], v[178:181], v[194:197], v[32:35]
	v_mfma_f32_16x16x32_bf16 v[20:23], v[170:173], v[202:205], v[20:23]
	v_mfma_f32_16x16x32_bf16 v[16:19], v[178:181], v[202:205], v[16:19]
	v_mfma_f32_16x16x32_bf16 v[4:7], v[170:173], v[210:213], v[4:7]
	v_mfma_f32_16x16x32_bf16 v[0:3], v[178:181], v[210:213], v[0:3]
	s_setprio 0
	s_barrier
; #define PG8_STAGE(bufoff, gbase, voff) do { _Pragma("unroll") for (int _i = 0; _i < 2; ++_i) \
;         __builtin_amdgcn_global_load_lds((const unsigned*)((const char*)(gbase) + (voff)[_i]), (PG8_LAS unsigned*)(lds + (bufoff) + ldsw + _i * 8192), 16, 0, 0); } while (0)
; #define PG8_LDA(dst, b, h) do { _Pragma("unroll") for (int m = 0; m < 4; ++m) _Pragma("unroll") for (int k = 0; k < 2; ++k) dst[m][k] = *(const PG8_LAS bf16x8*)(lds + PG8_SA(b, h) + aoff + m * 2048 + k * 1024); } while (0)
; #define PG8_LDB(dst, b, h) do { _Pragma("unroll") for (int n = 0; n < 2; ++n) _Pragma("unroll") for (int k = 0; k < 2; ++k) dst[n][k] = *(const PG8_LAS bf16x8*)(lds + PG8_SB(b, h) + boff + n * 2048 + k * 1024); } while (0)
; #define PG8_MMA(ai, bj, At, Bt) do { __builtin_amdgcn_s_setprio(1); _Pragma("unroll") for (int m = 0; m < 4; ++m) _Pragma("unroll") for (int n = 0; n < 2; ++n) _Pragma("unroll") for (int k = 0; k < 2; ++k) \
;         acc[ai][bj][m][n] = __builtin_amdgcn_mfma_f32_16x16x32_bf16(Bt[n][k], At[m][k], acc[ai][bj][m][n], 0, 0, 0); __builtin_amdgcn_s_setprio(0); } while (0)
; #define PG8_WAIT_V(n) asm volatile("s_waitcnt vmcnt(" #n ")" ::: "memory")
; #define PG8_WAIT_L(n) asm volatile("s_waitcnt lgkmcnt(" #n ")" ::: "memory")
; #define PG8_BAR __builtin_amdgcn_s_barrier()
; #define PG8_SCHED __builtin_amdgcn_sched_barrier(0)
; template <class Epi, class Sched, bool ALIGN_EPI = false, bool SP2 = false>
; __device__ __forceinline__ void gemm_phase(PG8_LAS unsigned char* lds, const Gemm g, const Sched& S, const Epi& E, const int wave_in) {
;     ...
;             PG8_LDB(B0, 1, 0); PG8_LDB(B1, 1, 1); PG8_SCHED; PG8_LDA(At, 1, 0); PG8_STAGE(PG8_SA(0, 1), a2 + hstep, voffA);
;             PG8_WAIT_V(8); PG8_WAIT_L(0); PG8_BAR; PG8_MMA(0, 0, At, B0); PG8_MMA(0, 1, At, B1); PG8_BAR; PG8_SCHED;
;             PG8_LDA(At, 1, 1); PG8_STAGE(PG8_SB(1, 0), b3, voffB); PG8_STAGE(PG8_SB(1, 1), b3 + hstep, voffB); PG8_STAGE(PG8_SA(1, 0), a3, voffA);
	s_add_i32 s29, 0, 0x18000
	s_add_i32 s36, 0, 0x1c000
	v_add_u32_e32 v162, s29, v145
	v_add_u32_e32 v178, s36, v145
	ds_read_b128 v[150:153], v162
	ds_read_b128 v[154:157], v162 offset:1024
	ds_read_b128 v[158:161], v162 offset:2048
	ds_read_b128 v[162:165], v162 offset:3072
	ds_read_b128 v[166:169], v178
	ds_read_b128 v[170:173], v178 offset:1024
	ds_read_b128 v[174:177], v178 offset:2048
	ds_read_b128 v[178:181], v178 offset:3072
	s_add_u32 s22, s22, s4
	s_addc_u32 s23, s23, s5
	s_mov_b32 m0, s47
	v_lshl_add_u64 v[226:227], s[22:23], 0, v[128:129]
	ds_read_b128 v[182:185], v149 offset:32768
	ds_read_b128 v[186:189], v149 offset:33792
	ds_read_b128 v[190:193], v149 offset:34816
	ds_read_b128 v[194:197], v149 offset:35840
	ds_read_b128 v[198:201], v149 offset:36864
	ds_read_b128 v[202:205], v149 offset:37888
	ds_read_b128 v[206:209], v149 offset:38912
	ds_read_b128 v[210:213], v149 offset:39936
	global_load_lds_dwordx4 v[226:227], off
	v_lshl_add_u64 v[226:227], s[22:23], 0, v[132:133]
	s_mov_b32 m0, s50
	s_nop 0
	global_load_lds_dwordx4 v[226:227], off
	s_waitcnt vmcnt(8)
	s_waitcnt lgkmcnt(0)
	s_barrier
	s_setprio 1
	s_waitcnt lgkmcnt(0)
	v_mfma_f32_16x16x32_bf16 v[120:123], v[150:153], v[182:185], v[120:123]
	v_mfma_f32_16x16x32_bf16 v[124:127], v[158:161], v[182:185], v[124:127]
	v_mfma_f32_16x16x32_bf16 v[108:111], v[150:153], v[190:193], v[108:111]
	v_mfma_f32_16x16x32_bf16 v[104:107], v[158:161], v[190:193], v[104:107]
	v_mfma_f32_16x16x32_bf16 v[92:95], v[150:153], v[198:201], v[92:95]
	v_mfma_f32_16x16x32_bf16 v[88:91], v[158:161], v[198:201], v[88:91]
	v_mfma_f32_16x16x32_bf16 v[76:79], v[150:153], v[206:209], v[76:79]
	v_mfma_f32_16x16x32_bf16 v[72:75], v[158:161], v[206:209], v[72:75]
	v_mfma_f32_16x16x32_bf16 v[120:123], v[154:157], v[186:189], v[120:123]
	v_mfma_f32_16x16x32_bf16 v[124:127], v[162:165], v[186:189], v[124:127]
	v_mfma_f32_16x16x32_bf16 v[108:111], v[154:157], v[194:197], v[108:111]
	v_mfma_f32_16x16x32_bf16 v[104:107], v[162:165], v[194:197], v[104:107]
	v_mfma_f32_16x16x32_bf16 v[92:95], v[154:157], v[202:205], v[92:95]
	v_mfma_f32_16x16x32_bf16 v[88:91], v[162:165], v[202:205], v[88:91]
	v_mfma_f32_16x16x32_bf16 v[76:79], v[154:157], v[210:213], v[76:79]
	v_mfma_f32_16x16x32_bf16 v[72:75], v[162:165], v[210:213], v[72:75]
	s_setprio 0
	s_setprio 1
	v_mfma_f32_16x16x32_bf16 v[116:119], v[166:169], v[182:185], v[116:119]
	v_mfma_f32_16x16x32_bf16 v[112:115], v[174:177], v[182:185], v[112:115]
	v_mfma_f32_16x16x32_bf16 v[100:103], v[166:169], v[190:193], v[100:103]
	v_mfma_f32_16x16x32_bf16 v[96:99], v[174:177], v[190:193], v[96:99]
	v_mfma_f32_16x16x32_bf16 v[84:87], v[166:169], v[198:201], v[84:87]
	v_mfma_f32_16x16x32_bf16 v[80:83], v[174:177], v[198:201], v[80:83]
	v_mfma_f32_16x16x32_bf16 v[68:71], v[166:169], v[206:209], v[68:71]
	v_mfma_f32_16x16x32_bf16 v[64:67], v[174:177], v[206:209], v[64:67]
	v_mfma_f32_16x16x32_bf16 v[116:119], v[170:173], v[186:189], v[116:119]
	v_mfma_f32_16x16x32_bf16 v[112:115], v[178:181], v[186:189], v[112:115]
	v_mfma_f32_16x16x32_bf16 v[100:103], v[170:173], v[194:197], v[100:103]
	v_mfma_f32_16x16x32_bf16 v[96:99], v[178:181], v[194:197], v[96:99]
	v_mfma_f32_16x16x32_bf16 v[84:87], v[170:173], v[202:205], v[84:87]
	v_mfma_f32_16x16x32_bf16 v[80:83], v[178:181], v[202:205], v[80:83]
	v_mfma_f32_16x16x32_bf16 v[68:71], v[170:173], v[210:213], v[68:71]
	v_mfma_f32_16x16x32_bf16 v[64:67], v[178:181], v[210:213], v[64:67]
	s_setprio 0
	s_barrier
	s_add_i32 s22, s29, s30
	v_lshl_add_u64 v[214:215], v[214:215], 0, s[12:13]
	s_mov_b32 m0, s22
	ds_read_b128 v[182:185], v149 offset:49152
	ds_read_b128 v[186:189], v149 offset:50176
	ds_read_b128 v[190:193], v149 offset:51200
	ds_read_b128 v[194:197], v149 offset:52224
	ds_read_b128 v[198:201], v149 offset:53248
	ds_read_b128 v[202:205], v149 offset:54272
	ds_read_b128 v[206:209], v149 offset:55296
	ds_read_b128 v[210:213], v149 offset:56320
	global_load_lds_dwordx4 v[214:215], off
	v_lshl_add_u64 v[214:215], v[216:217], 0, s[12:13]
	s_add_i32 m0, s22, 0x2000
	s_add_i32 s22, s36, s30
	global_load_lds_dwordx4 v[214:215], off
	v_lshl_add_u64 v[214:215], v[218:219], 0, s[12:13]
	s_mov_b32 m0, s22
	s_nop 0
	global_load_lds_dwordx4 v[214:215], off
	v_lshl_add_u64 v[214:215], v[220:221], 0, s[12:13]
	s_add_i32 m0, s22, 0x2000
	s_nop 0
	global_load_lds_dwordx4 v[214:215], off
	v_lshl_add_u64 v[214:215], v[222:223], 0, s[12:13]
	s_mov_b32 m0, s35
	s_nop 0
	global_load_lds_dwordx4 v[214:215], off
	v_lshl_add_u64 v[214:215], v[224:225], 0, s[12:13]
	s_mov_b32 m0, s52
	s_nop 0
	global_load_lds_dwordx4 v[214:215], off
	s_waitcnt vmcnt(8)
	s_waitcnt lgkmcnt(0)
	s_barrier
; #define PG8_STAGE(bufoff, gbase, voff) do { _Pragma("unroll") for (int _i = 0; _i < 2; ++_i) \
;         __builtin_amdgcn_global_load_lds((const unsigned*)((const char*)(gbase) + (voff)[_i]), (PG8_LAS unsigned*)(lds + (bufoff) + ldsw + _i * 8192), 16, 0, 0); } while (0)
; #define PG8_LDA(dst, b, h) do { _Pragma("unroll") for (int m = 0; m < 4; ++m) _Pragma("unroll") for (int k = 0; k < 2; ++k) dst[m][k] = *(const PG8_LAS bf16x8*)(lds + PG8_SA(b, h) + aoff + m * 2048 + k * 1024); } while (0)
; #define PG8_LDB(dst, b, h) do { _Pragma("unroll") for (int n = 0; n < 2; ++n) _Pragma("unroll") for (int k = 0; k < 2; ++k) dst[n][k] = *(const PG8_LAS bf16x8*)(lds + PG8_SB(b, h) + boff + n * 2048 + k * 1024); } while (0)
; #define PG8_MMA(ai, bj, At, Bt) do { __builtin_amdgcn_s_setprio(1); _Pragma("unroll") for (int m = 0; m < 4; ++m) _Pragma("unroll") for (int n = 0; n < 2; ++n) _Pragma("unroll") for (int k = 0; k < 2; ++k) \
;         acc[ai][bj][m][n] = __builtin_amdgcn_mfma_f32_16x16x32_bf16(Bt[n][k], At[m][k], acc[ai][bj][m][n], 0, 0, 0); __builtin_amdgcn_s_setprio(0); } while (0)
; #define PG8_WAIT_V(n) asm volatile("s_waitcnt vmcnt(" #n ")" ::: "memory")
; #define PG8_WAIT_L(n) asm volatile("s_waitcnt lgkmcnt(" #n ")" ::: "memory")
; template <class Epi, class Sched, bool ALIGN_EPI = false, bool SP2 = false>
; __device__ __forceinline__ void gemm_phase(PG8_LAS unsigned char* lds, const Gemm g, const Sched& S, const Epi& E, const int wave_in) {
;     ...
; #pragma unroll
;     for (int a = 0; a < 2; ++a)
; #pragma unroll
;         for (int b = 0; b < 2; ++b)
; #pragma unroll
;             for (int m = 0; m < 4; ++m)
; #pragma unroll
;                 for (int n = 0; n < 2; ++n) acc[a][b][m][n] = (f32x4){0.f, 0.f, 0.f, 0.f};
;     ...
;             PG8_WAIT_V(8); PG8_WAIT_L(0); PG8_BAR; PG8_MMA(1, 0, At, B0); PG8_MMA(1, 1, At, B1); PG8_BAR; PG8_SCHED;
;             PG8_LDB(B0, 1, 0); PG8_LDB(B1, 1, 1); PG8_SCHED; PG8_LDA(At, 1, 0); PG8_STAGE(PG8_SA(0, 1), a2 + hstep, voffA);
;             PG8_WAIT_V(8); PG8_WAIT_L(0); PG8_BAR; PG8_MMA(0, 0, At, B0); PG8_MMA(0, 1, At, B1); PG8_BAR; PG8_SCHED;
;             PG8_LDA(At, 1, 1); PG8_STAGE(PG8_SB(1, 0), b3, voffB); PG8_STAGE(PG8_SB(1, 1), b3 + hstep, voffB); PG8_STAGE(PG8_SA(1, 0), a3, voffA);
;             PG8_WAIT_V(8); PG8_WAIT_L(0); PG8_BAR; PG8_MMA(1, 0, At, B0); PG8_MMA(1, 1, At, B1); PG8_BAR; PG8_SCHED;
	s_setprio 1
	s_waitcnt lgkmcnt(0)
	v_mfma_f32_16x16x32_bf16 v[60:63], v[150:153], v[182:185], v[60:63]
	v_mfma_f32_16x16x32_bf16 v[56:59], v[158:161], v[182:185], v[56:59]
	v_mfma_f32_16x16x32_bf16 v[44:47], v[150:153], v[190:193], v[44:47]
	v_mfma_f32_16x16x32_bf16 v[40:43], v[158:161], v[190:193], v[40:43]
	v_mfma_f32_16x16x32_bf16 v[28:31], v[150:153], v[198:201], v[28:31]
	v_mfma_f32_16x16x32_bf16 v[24:27], v[158:161], v[198:201], v[24:27]
	v_mfma_f32_16x16x32_bf16 v[12:15], v[150:153], v[206:209], v[12:15]
	v_mfma_f32_16x16x32_bf16 v[8:11], v[158:161], v[206:209], v[8:11]
	v_mfma_f32_16x16x32_bf16 v[60:63], v[154:157], v[186:189], v[60:63]
	v_mfma_f32_16x16x32_bf16 v[56:59], v[162:165], v[186:189], v[56:59]
	v_mfma_f32_16x16x32_bf16 v[44:47], v[154:157], v[194:197], v[44:47]
	v_mfma_f32_16x16x32_bf16 v[40:43], v[162:165], v[194:197], v[40:43]
	v_mfma_f32_16x16x32_bf16 v[28:31], v[154:157], v[202:205], v[28:31]
	v_mfma_f32_16x16x32_bf16 v[24:27], v[162:165], v[202:205], v[24:27]
	v_mfma_f32_16x16x32_bf16 v[12:15], v[154:157], v[210:213], v[12:15]
	v_mfma_f32_16x16x32_bf16 v[8:11], v[162:165], v[210:213], v[8:11]
	s_setprio 0
	s_setprio 1
	v_mfma_f32_16x16x32_bf16 v[52:55], v[166:169], v[182:185], v[52:55]
	v_mfma_f32_16x16x32_bf16 v[48:51], v[174:177], v[182:185], v[48:51]
	v_mfma_f32_16x16x32_bf16 v[36:39], v[166:169], v[190:193], v[36:39]
	v_mfma_f32_16x16x32_bf16 v[32:35], v[174:177], v[190:193], v[32:35]
	v_mfma_f32_16x16x32_bf16 v[20:23], v[166:169], v[198:201], v[20:23]
	v_mfma_f32_16x16x32_bf16 v[16:19], v[174:177], v[198:201], v[16:19]
	v_mfma_f32_16x16x32_bf16 v[4:7], v[166:169], v[206:209], v[4:7]
	v_mfma_f32_16x16x32_bf16 v[0:3], v[174:177], v[206:209], v[0:3]
	v_mfma_f32_16x16x32_bf16 v[52:55], v[170:173], v[186:189], v[52:55]
	v_mfma_f32_16x16x32_bf16 v[48:51], v[178:181], v[186:189], v[48:51]
	v_mfma_f32_16x16x32_bf16 v[36:39], v[170:173], v[194:197], v[36:39]
	v_mfma_f32_16x16x32_bf16 v[32:35], v[178:181], v[194:197], v[32:35]
	v_mfma_f32_16x16x32_bf16 v[20:23], v[170:173], v[202:205], v[20:23]
	v_mfma_f32_16x16x32_bf16 v[16:19], v[178:181], v[202:205], v[16:19]
	v_mfma_f32_16x16x32_bf16 v[4:7], v[170:173], v[210:213], v[4:7]
	v_mfma_f32_16x16x32_bf16 v[0:3], v[178:181], v[210:213], v[0:3]
	s_setprio 0
	s_barrier
	s_add_u32 s20, s20, 0x100
	s_addc_u32 s21, s21, 0
	s_add_u32 s75, s75, 0x100
	s_addc_u32 s78, s78, 0
	s_cmp_ge_i32 s28, s53
	s_mov_b32 s22, s28
	s_cbranch_scc0 .LBB0_769
.Lkz_exit_2:
	s_branch .LBB0_770
.Lkz_skip_2:
	v_mov_b32_e32 v123, 0
	v_mov_b32_e32 v122, v123
	v_mov_b32_e32 v121, v123
	v_mov_b32_e32 v120, v123
	v_mov_b32_e32 v127, v123
	v_mov_b32_e32 v126, v123
	v_mov_b32_e32 v125, v123
	v_mov_b32_e32 v124, v123
	v_mov_b32_e32 v111, v123
	v_mov_b32_e32 v110, v123
	v_mov_b32_e32 v109, v123
	v_mov_b32_e32 v108, v123
	v_mov_b32_e32 v107, v123
	v_mov_b32_e32 v106, v123
	v_mov_b32_e32 v105, v123
	v_mov_b32_e32 v104, v123
	v_mov_b32_e32 v95, v123
	v_mov_b32_e32 v94, v123
	v_mov_b32_e32 v93, v123
	v_mov_b32_e32 v92, v123
	v_mov_b32_e32 v91, v123
	v_mov_b32_e32 v90, v123
	v_mov_b32_e32 v89, v123
	v_mov_b32_e32 v88, v123
	v_mov_b32_e32 v79, v123
	v_mov_b32_e32 v78, v123
	v_mov_b32_e32 v77, v123
	v_mov_b32_e32 v76, v123
	v_mov_b32_e32 v75, v123
	v_mov_b32_e32 v74, v123
	v_mov_b32_e32 v73, v123
	v_mov_b32_e32 v72, v123
	v_mov_b32_e32 v119, v123
	v_mov_b32_e32 v118, v123
	v_mov_b32_e32 v117, v123
	v_mov_b32_e32 v116, v123
	v_mov_b32_e32 v115, v123
	v_mov_b32_e32 v114, v123
	v_mov_b32_e32 v113, v123
	v_mov_b32_e32 v112, v123
	v_mov_b32_e32 v103, v123
	v_mov_b32_e32 v102, v123
	v_mov_b32_e32 v101, v123
	v_mov_b32_e32 v100, v123
	v_mov_b32_e32 v99, v123
	v_mov_b32_e32 v98, v123
	v_mov_b32_e32 v97, v123
	v_mov_b32_e32 v96, v123
	v_mov_b32_e32 v87, v123
	v_mov_b32_e32 v86, v123
	v_mov_b32_e32 v85, v123
	v_mov_b32_e32 v84, v123
	v_mov_b32_e32 v83, v123
	v_mov_b32_e32 v82, v123
	v_mov_b32_e32 v81, v123
	v_mov_b32_e32 v80, v123
	v_mov_b32_e32 v71, v123
	v_mov_b32_e32 v70, v123
	v_mov_b32_e32 v69, v123
	v_mov_b32_e32 v68, v123
	v_mov_b32_e32 v67, v123
	v_mov_b32_e32 v66, v123
	v_mov_b32_e32 v65, v123
	v_mov_b32_e32 v64, v123
	v_mov_b32_e32 v63, v123
	v_mov_b32_e32 v62, v123
	v_mov_b32_e32 v61, v123
	v_mov_b32_e32 v60, v123
	v_mov_b32_e32 v59, v123
	v_mov_b32_e32 v58, v123
	v_mov_b32_e32 v57, v123
	v_mov_b32_e32 v56, v123
	v_mov_b32_e32 v47, v123
	v_mov_b32_e32 v46, v123
	v_mov_b32_e32 v45, v123
	v_mov_b32_e32 v44, v123
	v_mov_b32_e32 v43, v123
	v_mov_b32_e32 v42, v123
	v_mov_b32_e32 v41, v123
	v_mov_b32_e32 v40, v123
	v_mov_b32_e32 v31, v123
	v_mov_b32_e32 v30, v123
	v_mov_b32_e32 v29, v123
	v_mov_b32_e32 v28, v123
	v_mov_b32_e32 v27, v123
	v_mov_b32_e32 v26, v123
	v_mov_b32_e32 v25, v123
	v_mov_b32_e32 v24, v123
	v_mov_b32_e32 v15, v123
	v_mov_b32_e32 v14, v123
	v_mov_b32_e32 v13, v123
	v_mov_b32_e32 v12, v123
	v_mov_b32_e32 v11, v123
	v_mov_b32_e32 v10, v123
	v_mov_b32_e32 v9, v123
	v_mov_b32_e32 v8, v123
	v_mov_b32_e32 v55, v123
	v_mov_b32_e32 v54, v123
	v_mov_b32_e32 v53, v123
	v_mov_b32_e32 v52, v123
	v_mov_b32_e32 v51, v123
	v_mov_b32_e32 v50, v123
	v_mov_b32_e32 v49, v123
	v_mov_b32_e32 v48, v123
	v_mov_b32_e32 v39, v123
	v_mov_b32_e32 v38, v123
	v_mov_b32_e32 v37, v123
	v_mov_b32_e32 v36, v123
	v_mov_b32_e32 v35, v123
	v_mov_b32_e32 v34, v123
	v_mov_b32_e32 v33, v123
	v_mov_b32_e32 v32, v123
	v_mov_b32_e32 v23, v123
	v_mov_b32_e32 v22, v123
	v_mov_b32_e32 v21, v123
	v_mov_b32_e32 v20, v123
	v_mov_b32_e32 v19, v123
	v_mov_b32_e32 v18, v123
	v_mov_b32_e32 v17, v123
	v_mov_b32_e32 v16, v123
	v_mov_b32_e32 v7, v123
	v_mov_b32_e32 v6, v123
	v_mov_b32_e32 v5, v123
	v_mov_b32_e32 v4, v123
	v_mov_b32_e32 v3, v123
	v_mov_b32_e32 v2, v123
	v_mov_b32_e32 v1, v123
	v_mov_b32_e32 v0, v123

; #define PG8_STAGE(bufoff, gbase, voff) do { _Pragma("unroll") for (int _i = 0; _i < 2; ++_i) \
;         __builtin_amdgcn_global_load_lds((const unsigned*)((const char*)(gbase) + (voff)[_i]), (PG8_LAS unsigned*)(lds + (bufoff) + ldsw + _i * 8192), 16, 0, 0); } while (0)
; #define PG8_LDA(dst, b, h) do { _Pragma("unroll") for (int m = 0; m < 4; ++m) _Pragma("unroll") for (int k = 0; k < 2; ++k) dst[m][k] = *(const PG8_LAS bf16x8*)(lds + PG8_SA(b, h) + aoff + m * 2048 + k * 1024); } while (0)
; #define PG8_LDB(dst, b, h) do { _Pragma("unroll") for (int n = 0; n < 2; ++n) _Pragma("unroll") for (int k = 0; k < 2; ++k) dst[n][k] = *(const PG8_LAS bf16x8*)(lds + PG8_SB(b, h) + boff + n * 2048 + k * 1024); } while (0)
; #define PG8_MMA(ai, bj, At, Bt) do { __builtin_amdgcn_s_setprio(1); _Pragma("unroll") for (int m = 0; m < 4; ++m) _Pragma("unroll") for (int n = 0; n < 2; ++n) _Pragma("unroll") for (int k = 0; k < 2; ++k) \
;         acc[ai][bj][m][n] = __builtin_amdgcn_mfma_f32_16x16x32_bf16(Bt[n][k], At[m][k], acc[ai][bj][m][n], 0, 0, 0); __builtin_amdgcn_s_setprio(0); } while (0)
; template <class Epi, class Sched, bool ALIGN_EPI = false, bool SP2 = false>
; __device__ __forceinline__ void gemm_phase(PG8_LAS unsigned char* lds, const Gemm g, const Sched& S, const Epi& E, const int wave_in) {
;     ...
;         const bool has_next = S.next(ui + 1, nxt);
;         const char* nA = has_next ? (const char*)g.A + (size_t)nxt.pm * tstep : cA; const char* nB = has_next ? (const char*)g.Bt + (size_t)nxt.pn * tstep : cB;
;         for (int t = 0; t < nt; t += 2) {
;             const bool last = (t == nt - 2);
;             const char* a1 = cA + (size_t)(t + 1) * kstep;
;             const char* a2 = last ? nA : cA + (size_t)(t + 2) * kstep; const char* b2 = last ? nB : cB + (size_t)(t + 2) * kstep;
;             const char* a3 = a2 + kstep; const char* b3 = b2 + kstep;
;             if (last && has_next) S.a_ready(nxt);
;             if constexpr (SP2) {
;             PG8_LDB(B0, 0, 0); PG8_LDB(B1, 0, 1); PG8_SCHED; PG8_LDA(At, 0, 0); PG8_STAGE(PG8_SA(1, 1), a1 + hstep, voffA);
;             PG8_WAIT_V(8); PG8_WAIT_L(0); PG8_BAR; PG8_MMA(0, 0, At, B0); PG8_MMA(0, 1, At, B1); PG8_BAR; PG8_SCHED;
;             PG8_LDA(At, 0, 1); PG8_STAGE(PG8_SB(0, 0), b2, voffB); PG8_STAGE(PG8_SB(0, 1), b2 + hstep, voffB); PG8_STAGE(PG8_SA(0, 0), a2, voffA);
.LBB0_1263:
	s_andn2_b64 vcc, exec, s[24:25]
	s_waitcnt vmcnt(0)
	s_waitcnt vmcnt(0)
	s_waitcnt lgkmcnt(0)
	s_cbranch_vccnz .Lkz_skip_3
	s_add_u32 s40, s40, 0x80
	s_addc_u32 s41, s41, 0
	s_add_u32 s64, s46, 0x100
	s_addc_u32 s65, s47, 0
	s_mov_b32 s28, 0
	ds_read_b128 v[144:147], v151
	ds_read_b128 v[156:159], v151 offset:1024
	ds_read_b128 v[160:163], v151 offset:2048
	ds_read_b128 v[164:167], v151 offset:3072
	ds_read_b128 v[168:171], v152
	ds_read_b128 v[172:175], v152 offset:1024
	ds_read_b128 v[176:179], v152 offset:2048
	ds_read_b128 v[180:183], v152 offset:3072
	s_add_i32 s29, s28, 2
	s_add_u32 s42, s40, 0x80
	s_addc_u32 s43, s41, 0
	s_cmp_eq_u32 s53, s28
	s_cselect_b32 s47, s5, s43
	s_cselect_b32 s46, s4, s42
	s_cselect_b32 s43, s39, s65
	s_cselect_b32 s42, s38, s64
	v_lshl_add_u64 v[216:217], s[40:41], 0, v[136:137]
	s_add_i32 m0, s31, 0xc000
	ds_read_b128 v[184:187], v153
	ds_read_b128 v[188:191], v153 offset:1024
	ds_read_b128 v[192:195], v153 offset:2048
	ds_read_b128 v[196:199], v153 offset:3072
	ds_read_b128 v[200:203], v153 offset:4096
	ds_read_b128 v[204:207], v153 offset:5120
	ds_read_b128 v[208:211], v153 offset:6144
	ds_read_b128 v[212:215], v153 offset:7168
	global_load_lds_dwordx4 v[216:217], off
	v_lshl_add_u64 v[216:217], s[40:41], 0, v[138:139]
	s_add_i32 m0, s31, 0xe000
	s_nop 0
	global_load_lds_dwordx4 v[216:217], off
	s_waitcnt vmcnt(8)
	s_waitcnt lgkmcnt(0)
	s_barrier
	s_setprio 1
	s_waitcnt lgkmcnt(0)
	v_mfma_f32_16x16x32_bf16 v[120:123], v[144:147], v[184:187], 0
	v_mfma_f32_16x16x32_bf16 v[124:127], v[160:163], v[184:187], 0
	v_mfma_f32_16x16x32_bf16 v[108:111], v[144:147], v[192:195], 0
	v_mfma_f32_16x16x32_bf16 v[104:107], v[160:163], v[192:195], 0
	v_mfma_f32_16x16x32_bf16 v[92:95], v[144:147], v[200:203], 0
	v_mfma_f32_16x16x32_bf16 v[88:91], v[160:163], v[200:203], 0
	v_mfma_f32_16x16x32_bf16 v[76:79], v[144:147], v[208:211], 0
	v_mfma_f32_16x16x32_bf16 v[72:75], v[160:163], v[208:211], 0
	v_mfma_f32_16x16x32_bf16 v[120:123], v[156:159], v[188:191], v[120:123]
	v_mfma_f32_16x16x32_bf16 v[124:127], v[164:167], v[188:191], v[124:127]
	v_mfma_f32_16x16x32_bf16 v[108:111], v[156:159], v[196:199], v[108:111]
	v_mfma_f32_16x16x32_bf16 v[104:107], v[164:167], v[196:199], v[104:107]
	v_mfma_f32_16x16x32_bf16 v[92:95], v[156:159], v[204:207], v[92:95]
	v_mfma_f32_16x16x32_bf16 v[88:91], v[164:167], v[204:207], v[88:91]
	v_mfma_f32_16x16x32_bf16 v[76:79], v[156:159], v[212:215], v[76:79]
	v_mfma_f32_16x16x32_bf16 v[72:75], v[164:167], v[212:215], v[72:75]
	s_setprio 0
	s_setprio 1
	v_mfma_f32_16x16x32_bf16 v[116:119], v[168:171], v[184:187], 0
	v_mfma_f32_16x16x32_bf16 v[112:115], v[176:179], v[184:187], 0
	v_mfma_f32_16x16x32_bf16 v[100:103], v[168:171], v[192:195], 0
	v_mfma_f32_16x16x32_bf16 v[96:99], v[176:179], v[192:195], 0
	v_mfma_f32_16x16x32_bf16 v[84:87], v[168:171], v[200:203], 0
	v_mfma_f32_16x16x32_bf16 v[80:83], v[176:179], v[200:203], 0
	v_mfma_f32_16x16x32_bf16 v[68:71], v[168:171], v[208:211], 0
	v_mfma_f32_16x16x32_bf16 v[64:67], v[176:179], v[208:211], 0
	v_mfma_f32_16x16x32_bf16 v[116:119], v[172:175], v[188:191], v[116:119]
	v_mfma_f32_16x16x32_bf16 v[112:115], v[180:183], v[188:191], v[112:115]
	v_mfma_f32_16x16x32_bf16 v[100:103], v[172:175], v[196:199], v[100:103]
	v_mfma_f32_16x16x32_bf16 v[96:99], v[180:183], v[196:199], v[96:99]
	v_mfma_f32_16x16x32_bf16 v[84:87], v[172:175], v[204:207], v[84:87]
	v_mfma_f32_16x16x32_bf16 v[80:83], v[180:183], v[204:207], v[80:83]
	v_mfma_f32_16x16x32_bf16 v[68:71], v[172:175], v[212:215], v[68:71]
	v_mfma_f32_16x16x32_bf16 v[64:67], v[180:183], v[212:215], v[64:67]
	s_setprio 0
	s_barrier
	s_add_i32 s28, s58, s30
	v_lshl_add_u64 v[216:217], s[42:43], 0, v[130:131]
	s_mov_b32 m0, s28
	ds_read_b128 v[184:187], v153 offset:16384
	ds_read_b128 v[188:191], v153 offset:17408
	ds_read_b128 v[192:195], v153 offset:18432
	ds_read_b128 v[196:199], v153 offset:19456
	ds_read_b128 v[200:203], v153 offset:20480
	ds_read_b128 v[204:207], v153 offset:21504
	ds_read_b128 v[208:211], v153 offset:22528
	ds_read_b128 v[212:215], v153 offset:23552
	global_load_lds_dwordx4 v[216:217], off
	s_add_i32 m0, s28, 0x2000
	v_lshl_add_u64 v[218:219], s[42:43], 0, v[134:135]
	s_add_u32 s42, s42, s14
	s_addc_u32 s43, s43, s15
	s_add_i32 s28, s59, s30
	global_load_lds_dwordx4 v[218:219], off
	v_lshl_add_u64 v[220:221], s[42:43], 0, v[130:131]
	s_mov_b32 m0, s28
	v_lshl_add_u64 v[222:223], s[42:43], 0, v[134:135]
	global_load_lds_dwordx4 v[220:221], off
	s_add_i32 m0, s28, 0x2000
	v_lshl_add_u64 v[224:225], s[46:47], 0, v[128:129]
	global_load_lds_dwordx4 v[222:223], off
	s_mov_b32 m0, s31
	v_lshl_add_u64 v[226:227], s[46:47], 0, v[132:133]
	global_load_lds_dwordx4 v[224:225], off
	s_mov_b32 m0, s33
	s_nop 0
	global_load_lds_dwordx4 v[226:227], off
	s_waitcnt vmcnt(8)
	s_waitcnt lgkmcnt(0)
	s_barrier
; #define PG8_STAGE(bufoff, gbase, voff) do { _Pragma("unroll") for (int _i = 0; _i < 2; ++_i) \
;         __builtin_amdgcn_global_load_lds((const unsigned*)((const char*)(gbase) + (voff)[_i]), (PG8_LAS unsigned*)(lds + (bufoff) + ldsw + _i * 8192), 16, 0, 0); } while (0)
; #define PG8_LDA(dst, b, h) do { _Pragma("unroll") for (int m = 0; m < 4; ++m) _Pragma("unroll") for (int k = 0; k < 2; ++k) dst[m][k] = *(const PG8_LAS bf16x8*)(lds + PG8_SA(b, h) + aoff + m * 2048 + k * 1024); } while (0)
; #define PG8_LDB(dst, b, h) do { _Pragma("unroll") for (int n = 0; n < 2; ++n) _Pragma("unroll") for (int k = 0; k < 2; ++k) dst[n][k] = *(const PG8_LAS bf16x8*)(lds + PG8_SB(b, h) + boff + n * 2048 + k * 1024); } while (0)
; #define PG8_MMA(ai, bj, At, Bt) do { __builtin_amdgcn_s_setprio(1); _Pragma("unroll") for (int m = 0; m < 4; ++m) _Pragma("unroll") for (int n = 0; n < 2; ++n) _Pragma("unroll") for (int k = 0; k < 2; ++k) \
;         acc[ai][bj][m][n] = __builtin_amdgcn_mfma_f32_16x16x32_bf16(Bt[n][k], At[m][k], acc[ai][bj][m][n], 0, 0, 0); __builtin_amdgcn_s_setprio(0); } while (0)
; #define PG8_WAIT_V(n) asm volatile("s_waitcnt vmcnt(" #n ")" ::: "memory")
; #define PG8_WAIT_L(n) asm volatile("s_waitcnt lgkmcnt(" #n ")" ::: "memory")
; #define PG8_BAR __builtin_amdgcn_s_barrier()
; #define PG8_SCHED __builtin_amdgcn_sched_barrier(0)
; template <class Epi, class Sched, bool ALIGN_EPI = false, bool SP2 = false>
; __device__ __forceinline__ void gemm_phase(PG8_LAS unsigned char* lds, const Gemm g, const Sched& S, const Epi& E, const int wave_in) {
;     ...
;             PG8_WAIT_V(8); PG8_WAIT_L(0); PG8_BAR; PG8_MMA(1, 0, At, B0); PG8_MMA(1, 1, At, B1); PG8_BAR; PG8_SCHED;
;             PG8_LDB(B0, 1, 0); PG8_LDB(B1, 1, 1); PG8_SCHED; PG8_LDA(At, 1, 0); PG8_STAGE(PG8_SA(0, 1), a2 + hstep, voffA);
;             PG8_WAIT_V(8); PG8_WAIT_L(0); PG8_BAR; PG8_MMA(0, 0, At, B0); PG8_MMA(0, 1, At, B1); PG8_BAR; PG8_SCHED;
	s_setprio 1
	s_waitcnt lgkmcnt(0)
	v_mfma_f32_16x16x32_bf16 v[60:63], v[144:147], v[184:187], 0
	v_mfma_f32_16x16x32_bf16 v[56:59], v[160:163], v[184:187], 0
	v_mfma_f32_16x16x32_bf16 v[44:47], v[144:147], v[192:195], 0
	v_mfma_f32_16x16x32_bf16 v[40:43], v[160:163], v[192:195], 0
	v_mfma_f32_16x16x32_bf16 v[28:31], v[144:147], v[200:203], 0
	v_mfma_f32_16x16x32_bf16 v[24:27], v[160:163], v[200:203], 0
	v_mfma_f32_16x16x32_bf16 v[12:15], v[144:147], v[208:211], 0
	v_mfma_f32_16x16x32_bf16 v[8:11], v[160:163], v[208:211], 0
	v_mfma_f32_16x16x32_bf16 v[60:63], v[156:159], v[188:191], v[60:63]
	v_mfma_f32_16x16x32_bf16 v[56:59], v[164:167], v[188:191], v[56:59]
	v_mfma_f32_16x16x32_bf16 v[44:47], v[156:159], v[196:199], v[44:47]
	v_mfma_f32_16x16x32_bf16 v[40:43], v[164:167], v[196:199], v[40:43]
	v_mfma_f32_16x16x32_bf16 v[28:31], v[156:159], v[204:207], v[28:31]
	v_mfma_f32_16x16x32_bf16 v[24:27], v[164:167], v[204:207], v[24:27]
	v_mfma_f32_16x16x32_bf16 v[12:15], v[156:159], v[212:215], v[12:15]
	v_mfma_f32_16x16x32_bf16 v[8:11], v[164:167], v[212:215], v[8:11]
	s_setprio 0
	s_setprio 1
	v_mfma_f32_16x16x32_bf16 v[52:55], v[168:171], v[184:187], 0
	v_mfma_f32_16x16x32_bf16 v[48:51], v[176:179], v[184:187], 0
	v_mfma_f32_16x16x32_bf16 v[36:39], v[168:171], v[192:195], 0
	v_mfma_f32_16x16x32_bf16 v[32:35], v[176:179], v[192:195], 0
	v_mfma_f32_16x16x32_bf16 v[20:23], v[168:171], v[200:203], 0
	v_mfma_f32_16x16x32_bf16 v[16:19], v[176:179], v[200:203], 0
	v_mfma_f32_16x16x32_bf16 v[4:7], v[168:171], v[208:211], 0
	v_mfma_f32_16x16x32_bf16 v[0:3], v[176:179], v[208:211], 0
	v_mfma_f32_16x16x32_bf16 v[52:55], v[172:175], v[188:191], v[52:55]
	v_mfma_f32_16x16x32_bf16 v[48:51], v[180:183], v[188:191], v[48:51]
	v_mfma_f32_16x16x32_bf16 v[36:39], v[172:175], v[196:199], v[36:39]
	v_mfma_f32_16x16x32_bf16 v[32:35], v[180:183], v[196:199], v[32:35]
	v_mfma_f32_16x16x32_bf16 v[20:23], v[172:175], v[204:207], v[20:23]
	v_mfma_f32_16x16x32_bf16 v[16:19], v[180:183], v[204:207], v[16:19]
	v_mfma_f32_16x16x32_bf16 v[4:7], v[172:175], v[212:215], v[4:7]
	v_mfma_f32_16x16x32_bf16 v[0:3], v[180:183], v[212:215], v[0:3]
	s_setprio 0
	s_barrier
	s_add_i32 s28, 0, 0x18000
	v_add_u32_e32 v155, s28, v149
	s_add_i32 s44, 0, 0x1c000
	ds_read_b128 v[144:147], v155
	ds_read_b128 v[156:159], v155 offset:1024
	ds_read_b128 v[160:163], v155 offset:2048
	ds_read_b128 v[164:167], v155 offset:3072
	v_add_u32_e32 v155, s44, v149
	ds_read_b128 v[168:171], v155
	ds_read_b128 v[172:175], v155 offset:1024
	ds_read_b128 v[176:179], v155 offset:2048
	ds_read_b128 v[180:183], v155 offset:3072
	s_add_u32 s42, s46, s14
	s_addc_u32 s43, s47, s15
	s_mov_b32 m0, s34
	v_lshl_add_u64 v[228:229], s[42:43], 0, v[128:129]
	ds_read_b128 v[184:187], v153 offset:32768
	ds_read_b128 v[188:191], v153 offset:33792
	ds_read_b128 v[192:195], v153 offset:34816
	ds_read_b128 v[196:199], v153 offset:35840
	ds_read_b128 v[200:203], v153 offset:36864
	ds_read_b128 v[204:207], v153 offset:37888
	ds_read_b128 v[208:211], v153 offset:38912
	ds_read_b128 v[212:215], v153 offset:39936
	global_load_lds_dwordx4 v[228:229], off
	v_lshl_add_u64 v[228:229], s[42:43], 0, v[132:133]
	s_mov_b32 m0, s35
	s_nop 0
	global_load_lds_dwordx4 v[228:229], off
	s_waitcnt vmcnt(8)
	s_waitcnt lgkmcnt(0)
	s_barrier
	s_setprio 1
	s_waitcnt lgkmcnt(0)
	v_mfma_f32_16x16x32_bf16 v[120:123], v[144:147], v[184:187], v[120:123]
	v_mfma_f32_16x16x32_bf16 v[124:127], v[160:163], v[184:187], v[124:127]
	v_mfma_f32_16x16x32_bf16 v[108:111], v[144:147], v[192:195], v[108:111]
	v_mfma_f32_16x16x32_bf16 v[104:107], v[160:163], v[192:195], v[104:107]
	v_mfma_f32_16x16x32_bf16 v[92:95], v[144:147], v[200:203], v[92:95]
	v_mfma_f32_16x16x32_bf16 v[88:91], v[160:163], v[200:203], v[88:91]
	v_mfma_f32_16x16x32_bf16 v[76:79], v[144:147], v[208:211], v[76:79]
	v_mfma_f32_16x16x32_bf16 v[72:75], v[160:163], v[208:211], v[72:75]
	v_mfma_f32_16x16x32_bf16 v[120:123], v[156:159], v[188:191], v[120:123]
	v_mfma_f32_16x16x32_bf16 v[124:127], v[164:167], v[188:191], v[124:127]
	v_mfma_f32_16x16x32_bf16 v[108:111], v[156:159], v[196:199], v[108:111]
	v_mfma_f32_16x16x32_bf16 v[104:107], v[164:167], v[196:199], v[104:107]
	v_mfma_f32_16x16x32_bf16 v[92:95], v[156:159], v[204:207], v[92:95]
	v_mfma_f32_16x16x32_bf16 v[88:91], v[164:167], v[204:207], v[88:91]
	v_mfma_f32_16x16x32_bf16 v[76:79], v[156:159], v[212:215], v[76:79]
	v_mfma_f32_16x16x32_bf16 v[72:75], v[164:167], v[212:215], v[72:75]
	s_setprio 0
	s_setprio 1
	v_mfma_f32_16x16x32_bf16 v[116:119], v[168:171], v[184:187], v[116:119]
	v_mfma_f32_16x16x32_bf16 v[112:115], v[176:179], v[184:187], v[112:115]
	v_mfma_f32_16x16x32_bf16 v[100:103], v[168:171], v[192:195], v[100:103]
	v_mfma_f32_16x16x32_bf16 v[96:99], v[176:179], v[192:195], v[96:99]
	v_mfma_f32_16x16x32_bf16 v[84:87], v[168:171], v[200:203], v[84:87]
	v_mfma_f32_16x16x32_bf16 v[80:83], v[176:179], v[200:203], v[80:83]
	v_mfma_f32_16x16x32_bf16 v[68:71], v[168:171], v[208:211], v[68:71]
	v_mfma_f32_16x16x32_bf16 v[64:67], v[176:179], v[208:211], v[64:67]
	v_mfma_f32_16x16x32_bf16 v[116:119], v[172:175], v[188:191], v[116:119]
	v_mfma_f32_16x16x32_bf16 v[112:115], v[180:183], v[188:191], v[112:115]
	v_mfma_f32_16x16x32_bf16 v[100:103], v[172:175], v[196:199], v[100:103]
	v_mfma_f32_16x16x32_bf16 v[96:99], v[180:183], v[196:199], v[96:99]
	v_mfma_f32_16x16x32_bf16 v[84:87], v[172:175], v[204:207], v[84:87]
	v_mfma_f32_16x16x32_bf16 v[80:83], v[180:183], v[204:207], v[80:83]
	v_mfma_f32_16x16x32_bf16 v[68:71], v[172:175], v[212:215], v[68:71]
	v_mfma_f32_16x16x32_bf16 v[64:67], v[180:183], v[212:215], v[64:67]
	s_setprio 0
	s_barrier
; #define PG8_STAGE(bufoff, gbase, voff) do { _Pragma("unroll") for (int _i = 0; _i < 2; ++_i) \
;         __builtin_amdgcn_global_load_lds((const unsigned*)((const char*)(gbase) + (voff)[_i]), (PG8_LAS unsigned*)(lds + (bufoff) + ldsw + _i * 8192), 16, 0, 0); } while (0)
; #define PG8_LDA(dst, b, h) do { _Pragma("unroll") for (int m = 0; m < 4; ++m) _Pragma("unroll") for (int k = 0; k < 2; ++k) dst[m][k] = *(const PG8_LAS bf16x8*)(lds + PG8_SA(b, h) + aoff + m * 2048 + k * 1024); } while (0)
; #define PG8_LDB(dst, b, h) do { _Pragma("unroll") for (int n = 0; n < 2; ++n) _Pragma("unroll") for (int k = 0; k < 2; ++k) dst[n][k] = *(const PG8_LAS bf16x8*)(lds + PG8_SB(b, h) + boff + n * 2048 + k * 1024); } while (0)
; #define PG8_MMA(ai, bj, At, Bt) do { __builtin_amdgcn_s_setprio(1); _Pragma("unroll") for (int m = 0; m < 4; ++m) _Pragma("unroll") for (int n = 0; n < 2; ++n) _Pragma("unroll") for (int k = 0; k < 2; ++k) \
;         acc[ai][bj][m][n] = __builtin_amdgcn_mfma_f32_16x16x32_bf16(Bt[n][k], At[m][k], acc[ai][bj][m][n], 0, 0, 0); __builtin_amdgcn_s_setprio(0); } while (0)
; #define PG8_WAIT_V(n) asm volatile("s_waitcnt vmcnt(" #n ")" ::: "memory")
; #define PG8_WAIT_L(n) asm volatile("s_waitcnt lgkmcnt(" #n ")" ::: "memory")
; #define PG8_BAR __builtin_amdgcn_s_barrier()
; #define PG8_SCHED __builtin_amdgcn_sched_barrier(0)
; template <class Epi, class Sched, bool ALIGN_EPI = false, bool SP2 = false>
; __device__ __forceinline__ void gemm_phase(PG8_LAS unsigned char* lds, const Gemm g, const Sched& S, const Epi& E, const int wave_in) {
;     ...
;             PG8_LDB(B0, 0, 0); PG8_LDB(B1, 0, 1); PG8_SCHED; PG8_LDA(At, 0, 0); PG8_STAGE(PG8_SA(1, 1), a1 + hstep, voffA);
;             PG8_WAIT_V(8); PG8_WAIT_L(0); PG8_BAR; PG8_MMA(0, 0, At, B0); PG8_MMA(0, 1, At, B1); PG8_BAR; PG8_SCHED;
;     ...
;             PG8_LDA(At, 1, 1); PG8_STAGE(PG8_SB(1, 0), b3, voffB); PG8_STAGE(PG8_SB(1, 1), b3 + hstep, voffB); PG8_STAGE(PG8_SA(1, 0), a3, voffA);
;             PG8_WAIT_V(8); PG8_WAIT_L(0); PG8_BAR; PG8_MMA(1, 0, At, B0); PG8_MMA(1, 1, At, B1); PG8_BAR; PG8_SCHED;
	s_add_i32 s28, s28, s30
	v_lshl_add_u64 v[216:217], v[216:217], 0, s[22:23]
	s_mov_b32 m0, s28
	ds_read_b128 v[184:187], v153 offset:49152
	ds_read_b128 v[188:191], v153 offset:50176
	ds_read_b128 v[192:195], v153 offset:51200
	ds_read_b128 v[196:199], v153 offset:52224
	ds_read_b128 v[200:203], v153 offset:53248
	ds_read_b128 v[204:207], v153 offset:54272
	ds_read_b128 v[208:211], v153 offset:55296
	ds_read_b128 v[212:215], v153 offset:56320
	global_load_lds_dwordx4 v[216:217], off
	v_lshl_add_u64 v[216:217], v[218:219], 0, s[22:23]
	s_add_i32 m0, s28, 0x2000
	s_add_i32 s28, s44, s30
	global_load_lds_dwordx4 v[216:217], off
	v_lshl_add_u64 v[216:217], v[220:221], 0, s[22:23]
	s_mov_b32 m0, s28
	s_nop 0
	global_load_lds_dwordx4 v[216:217], off
	v_lshl_add_u64 v[216:217], v[222:223], 0, s[22:23]
	s_add_i32 m0, s28, 0x2000
	s_nop 0
	global_load_lds_dwordx4 v[216:217], off
	v_lshl_add_u64 v[216:217], v[224:225], 0, s[22:23]
	s_mov_b32 m0, s50
	s_nop 0
	global_load_lds_dwordx4 v[216:217], off
	v_lshl_add_u64 v[216:217], v[226:227], 0, s[22:23]
	s_mov_b32 m0, s51
	s_nop 0
	global_load_lds_dwordx4 v[216:217], off
	s_waitcnt vmcnt(8)
	s_waitcnt lgkmcnt(0)
	s_barrier
	s_setprio 1
	s_waitcnt lgkmcnt(0)
	v_mfma_f32_16x16x32_bf16 v[60:63], v[144:147], v[184:187], v[60:63]
	v_mfma_f32_16x16x32_bf16 v[56:59], v[160:163], v[184:187], v[56:59]
	v_mfma_f32_16x16x32_bf16 v[44:47], v[144:147], v[192:195], v[44:47]
	v_mfma_f32_16x16x32_bf16 v[40:43], v[160:163], v[192:195], v[40:43]
	v_mfma_f32_16x16x32_bf16 v[28:31], v[144:147], v[200:203], v[28:31]
	v_mfma_f32_16x16x32_bf16 v[24:27], v[160:163], v[200:203], v[24:27]
	v_mfma_f32_16x16x32_bf16 v[12:15], v[144:147], v[208:211], v[12:15]
	v_mfma_f32_16x16x32_bf16 v[8:11], v[160:163], v[208:211], v[8:11]
	v_mfma_f32_16x16x32_bf16 v[60:63], v[156:159], v[188:191], v[60:63]
	v_mfma_f32_16x16x32_bf16 v[56:59], v[164:167], v[188:191], v[56:59]
	v_mfma_f32_16x16x32_bf16 v[44:47], v[156:159], v[196:199], v[44:47]
	v_mfma_f32_16x16x32_bf16 v[40:43], v[164:167], v[196:199], v[40:43]
	v_mfma_f32_16x16x32_bf16 v[28:31], v[156:159], v[204:207], v[28:31]
	v_mfma_f32_16x16x32_bf16 v[24:27], v[164:167], v[204:207], v[24:27]
	v_mfma_f32_16x16x32_bf16 v[12:15], v[156:159], v[212:215], v[12:15]
	v_mfma_f32_16x16x32_bf16 v[8:11], v[164:167], v[212:215], v[8:11]
	s_setprio 0
	s_setprio 1
	v_mfma_f32_16x16x32_bf16 v[52:55], v[168:171], v[184:187], v[52:55]
	v_mfma_f32_16x16x32_bf16 v[48:51], v[176:179], v[184:187], v[48:51]
	v_mfma_f32_16x16x32_bf16 v[36:39], v[168:171], v[192:195], v[36:39]
	v_mfma_f32_16x16x32_bf16 v[32:35], v[176:179], v[192:195], v[32:35]
	v_mfma_f32_16x16x32_bf16 v[20:23], v[168:171], v[200:203], v[20:23]
	v_mfma_f32_16x16x32_bf16 v[16:19], v[176:179], v[200:203], v[16:19]
	v_mfma_f32_16x16x32_bf16 v[4:7], v[168:171], v[208:211], v[4:7]
	v_mfma_f32_16x16x32_bf16 v[0:3], v[176:179], v[208:211], v[0:3]
	v_mfma_f32_16x16x32_bf16 v[52:55], v[172:175], v[188:191], v[52:55]
	v_mfma_f32_16x16x32_bf16 v[48:51], v[180:183], v[188:191], v[48:51]
	v_mfma_f32_16x16x32_bf16 v[36:39], v[172:175], v[196:199], v[36:39]
	v_mfma_f32_16x16x32_bf16 v[32:35], v[180:183], v[196:199], v[32:35]
	v_mfma_f32_16x16x32_bf16 v[20:23], v[172:175], v[204:207], v[20:23]
	v_mfma_f32_16x16x32_bf16 v[16:19], v[180:183], v[204:207], v[16:19]
	v_mfma_f32_16x16x32_bf16 v[4:7], v[172:175], v[212:215], v[4:7]
	v_mfma_f32_16x16x32_bf16 v[0:3], v[180:183], v[212:215], v[0:3]
	s_setprio 0
	s_barrier
	s_add_u32 s40, s40, 0x100
	s_addc_u32 s41, s41, 0
	s_add_u32 s64, s64, 0x100
	s_addc_u32 s65, s65, 0
	s_cmp_ge_i32 s29, s52
	s_mov_b32 s28, s29
	s_cbranch_scc1 .Lkz_exit_3
.LBB0_1265:
	ds_read_b128 v[144:147], v151
	ds_read_b128 v[156:159], v151 offset:1024
	ds_read_b128 v[160:163], v151 offset:2048
	ds_read_b128 v[164:167], v151 offset:3072
	ds_read_b128 v[168:171], v152
	ds_read_b128 v[172:175], v152 offset:1024
	ds_read_b128 v[176:179], v152 offset:2048
	ds_read_b128 v[180:183], v152 offset:3072
	s_add_i32 s29, s28, 2
	s_add_u32 s42, s40, 0x80
	s_addc_u32 s43, s41, 0
	s_cmp_eq_u32 s53, s28
	s_cselect_b32 s47, s5, s43
	s_cselect_b32 s46, s4, s42
	s_cselect_b32 s43, s39, s65
	s_cselect_b32 s42, s38, s64
	v_lshl_add_u64 v[216:217], s[40:41], 0, v[136:137]
	s_add_i32 m0, s31, 0xc000
	ds_read_b128 v[184:187], v153
	ds_read_b128 v[188:191], v153 offset:1024
	ds_read_b128 v[192:195], v153 offset:2048
	ds_read_b128 v[196:199], v153 offset:3072
	ds_read_b128 v[200:203], v153 offset:4096
	ds_read_b128 v[204:207], v153 offset:5120
	ds_read_b128 v[208:211], v153 offset:6144
	ds_read_b128 v[212:215], v153 offset:7168
	global_load_lds_dwordx4 v[216:217], off
	v_lshl_add_u64 v[216:217], s[40:41], 0, v[138:139]
	s_add_i32 m0, s31, 0xe000
	s_nop 0
	global_load_lds_dwordx4 v[216:217], off
	s_waitcnt vmcnt(8)
	s_waitcnt lgkmcnt(0)
	s_barrier
; #define PG8_STAGE(bufoff, gbase, voff) do { _Pragma("unroll") for (int _i = 0; _i < 2; ++_i) \
;         __builtin_amdgcn_global_load_lds((const unsigned*)((const char*)(gbase) + (voff)[_i]), (PG8_LAS unsigned*)(lds + (bufoff) + ldsw + _i * 8192), 16, 0, 0); } while (0)
; #define PG8_LDA(dst, b, h) do { _Pragma("unroll") for (int m = 0; m < 4; ++m) _Pragma("unroll") for (int k = 0; k < 2; ++k) dst[m][k] = *(const PG8_LAS bf16x8*)(lds + PG8_SA(b, h) + aoff + m * 2048 + k * 1024); } while (0)
; #define PG8_MMA(ai, bj, At, Bt) do { __builtin_amdgcn_s_setprio(1); _Pragma("unroll") for (int m = 0; m < 4; ++m) _Pragma("unroll") for (int n = 0; n < 2; ++n) _Pragma("unroll") for (int k = 0; k < 2; ++k) \
;         acc[ai][bj][m][n] = __builtin_amdgcn_mfma_f32_16x16x32_bf16(Bt[n][k], At[m][k], acc[ai][bj][m][n], 0, 0, 0); __builtin_amdgcn_s_setprio(0); } while (0)
; #define PG8_WAIT_V(n) asm volatile("s_waitcnt vmcnt(" #n ")" ::: "memory")
; #define PG8_WAIT_L(n) asm volatile("s_waitcnt lgkmcnt(" #n ")" ::: "memory")
; #define PG8_BAR __builtin_amdgcn_s_barrier()
; #define PG8_SCHED __builtin_amdgcn_sched_barrier(0)
; template <class Epi, class Sched, bool ALIGN_EPI = false, bool SP2 = false>
; __device__ __forceinline__ void gemm_phase(PG8_LAS unsigned char* lds, const Gemm g, const Sched& S, const Epi& E, const int wave_in) {
;     ...
;             PG8_WAIT_V(8); PG8_WAIT_L(0); PG8_BAR; PG8_MMA(0, 0, At, B0); PG8_MMA(0, 1, At, B1); PG8_BAR; PG8_SCHED;
;             PG8_LDA(At, 0, 1); PG8_STAGE(PG8_SB(0, 0), b2, voffB); PG8_STAGE(PG8_SB(0, 1), b2 + hstep, voffB); PG8_STAGE(PG8_SA(0, 0), a2, voffA);
;             PG8_WAIT_V(8); PG8_WAIT_L(0); PG8_BAR; PG8_MMA(1, 0, At, B0); PG8_MMA(1, 1, At, B1); PG8_BAR; PG8_SCHED;
	s_setprio 1
	s_waitcnt lgkmcnt(0)
	v_mfma_f32_16x16x32_bf16 v[120:123], v[144:147], v[184:187], v[120:123]
	v_mfma_f32_16x16x32_bf16 v[124:127], v[160:163], v[184:187], v[124:127]
	v_mfma_f32_16x16x32_bf16 v[108:111], v[144:147], v[192:195], v[108:111]
	v_mfma_f32_16x16x32_bf16 v[104:107], v[160:163], v[192:195], v[104:107]
	v_mfma_f32_16x16x32_bf16 v[92:95], v[144:147], v[200:203], v[92:95]
	v_mfma_f32_16x16x32_bf16 v[88:91], v[160:163], v[200:203], v[88:91]
	v_mfma_f32_16x16x32_bf16 v[76:79], v[144:147], v[208:211], v[76:79]
	v_mfma_f32_16x16x32_bf16 v[72:75], v[160:163], v[208:211], v[72:75]
	v_mfma_f32_16x16x32_bf16 v[120:123], v[156:159], v[188:191], v[120:123]
	v_mfma_f32_16x16x32_bf16 v[124:127], v[164:167], v[188:191], v[124:127]
	v_mfma_f32_16x16x32_bf16 v[108:111], v[156:159], v[196:199], v[108:111]
	v_mfma_f32_16x16x32_bf16 v[104:107], v[164:167], v[196:199], v[104:107]
	v_mfma_f32_16x16x32_bf16 v[92:95], v[156:159], v[204:207], v[92:95]
	v_mfma_f32_16x16x32_bf16 v[88:91], v[164:167], v[204:207], v[88:91]
	v_mfma_f32_16x16x32_bf16 v[76:79], v[156:159], v[212:215], v[76:79]
	v_mfma_f32_16x16x32_bf16 v[72:75], v[164:167], v[212:215], v[72:75]
	s_setprio 0
	s_setprio 1
	v_mfma_f32_16x16x32_bf16 v[116:119], v[168:171], v[184:187], v[116:119]
	v_mfma_f32_16x16x32_bf16 v[112:115], v[176:179], v[184:187], v[112:115]
	v_mfma_f32_16x16x32_bf16 v[100:103], v[168:171], v[192:195], v[100:103]
	v_mfma_f32_16x16x32_bf16 v[96:99], v[176:179], v[192:195], v[96:99]
	v_mfma_f32_16x16x32_bf16 v[84:87], v[168:171], v[200:203], v[84:87]
	v_mfma_f32_16x16x32_bf16 v[80:83], v[176:179], v[200:203], v[80:83]
	v_mfma_f32_16x16x32_bf16 v[68:71], v[168:171], v[208:211], v[68:71]
	v_mfma_f32_16x16x32_bf16 v[64:67], v[176:179], v[208:211], v[64:67]
	v_mfma_f32_16x16x32_bf16 v[116:119], v[172:175], v[188:191], v[116:119]
	v_mfma_f32_16x16x32_bf16 v[112:115], v[180:183], v[188:191], v[112:115]
	v_mfma_f32_16x16x32_bf16 v[100:103], v[172:175], v[196:199], v[100:103]
	v_mfma_f32_16x16x32_bf16 v[96:99], v[180:183], v[196:199], v[96:99]
	v_mfma_f32_16x16x32_bf16 v[84:87], v[172:175], v[204:207], v[84:87]
	v_mfma_f32_16x16x32_bf16 v[80:83], v[180:183], v[204:207], v[80:83]
	v_mfma_f32_16x16x32_bf16 v[68:71], v[172:175], v[212:215], v[68:71]
	v_mfma_f32_16x16x32_bf16 v[64:67], v[180:183], v[212:215], v[64:67]
	s_setprio 0
	s_barrier
	s_add_i32 s28, s58, s30
	v_lshl_add_u64 v[216:217], s[42:43], 0, v[130:131]
	s_mov_b32 m0, s28
	ds_read_b128 v[184:187], v153 offset:16384
	ds_read_b128 v[188:191], v153 offset:17408
	ds_read_b128 v[192:195], v153 offset:18432
	ds_read_b128 v[196:199], v153 offset:19456
	ds_read_b128 v[200:203], v153 offset:20480
	ds_read_b128 v[204:207], v153 offset:21504
	ds_read_b128 v[208:211], v153 offset:22528
	ds_read_b128 v[212:215], v153 offset:23552
	global_load_lds_dwordx4 v[216:217], off
	s_add_i32 m0, s28, 0x2000
	v_lshl_add_u64 v[218:219], s[42:43], 0, v[134:135]
	s_add_u32 s42, s42, s14
	s_addc_u32 s43, s43, s15
	s_add_i32 s28, s59, s30
	global_load_lds_dwordx4 v[218:219], off
	v_lshl_add_u64 v[220:221], s[42:43], 0, v[130:131]
	s_mov_b32 m0, s28
	v_lshl_add_u64 v[222:223], s[42:43], 0, v[134:135]
	global_load_lds_dwordx4 v[220:221], off
	s_add_i32 m0, s28, 0x2000
	v_lshl_add_u64 v[224:225], s[46:47], 0, v[128:129]
	global_load_lds_dwordx4 v[222:223], off
	s_mov_b32 m0, s31
	v_lshl_add_u64 v[226:227], s[46:47], 0, v[132:133]
	global_load_lds_dwordx4 v[224:225], off
	s_mov_b32 m0, s33
	s_nop 0
	global_load_lds_dwordx4 v[226:227], off
	s_waitcnt vmcnt(8)
	s_waitcnt lgkmcnt(0)
	s_barrier
	s_setprio 1
	s_waitcnt lgkmcnt(0)
	v_mfma_f32_16x16x32_bf16 v[60:63], v[144:147], v[184:187], v[60:63]
	v_mfma_f32_16x16x32_bf16 v[56:59], v[160:163], v[184:187], v[56:59]
	v_mfma_f32_16x16x32_bf16 v[44:47], v[144:147], v[192:195], v[44:47]
	v_mfma_f32_16x16x32_bf16 v[40:43], v[160:163], v[192:195], v[40:43]
	v_mfma_f32_16x16x32_bf16 v[28:31], v[144:147], v[200:203], v[28:31]
	v_mfma_f32_16x16x32_bf16 v[24:27], v[160:163], v[200:203], v[24:27]
	v_mfma_f32_16x16x32_bf16 v[12:15], v[144:147], v[208:211], v[12:15]
	v_mfma_f32_16x16x32_bf16 v[8:11], v[160:163], v[208:211], v[8:11]
	v_mfma_f32_16x16x32_bf16 v[60:63], v[156:159], v[188:191], v[60:63]
	v_mfma_f32_16x16x32_bf16 v[56:59], v[164:167], v[188:191], v[56:59]
	v_mfma_f32_16x16x32_bf16 v[44:47], v[156:159], v[196:199], v[44:47]
	v_mfma_f32_16x16x32_bf16 v[40:43], v[164:167], v[196:199], v[40:43]
	v_mfma_f32_16x16x32_bf16 v[28:31], v[156:159], v[204:207], v[28:31]
	v_mfma_f32_16x16x32_bf16 v[24:27], v[164:167], v[204:207], v[24:27]
	v_mfma_f32_16x16x32_bf16 v[12:15], v[156:159], v[212:215], v[12:15]
	v_mfma_f32_16x16x32_bf16 v[8:11], v[164:167], v[212:215], v[8:11]
	s_setprio 0
	s_setprio 1
	v_mfma_f32_16x16x32_bf16 v[52:55], v[168:171], v[184:187], v[52:55]
	v_mfma_f32_16x16x32_bf16 v[48:51], v[176:179], v[184:187], v[48:51]
	v_mfma_f32_16x16x32_bf16 v[36:39], v[168:171], v[192:195], v[36:39]
	v_mfma_f32_16x16x32_bf16 v[32:35], v[176:179], v[192:195], v[32:35]
	v_mfma_f32_16x16x32_bf16 v[20:23], v[168:171], v[200:203], v[20:23]
	v_mfma_f32_16x16x32_bf16 v[16:19], v[176:179], v[200:203], v[16:19]
	v_mfma_f32_16x16x32_bf16 v[4:7], v[168:171], v[208:211], v[4:7]
	v_mfma_f32_16x16x32_bf16 v[0:3], v[176:179], v[208:211], v[0:3]
	v_mfma_f32_16x16x32_bf16 v[52:55], v[172:175], v[188:191], v[52:55]
	v_mfma_f32_16x16x32_bf16 v[48:51], v[180:183], v[188:191], v[48:51]
	v_mfma_f32_16x16x32_bf16 v[36:39], v[172:175], v[196:199], v[36:39]
	v_mfma_f32_16x16x32_bf16 v[32:35], v[180:183], v[196:199], v[32:35]
	v_mfma_f32_16x16x32_bf16 v[20:23], v[172:175], v[204:207], v[20:23]
	v_mfma_f32_16x16x32_bf16 v[16:19], v[180:183], v[204:207], v[16:19]
	v_mfma_f32_16x16x32_bf16 v[4:7], v[172:175], v[212:215], v[4:7]
	v_mfma_f32_16x16x32_bf16 v[0:3], v[180:183], v[212:215], v[0:3]
	s_setprio 0
	s_barrier
; #define PG8_STAGE(bufoff, gbase, voff) do { _Pragma("unroll") for (int _i = 0; _i < 2; ++_i) \
;         __builtin_amdgcn_global_load_lds((const unsigned*)((const char*)(gbase) + (voff)[_i]), (PG8_LAS unsigned*)(lds + (bufoff) + ldsw + _i * 8192), 16, 0, 0); } while (0)
; #define PG8_LDA(dst, b, h) do { _Pragma("unroll") for (int m = 0; m < 4; ++m) _Pragma("unroll") for (int k = 0; k < 2; ++k) dst[m][k] = *(const PG8_LAS bf16x8*)(lds + PG8_SA(b, h) + aoff + m * 2048 + k * 1024); } while (0)
; #define PG8_LDB(dst, b, h) do { _Pragma("unroll") for (int n = 0; n < 2; ++n) _Pragma("unroll") for (int k = 0; k < 2; ++k) dst[n][k] = *(const PG8_LAS bf16x8*)(lds + PG8_SB(b, h) + boff + n * 2048 + k * 1024); } while (0)
; #define PG8_MMA(ai, bj, At, Bt) do { __builtin_amdgcn_s_setprio(1); _Pragma("unroll") for (int m = 0; m < 4; ++m) _Pragma("unroll") for (int n = 0; n < 2; ++n) _Pragma("unroll") for (int k = 0; k < 2; ++k) \
;         acc[ai][bj][m][n] = __builtin_amdgcn_mfma_f32_16x16x32_bf16(Bt[n][k], At[m][k], acc[ai][bj][m][n], 0, 0, 0); __builtin_amdgcn_s_setprio(0); } while (0)
; #define PG8_WAIT_V(n) asm volatile("s_waitcnt vmcnt(" #n ")" ::: "memory")
; #define PG8_WAIT_L(n) asm volatile("s_waitcnt lgkmcnt(" #n ")" ::: "memory")
; #define PG8_BAR __builtin_amdgcn_s_barrier()
; #define PG8_SCHED __builtin_amdgcn_sched_barrier(0)
; template <class Epi, class Sched, bool ALIGN_EPI = false, bool SP2 = false>
; __device__ __forceinline__ void gemm_phase(PG8_LAS unsigned char* lds, const Gemm g, const Sched& S, const Epi& E, const int wave_in) {
;     ...
;             PG8_LDB(B0, 1, 0); PG8_LDB(B1, 1, 1); PG8_SCHED; PG8_LDA(At, 1, 0); PG8_STAGE(PG8_SA(0, 1), a2 + hstep, voffA);
;             PG8_WAIT_V(8); PG8_WAIT_L(0); PG8_BAR; PG8_MMA(0, 0, At, B0); PG8_MMA(0, 1, At, B1); PG8_BAR; PG8_SCHED;
	s_add_i32 s28, 0, 0x18000
	v_add_u32_e32 v155, s28, v149
	s_add_i32 s44, 0, 0x1c000
	ds_read_b128 v[144:147], v155
	ds_read_b128 v[156:159], v155 offset:1024
	ds_read_b128 v[160:163], v155 offset:2048
	ds_read_b128 v[164:167], v155 offset:3072
	v_add_u32_e32 v155, s44, v149
	ds_read_b128 v[168:171], v155
	ds_read_b128 v[172:175], v155 offset:1024
	ds_read_b128 v[176:179], v155 offset:2048
	ds_read_b128 v[180:183], v155 offset:3072
	s_add_u32 s42, s46, s14
	s_addc_u32 s43, s47, s15
	s_mov_b32 m0, s34
	v_lshl_add_u64 v[228:229], s[42:43], 0, v[128:129]
	ds_read_b128 v[184:187], v153 offset:32768
	ds_read_b128 v[188:191], v153 offset:33792
	ds_read_b128 v[192:195], v153 offset:34816
	ds_read_b128 v[196:199], v153 offset:35840
	ds_read_b128 v[200:203], v153 offset:36864
	ds_read_b128 v[204:207], v153 offset:37888
	ds_read_b128 v[208:211], v153 offset:38912
	ds_read_b128 v[212:215], v153 offset:39936
	global_load_lds_dwordx4 v[228:229], off
	v_lshl_add_u64 v[228:229], s[42:43], 0, v[132:133]
	s_mov_b32 m0, s35
	s_nop 0
	global_load_lds_dwordx4 v[228:229], off
	s_waitcnt vmcnt(8)
	s_waitcnt lgkmcnt(0)
	s_barrier
	s_setprio 1
	s_waitcnt lgkmcnt(0)
	v_mfma_f32_16x16x32_bf16 v[120:123], v[144:147], v[184:187], v[120:123]
	v_mfma_f32_16x16x32_bf16 v[124:127], v[160:163], v[184:187], v[124:127]
	v_mfma_f32_16x16x32_bf16 v[108:111], v[144:147], v[192:195], v[108:111]
	v_mfma_f32_16x16x32_bf16 v[104:107], v[160:163], v[192:195], v[104:107]
	v_mfma_f32_16x16x32_bf16 v[92:95], v[144:147], v[200:203], v[92:95]
	v_mfma_f32_16x16x32_bf16 v[88:91], v[160:163], v[200:203], v[88:91]
	v_mfma_f32_16x16x32_bf16 v[76:79], v[144:147], v[208:211], v[76:79]
	v_mfma_f32_16x16x32_bf16 v[72:75], v[160:163], v[208:211], v[72:75]
	v_mfma_f32_16x16x32_bf16 v[120:123], v[156:159], v[188:191], v[120:123]
	v_mfma_f32_16x16x32_bf16 v[124:127], v[164:167], v[188:191], v[124:127]
	v_mfma_f32_16x16x32_bf16 v[108:111], v[156:159], v[196:199], v[108:111]
	v_mfma_f32_16x16x32_bf16 v[104:107], v[164:167], v[196:199], v[104:107]
	v_mfma_f32_16x16x32_bf16 v[92:95], v[156:159], v[204:207], v[92:95]
	v_mfma_f32_16x16x32_bf16 v[88:91], v[164:167], v[204:207], v[88:91]
	v_mfma_f32_16x16x32_bf16 v[76:79], v[156:159], v[212:215], v[76:79]
	v_mfma_f32_16x16x32_bf16 v[72:75], v[164:167], v[212:215], v[72:75]
	s_setprio 0
	s_setprio 1
	v_mfma_f32_16x16x32_bf16 v[116:119], v[168:171], v[184:187], v[116:119]
	v_mfma_f32_16x16x32_bf16 v[112:115], v[176:179], v[184:187], v[112:115]
	v_mfma_f32_16x16x32_bf16 v[100:103], v[168:171], v[192:195], v[100:103]
	v_mfma_f32_16x16x32_bf16 v[96:99], v[176:179], v[192:195], v[96:99]
	v_mfma_f32_16x16x32_bf16 v[84:87], v[168:171], v[200:203], v[84:87]
	v_mfma_f32_16x16x32_bf16 v[80:83], v[176:179], v[200:203], v[80:83]
	v_mfma_f32_16x16x32_bf16 v[68:71], v[168:171], v[208:211], v[68:71]
	v_mfma_f32_16x16x32_bf16 v[64:67], v[176:179], v[208:211], v[64:67]
	v_mfma_f32_16x16x32_bf16 v[116:119], v[172:175], v[188:191], v[116:119]
	v_mfma_f32_16x16x32_bf16 v[112:115], v[180:183], v[188:191], v[112:115]
	v_mfma_f32_16x16x32_bf16 v[100:103], v[172:175], v[196:199], v[100:103]
	v_mfma_f32_16x16x32_bf16 v[96:99], v[180:183], v[196:199], v[96:99]
	v_mfma_f32_16x16x32_bf16 v[84:87], v[172:175], v[204:207], v[84:87]
	v_mfma_f32_16x16x32_bf16 v[80:83], v[180:183], v[204:207], v[80:83]
	v_mfma_f32_16x16x32_bf16 v[68:71], v[172:175], v[212:215], v[68:71]
	v_mfma_f32_16x16x32_bf16 v[64:67], v[180:183], v[212:215], v[64:67]
	s_setprio 0
	s_barrier
; #define PG8_STAGE(bufoff, gbase, voff) do { _Pragma("unroll") for (int _i = 0; _i < 2; ++_i) \
;         __builtin_amdgcn_global_load_lds((const unsigned*)((const char*)(gbase) + (voff)[_i]), (PG8_LAS unsigned*)(lds + (bufoff) + ldsw + _i * 8192), 16, 0, 0); } while (0)
; #define PG8_LDA(dst, b, h) do { _Pragma("unroll") for (int m = 0; m < 4; ++m) _Pragma("unroll") for (int k = 0; k < 2; ++k) dst[m][k] = *(const PG8_LAS bf16x8*)(lds + PG8_SA(b, h) + aoff + m * 2048 + k * 1024); } while (0)
; #define PG8_MMA(ai, bj, At, Bt) do { __builtin_amdgcn_s_setprio(1); _Pragma("unroll") for (int m = 0; m < 4; ++m) _Pragma("unroll") for (int n = 0; n < 2; ++n) _Pragma("unroll") for (int k = 0; k < 2; ++k) \
;         acc[ai][bj][m][n] = __builtin_amdgcn_mfma_f32_16x16x32_bf16(Bt[n][k], At[m][k], acc[ai][bj][m][n], 0, 0, 0); __builtin_amdgcn_s_setprio(0); } while (0)
; #define PG8_WAIT_V(n) asm volatile("s_waitcnt vmcnt(" #n ")" ::: "memory")
; #define PG8_WAIT_L(n) asm volatile("s_waitcnt lgkmcnt(" #n ")" ::: "memory")
; #define PG8_BAR __builtin_amdgcn_s_barrier()
; #define PG8_SCHED __builtin_amdgcn_sched_barrier(0)
; template <class Epi, class Sched, bool ALIGN_EPI = false, bool SP2 = false>
; __device__ __forceinline__ void gemm_phase(PG8_LAS unsigned char* lds, const Gemm g, const Sched& S, const Epi& E, const int wave_in) {
;     ...
;             PG8_LDA(At, 1, 1); PG8_STAGE(PG8_SB(1, 0), b3, voffB); PG8_STAGE(PG8_SB(1, 1), b3 + hstep, voffB); PG8_STAGE(PG8_SA(1, 0), a3, voffA);
;             PG8_WAIT_V(8); PG8_WAIT_L(0); PG8_BAR; PG8_MMA(1, 0, At, B0); PG8_MMA(1, 1, At, B1); PG8_BAR; PG8_SCHED;
	s_add_i32 s28, s28, s30
	v_lshl_add_u64 v[216:217], v[216:217], 0, s[22:23]
	s_mov_b32 m0, s28
	ds_read_b128 v[184:187], v153 offset:49152
	ds_read_b128 v[188:191], v153 offset:50176
	ds_read_b128 v[192:195], v153 offset:51200
	ds_read_b128 v[196:199], v153 offset:52224
	ds_read_b128 v[200:203], v153 offset:53248
	ds_read_b128 v[204:207], v153 offset:54272
	ds_read_b128 v[208:211], v153 offset:55296
	ds_read_b128 v[212:215], v153 offset:56320
	global_load_lds_dwordx4 v[216:217], off
	v_lshl_add_u64 v[216:217], v[218:219], 0, s[22:23]
	s_add_i32 m0, s28, 0x2000
	s_add_i32 s28, s44, s30
	global_load_lds_dwordx4 v[216:217], off
	v_lshl_add_u64 v[216:217], v[220:221], 0, s[22:23]
	s_mov_b32 m0, s28
	s_nop 0
	global_load_lds_dwordx4 v[216:217], off
	v_lshl_add_u64 v[216:217], v[222:223], 0, s[22:23]
	s_add_i32 m0, s28, 0x2000
	s_nop 0
	global_load_lds_dwordx4 v[216:217], off
	v_lshl_add_u64 v[216:217], v[224:225], 0, s[22:23]
	s_mov_b32 m0, s50
	s_nop 0
	global_load_lds_dwordx4 v[216:217], off
	v_lshl_add_u64 v[216:217], v[226:227], 0, s[22:23]
	s_mov_b32 m0, s51
	s_nop 0
	global_load_lds_dwordx4 v[216:217], off
	s_waitcnt vmcnt(8)
	s_waitcnt lgkmcnt(0)
	s_barrier
	s_setprio 1
	s_waitcnt lgkmcnt(0)
	v_mfma_f32_16x16x32_bf16 v[60:63], v[144:147], v[184:187], v[60:63]
	v_mfma_f32_16x16x32_bf16 v[56:59], v[160:163], v[184:187], v[56:59]
	v_mfma_f32_16x16x32_bf16 v[44:47], v[144:147], v[192:195], v[44:47]
	v_mfma_f32_16x16x32_bf16 v[40:43], v[160:163], v[192:195], v[40:43]
	v_mfma_f32_16x16x32_bf16 v[28:31], v[144:147], v[200:203], v[28:31]
	v_mfma_f32_16x16x32_bf16 v[24:27], v[160:163], v[200:203], v[24:27]
	v_mfma_f32_16x16x32_bf16 v[12:15], v[144:147], v[208:211], v[12:15]
	v_mfma_f32_16x16x32_bf16 v[8:11], v[160:163], v[208:211], v[8:11]
	v_mfma_f32_16x16x32_bf16 v[60:63], v[156:159], v[188:191], v[60:63]
	v_mfma_f32_16x16x32_bf16 v[56:59], v[164:167], v[188:191], v[56:59]
	v_mfma_f32_16x16x32_bf16 v[44:47], v[156:159], v[196:199], v[44:47]
	v_mfma_f32_16x16x32_bf16 v[40:43], v[164:167], v[196:199], v[40:43]
	v_mfma_f32_16x16x32_bf16 v[28:31], v[156:159], v[204:207], v[28:31]
	v_mfma_f32_16x16x32_bf16 v[24:27], v[164:167], v[204:207], v[24:27]
	v_mfma_f32_16x16x32_bf16 v[12:15], v[156:159], v[212:215], v[12:15]
	v_mfma_f32_16x16x32_bf16 v[8:11], v[164:167], v[212:215], v[8:11]
	s_setprio 0
	s_setprio 1
	v_mfma_f32_16x16x32_bf16 v[52:55], v[168:171], v[184:187], v[52:55]
	v_mfma_f32_16x16x32_bf16 v[48:51], v[176:179], v[184:187], v[48:51]
	v_mfma_f32_16x16x32_bf16 v[36:39], v[168:171], v[192:195], v[36:39]
	v_mfma_f32_16x16x32_bf16 v[32:35], v[176:179], v[192:195], v[32:35]
	v_mfma_f32_16x16x32_bf16 v[20:23], v[168:171], v[200:203], v[20:23]
	v_mfma_f32_16x16x32_bf16 v[16:19], v[176:179], v[200:203], v[16:19]
	v_mfma_f32_16x16x32_bf16 v[4:7], v[168:171], v[208:211], v[4:7]
	v_mfma_f32_16x16x32_bf16 v[0:3], v[176:179], v[208:211], v[0:3]
	v_mfma_f32_16x16x32_bf16 v[52:55], v[172:175], v[188:191], v[52:55]
	v_mfma_f32_16x16x32_bf16 v[48:51], v[180:183], v[188:191], v[48:51]
	v_mfma_f32_16x16x32_bf16 v[36:39], v[172:175], v[196:199], v[36:39]
	v_mfma_f32_16x16x32_bf16 v[32:35], v[180:183], v[196:199], v[32:35]
	v_mfma_f32_16x16x32_bf16 v[20:23], v[172:175], v[204:207], v[20:23]
	v_mfma_f32_16x16x32_bf16 v[16:19], v[180:183], v[204:207], v[16:19]
	v_mfma_f32_16x16x32_bf16 v[4:7], v[172:175], v[212:215], v[4:7]
	v_mfma_f32_16x16x32_bf16 v[0:3], v[180:183], v[212:215], v[0:3]
	s_setprio 0
	s_barrier
	s_add_u32 s40, s40, 0x100
	s_addc_u32 s41, s41, 0
	s_add_u32 s64, s64, 0x100
	s_addc_u32 s65, s65, 0
	s_cmp_ge_i32 s29, s52
	s_mov_b32 s28, s29
	s_cbranch_scc0 .LBB0_1265
.Lkz_exit_3:
	s_branch .LBB0_1266

; #define PG8_STAGE(bufoff, gbase, voff) do { _Pragma("unroll") for (int _i = 0; _i < 2; ++_i) \
;         __builtin_amdgcn_global_load_lds((const unsigned*)((const char*)(gbase) + (voff)[_i]), (PG8_LAS unsigned*)(lds + (bufoff) + ldsw + _i * 8192), 16, 0, 0); } while (0)
; #define PG8_LDA(dst, b, h) do { _Pragma("unroll") for (int m = 0; m < 4; ++m) _Pragma("unroll") for (int k = 0; k < 2; ++k) dst[m][k] = *(const PG8_LAS bf16x8*)(lds + PG8_SA(b, h) + aoff + m * 2048 + k * 1024); } while (0)
; #define PG8_LDB(dst, b, h) do { _Pragma("unroll") for (int n = 0; n < 2; ++n) _Pragma("unroll") for (int k = 0; k < 2; ++k) dst[n][k] = *(const PG8_LAS bf16x8*)(lds + PG8_SB(b, h) + boff + n * 2048 + k * 1024); } while (0)
; #define PG8_MMA(ai, bj, At, Bt) do { __builtin_amdgcn_s_setprio(1); _Pragma("unroll") for (int m = 0; m < 4; ++m) _Pragma("unroll") for (int n = 0; n < 2; ++n) _Pragma("unroll") for (int k = 0; k < 2; ++k) \
;         acc[ai][bj][m][n] = __builtin_amdgcn_mfma_f32_16x16x32_bf16(Bt[n][k], At[m][k], acc[ai][bj][m][n], 0, 0, 0); __builtin_amdgcn_s_setprio(0); } while (0)
; template <class Epi, class Sched, bool ALIGN_EPI = false, bool SP2 = false>
; __device__ __forceinline__ void gemm_phase(PG8_LAS unsigned char* lds, const Gemm g, const Sched& S, const Epi& E, const int wave_in) {
;     ...
;         const bool has_next = S.next(ui + 1, nxt);
;         const char* nA = has_next ? (const char*)g.A + (size_t)nxt.pm * tstep : cA; const char* nB = has_next ? (const char*)g.Bt + (size_t)nxt.pn * tstep : cB;
;         for (int t = 0; t < nt; t += 2) {
;             const bool last = (t == nt - 2);
;             const char* a1 = cA + (size_t)(t + 1) * kstep;
;             const char* a2 = last ? nA : cA + (size_t)(t + 2) * kstep; const char* b2 = last ? nB : cB + (size_t)(t + 2) * kstep;
;             const char* a3 = a2 + kstep; const char* b3 = b2 + kstep;
;             if (last && has_next) S.a_ready(nxt);
;             if constexpr (SP2) {
;             PG8_LDB(B0, 0, 0); PG8_LDB(B1, 0, 1); PG8_SCHED; PG8_LDA(At, 0, 0); PG8_STAGE(PG8_SA(1, 1), a1 + hstep, voffA);
;             PG8_WAIT_V(8); PG8_WAIT_L(0); PG8_BAR; PG8_MMA(0, 0, At, B0); PG8_MMA(0, 1, At, B1); PG8_BAR; PG8_SCHED;
;             PG8_LDA(At, 0, 1); PG8_STAGE(PG8_SB(0, 0), b2, voffB); PG8_STAGE(PG8_SB(0, 1), b2 + hstep, voffB); PG8_STAGE(PG8_SA(0, 0), a2, voffA);
.LBB0_1362:
	s_andn2_b64 vcc, exec, s[26:27]
	s_cbranch_vccnz .Lkz_skip_4
	s_add_u32 s8, s64, 0x80
	s_addc_u32 s9, s65, 0
	s_add_u32 s46, s62, 0x100
	s_addc_u32 s64, s63, 0
	s_mov_b32 s28, 0
	ds_read_b128 v[96:99], v250
	ds_read_b128 v[100:103], v250 offset:1024
	ds_read_b128 v[104:107], v250 offset:2048
	ds_read_b128 v[108:111], v250 offset:3072
	ds_read_b128 v[112:115], v251
	ds_read_b128 v[116:119], v251 offset:1024
	ds_read_b128 v[120:123], v251 offset:2048
	ds_read_b128 v[124:127], v251 offset:3072
	s_add_i32 s29, s28, 2
	s_add_u32 s42, s8, 0x80
	s_addc_u32 s43, s9, 0
	s_cmp_eq_u32 s96, s28
	s_cselect_b32 s63, s59, s43
	s_cselect_b32 s62, s58, s42
	s_cselect_b32 s43, s61, s64
	s_cselect_b32 s42, s60, s46
	v_lshl_add_u64 v[214:215], s[8:9], 0, v[174:175]
	s_add_i32 m0, s57, 0xc000
	ds_read_b128 v[182:185], v252
	ds_read_b128 v[186:189], v252 offset:1024
	ds_read_b128 v[190:193], v252 offset:2048
	ds_read_b128 v[194:197], v252 offset:3072
	ds_read_b128 v[198:201], v252 offset:4096
	ds_read_b128 v[202:205], v252 offset:5120
	ds_read_b128 v[206:209], v252 offset:6144
	ds_read_b128 v[210:213], v252 offset:7168
	global_load_lds_dwordx4 v[214:215], off
	v_lshl_add_u64 v[214:215], s[8:9], 0, v[176:177]
	s_add_i32 m0, s57, 0xe000
	s_nop 0
	global_load_lds_dwordx4 v[214:215], off
	s_waitcnt vmcnt(8)
	s_waitcnt lgkmcnt(0)
	s_barrier
	s_setprio 1
	s_waitcnt lgkmcnt(0)
	v_mfma_f32_16x16x32_bf16 v[156:159], v[96:99], v[182:185], 0
	v_mfma_f32_16x16x32_bf16 v[152:155], v[104:107], v[182:185], 0
	v_mfma_f32_16x16x32_bf16 v[140:143], v[96:99], v[190:193], 0
	v_mfma_f32_16x16x32_bf16 v[136:139], v[104:107], v[190:193], 0
	v_mfma_f32_16x16x32_bf16 v[20:23], v[96:99], v[198:201], 0
	v_mfma_f32_16x16x32_bf16 v[28:31], v[104:107], v[198:201], 0
	v_mfma_f32_16x16x32_bf16 v[4:7], v[96:99], v[206:209], 0
	v_mfma_f32_16x16x32_bf16 v[12:15], v[104:107], v[206:209], 0
	v_mfma_f32_16x16x32_bf16 v[156:159], v[100:103], v[186:189], v[156:159]
	v_mfma_f32_16x16x32_bf16 v[152:155], v[108:111], v[186:189], v[152:155]
	v_mfma_f32_16x16x32_bf16 v[140:143], v[100:103], v[194:197], v[140:143]
	v_mfma_f32_16x16x32_bf16 v[136:139], v[108:111], v[194:197], v[136:139]
	v_mfma_f32_16x16x32_bf16 v[20:23], v[100:103], v[202:205], v[20:23]
	v_mfma_f32_16x16x32_bf16 v[28:31], v[108:111], v[202:205], v[28:31]
	v_mfma_f32_16x16x32_bf16 v[4:7], v[100:103], v[210:213], v[4:7]
	v_mfma_f32_16x16x32_bf16 v[12:15], v[108:111], v[210:213], v[12:15]
	s_setprio 0
	s_setprio 1
	v_mfma_f32_16x16x32_bf16 v[148:151], v[112:115], v[182:185], 0
	v_mfma_f32_16x16x32_bf16 v[144:147], v[120:123], v[182:185], 0
	v_mfma_f32_16x16x32_bf16 v[132:135], v[112:115], v[190:193], 0
	v_mfma_f32_16x16x32_bf16 v[128:131], v[120:123], v[190:193], 0
	v_mfma_f32_16x16x32_bf16 v[16:19], v[112:115], v[198:201], 0
	v_mfma_f32_16x16x32_bf16 v[24:27], v[120:123], v[198:201], 0
	v_mfma_f32_16x16x32_bf16 v[0:3], v[112:115], v[206:209], 0
	v_mfma_f32_16x16x32_bf16 v[8:11], v[120:123], v[206:209], 0
	v_mfma_f32_16x16x32_bf16 v[148:151], v[116:119], v[186:189], v[148:151]
	v_mfma_f32_16x16x32_bf16 v[144:147], v[124:127], v[186:189], v[144:147]
	v_mfma_f32_16x16x32_bf16 v[132:135], v[116:119], v[194:197], v[132:135]
	v_mfma_f32_16x16x32_bf16 v[128:131], v[124:127], v[194:197], v[128:131]
	v_mfma_f32_16x16x32_bf16 v[16:19], v[116:119], v[202:205], v[16:19]
	v_mfma_f32_16x16x32_bf16 v[24:27], v[124:127], v[202:205], v[24:27]
	v_mfma_f32_16x16x32_bf16 v[0:3], v[116:119], v[210:213], v[0:3]
	v_mfma_f32_16x16x32_bf16 v[8:11], v[124:127], v[210:213], v[8:11]
	s_setprio 0
	s_barrier
	s_add_i32 s28, s17, s35
	v_lshl_add_u64 v[214:215], s[42:43], 0, v[162:163]
	s_mov_b32 m0, s28
	ds_read_b128 v[182:185], v252 offset:16384
	ds_read_b128 v[186:189], v252 offset:17408
	ds_read_b128 v[190:193], v252 offset:18432
	ds_read_b128 v[194:197], v252 offset:19456
	ds_read_b128 v[198:201], v252 offset:20480
	ds_read_b128 v[202:205], v252 offset:21504
	ds_read_b128 v[206:209], v252 offset:22528
	ds_read_b128 v[210:213], v252 offset:23552
	global_load_lds_dwordx4 v[214:215], off
	s_add_i32 m0, s28, 0x2000
	v_lshl_add_u64 v[216:217], s[42:43], 0, v[166:167]
	s_add_u32 s42, s42, s10
	s_addc_u32 s43, s43, s11
	s_add_i32 s28, s30, s35
	global_load_lds_dwordx4 v[216:217], off
	v_lshl_add_u64 v[218:219], s[42:43], 0, v[162:163]
	s_mov_b32 m0, s28
	v_lshl_add_u64 v[220:221], s[42:43], 0, v[166:167]
	global_load_lds_dwordx4 v[218:219], off
	s_add_i32 m0, s28, 0x2000
	v_lshl_add_u64 v[222:223], s[62:63], 0, v[160:161]
	global_load_lds_dwordx4 v[220:221], off
	s_mov_b32 m0, s57
	v_lshl_add_u64 v[224:225], s[62:63], 0, v[164:165]
	global_load_lds_dwordx4 v[222:223], off
	s_mov_b32 m0, s84
	s_nop 0
	global_load_lds_dwordx4 v[224:225], off
	s_waitcnt vmcnt(8)
	s_waitcnt lgkmcnt(0)
	s_barrier
; #define PG8_STAGE(bufoff, gbase, voff) do { _Pragma("unroll") for (int _i = 0; _i < 2; ++_i) \
;         __builtin_amdgcn_global_load_lds((const unsigned*)((const char*)(gbase) + (voff)[_i]), (PG8_LAS unsigned*)(lds + (bufoff) + ldsw + _i * 8192), 16, 0, 0); } while (0)
; #define PG8_LDA(dst, b, h) do { _Pragma("unroll") for (int m = 0; m < 4; ++m) _Pragma("unroll") for (int k = 0; k < 2; ++k) dst[m][k] = *(const PG8_LAS bf16x8*)(lds + PG8_SA(b, h) + aoff + m * 2048 + k * 1024); } while (0)
; #define PG8_LDB(dst, b, h) do { _Pragma("unroll") for (int n = 0; n < 2; ++n) _Pragma("unroll") for (int k = 0; k < 2; ++k) dst[n][k] = *(const PG8_LAS bf16x8*)(lds + PG8_SB(b, h) + boff + n * 2048 + k * 1024); } while (0)
; #define PG8_MMA(ai, bj, At, Bt) do { __builtin_amdgcn_s_setprio(1); _Pragma("unroll") for (int m = 0; m < 4; ++m) _Pragma("unroll") for (int n = 0; n < 2; ++n) _Pragma("unroll") for (int k = 0; k < 2; ++k) \
;         acc[ai][bj][m][n] = __builtin_amdgcn_mfma_f32_16x16x32_bf16(Bt[n][k], At[m][k], acc[ai][bj][m][n], 0, 0, 0); __builtin_amdgcn_s_setprio(0); } while (0)
; #define PG8_WAIT_V(n) asm volatile("s_waitcnt vmcnt(" #n ")" ::: "memory")
; #define PG8_WAIT_L(n) asm volatile("s_waitcnt lgkmcnt(" #n ")" ::: "memory")
; #define PG8_BAR __builtin_amdgcn_s_barrier()
; #define PG8_SCHED __builtin_amdgcn_sched_barrier(0)
; template <class Epi, class Sched, bool ALIGN_EPI = false, bool SP2 = false>
; __device__ __forceinline__ void gemm_phase(PG8_LAS unsigned char* lds, const Gemm g, const Sched& S, const Epi& E, const int wave_in) {
;     ...
;             PG8_WAIT_V(8); PG8_WAIT_L(0); PG8_BAR; PG8_MMA(1, 0, At, B0); PG8_MMA(1, 1, At, B1); PG8_BAR; PG8_SCHED;
;             PG8_LDB(B0, 1, 0); PG8_LDB(B1, 1, 1); PG8_SCHED; PG8_LDA(At, 1, 0); PG8_STAGE(PG8_SA(0, 1), a2 + hstep, voffA);
;             PG8_WAIT_V(8); PG8_WAIT_L(0); PG8_BAR; PG8_MMA(0, 0, At, B0); PG8_MMA(0, 1, At, B1); PG8_BAR; PG8_SCHED;
	s_setprio 1
	s_waitcnt lgkmcnt(0)
	v_mfma_f32_16x16x32_bf16 v[92:95], v[96:99], v[182:185], 0
	v_mfma_f32_16x16x32_bf16 v[88:91], v[104:107], v[182:185], 0
	v_mfma_f32_16x16x32_bf16 v[76:79], v[96:99], v[190:193], 0
	v_mfma_f32_16x16x32_bf16 v[72:75], v[104:107], v[190:193], 0
	v_mfma_f32_16x16x32_bf16 v[48:51], v[96:99], v[198:201], 0
	v_mfma_f32_16x16x32_bf16 v[52:55], v[104:107], v[198:201], 0
	v_mfma_f32_16x16x32_bf16 v[32:35], v[96:99], v[206:209], 0
	v_mfma_f32_16x16x32_bf16 v[36:39], v[104:107], v[206:209], 0
	v_mfma_f32_16x16x32_bf16 v[92:95], v[100:103], v[186:189], v[92:95]
	v_mfma_f32_16x16x32_bf16 v[88:91], v[108:111], v[186:189], v[88:91]
	v_mfma_f32_16x16x32_bf16 v[76:79], v[100:103], v[194:197], v[76:79]
	v_mfma_f32_16x16x32_bf16 v[72:75], v[108:111], v[194:197], v[72:75]
	v_mfma_f32_16x16x32_bf16 v[48:51], v[100:103], v[202:205], v[48:51]
	v_mfma_f32_16x16x32_bf16 v[52:55], v[108:111], v[202:205], v[52:55]
	v_mfma_f32_16x16x32_bf16 v[32:35], v[100:103], v[210:213], v[32:35]
	v_mfma_f32_16x16x32_bf16 v[36:39], v[108:111], v[210:213], v[36:39]
	s_setprio 0
	s_setprio 1
	v_mfma_f32_16x16x32_bf16 v[84:87], v[112:115], v[182:185], 0
	v_mfma_f32_16x16x32_bf16 v[80:83], v[120:123], v[182:185], 0
	v_mfma_f32_16x16x32_bf16 v[68:71], v[112:115], v[190:193], 0
	v_mfma_f32_16x16x32_bf16 v[64:67], v[120:123], v[190:193], 0
	v_mfma_f32_16x16x32_bf16 v[56:59], v[112:115], v[198:201], 0
	v_mfma_f32_16x16x32_bf16 v[60:63], v[120:123], v[198:201], 0
	v_mfma_f32_16x16x32_bf16 v[40:43], v[112:115], v[206:209], 0
	v_mfma_f32_16x16x32_bf16 v[44:47], v[120:123], v[206:209], 0
	v_mfma_f32_16x16x32_bf16 v[84:87], v[116:119], v[186:189], v[84:87]
	v_mfma_f32_16x16x32_bf16 v[80:83], v[124:127], v[186:189], v[80:83]
	v_mfma_f32_16x16x32_bf16 v[68:71], v[116:119], v[194:197], v[68:71]
	v_mfma_f32_16x16x32_bf16 v[64:67], v[124:127], v[194:197], v[64:67]
	v_mfma_f32_16x16x32_bf16 v[56:59], v[116:119], v[202:205], v[56:59]
	v_mfma_f32_16x16x32_bf16 v[60:63], v[124:127], v[202:205], v[60:63]
	v_mfma_f32_16x16x32_bf16 v[40:43], v[116:119], v[210:213], v[40:43]
	v_mfma_f32_16x16x32_bf16 v[44:47], v[124:127], v[210:213], v[44:47]
	s_setprio 0
	s_barrier
	s_add_i32 s28, 0, 0x18000
	s_add_i32 s44, 0, 0x1c000
	v_add_u32_e32 v108, s28, v249
	v_add_u32_e32 v124, s44, v249
	ds_read_b128 v[96:99], v108
	ds_read_b128 v[100:103], v108 offset:1024
	ds_read_b128 v[104:107], v108 offset:2048
	ds_read_b128 v[108:111], v108 offset:3072
	ds_read_b128 v[112:115], v124
	ds_read_b128 v[116:119], v124 offset:1024
	ds_read_b128 v[120:123], v124 offset:2048
	ds_read_b128 v[124:127], v124 offset:3072
	s_add_u32 s42, s62, s10
	s_addc_u32 s43, s63, s11
	s_mov_b32 m0, s85
	v_lshl_add_u64 v[226:227], s[42:43], 0, v[160:161]
	ds_read_b128 v[182:185], v252 offset:32768
	ds_read_b128 v[186:189], v252 offset:33792
	ds_read_b128 v[190:193], v252 offset:34816
	ds_read_b128 v[194:197], v252 offset:35840
	ds_read_b128 v[198:201], v252 offset:36864
	ds_read_b128 v[202:205], v252 offset:37888
	ds_read_b128 v[206:209], v252 offset:38912
	ds_read_b128 v[210:213], v252 offset:39936
	global_load_lds_dwordx4 v[226:227], off
	v_lshl_add_u64 v[226:227], s[42:43], 0, v[164:165]
	s_mov_b32 m0, s86
	s_nop 0
	global_load_lds_dwordx4 v[226:227], off
	s_waitcnt vmcnt(8)
	s_waitcnt lgkmcnt(0)
	s_barrier
	s_setprio 1
	s_waitcnt lgkmcnt(0)
	v_mfma_f32_16x16x32_bf16 v[156:159], v[96:99], v[182:185], v[156:159]
	v_mfma_f32_16x16x32_bf16 v[152:155], v[104:107], v[182:185], v[152:155]
	v_mfma_f32_16x16x32_bf16 v[140:143], v[96:99], v[190:193], v[140:143]
	v_mfma_f32_16x16x32_bf16 v[136:139], v[104:107], v[190:193], v[136:139]
	v_mfma_f32_16x16x32_bf16 v[20:23], v[96:99], v[198:201], v[20:23]
	v_mfma_f32_16x16x32_bf16 v[28:31], v[104:107], v[198:201], v[28:31]
	v_mfma_f32_16x16x32_bf16 v[4:7], v[96:99], v[206:209], v[4:7]
	v_mfma_f32_16x16x32_bf16 v[12:15], v[104:107], v[206:209], v[12:15]
	v_mfma_f32_16x16x32_bf16 v[156:159], v[100:103], v[186:189], v[156:159]
	v_mfma_f32_16x16x32_bf16 v[152:155], v[108:111], v[186:189], v[152:155]
	v_mfma_f32_16x16x32_bf16 v[140:143], v[100:103], v[194:197], v[140:143]
	v_mfma_f32_16x16x32_bf16 v[136:139], v[108:111], v[194:197], v[136:139]
	v_mfma_f32_16x16x32_bf16 v[20:23], v[100:103], v[202:205], v[20:23]
	v_mfma_f32_16x16x32_bf16 v[28:31], v[108:111], v[202:205], v[28:31]
	v_mfma_f32_16x16x32_bf16 v[4:7], v[100:103], v[210:213], v[4:7]
	v_mfma_f32_16x16x32_bf16 v[12:15], v[108:111], v[210:213], v[12:15]
	s_setprio 0
	s_setprio 1
	v_mfma_f32_16x16x32_bf16 v[148:151], v[112:115], v[182:185], v[148:151]
	v_mfma_f32_16x16x32_bf16 v[144:147], v[120:123], v[182:185], v[144:147]
	v_mfma_f32_16x16x32_bf16 v[132:135], v[112:115], v[190:193], v[132:135]
	v_mfma_f32_16x16x32_bf16 v[128:131], v[120:123], v[190:193], v[128:131]
	v_mfma_f32_16x16x32_bf16 v[16:19], v[112:115], v[198:201], v[16:19]
	v_mfma_f32_16x16x32_bf16 v[24:27], v[120:123], v[198:201], v[24:27]
	v_mfma_f32_16x16x32_bf16 v[0:3], v[112:115], v[206:209], v[0:3]
	v_mfma_f32_16x16x32_bf16 v[8:11], v[120:123], v[206:209], v[8:11]
	v_mfma_f32_16x16x32_bf16 v[148:151], v[116:119], v[186:189], v[148:151]
	v_mfma_f32_16x16x32_bf16 v[144:147], v[124:127], v[186:189], v[144:147]
	v_mfma_f32_16x16x32_bf16 v[132:135], v[116:119], v[194:197], v[132:135]
	v_mfma_f32_16x16x32_bf16 v[128:131], v[124:127], v[194:197], v[128:131]
	v_mfma_f32_16x16x32_bf16 v[16:19], v[116:119], v[202:205], v[16:19]
	v_mfma_f32_16x16x32_bf16 v[24:27], v[124:127], v[202:205], v[24:27]
	v_mfma_f32_16x16x32_bf16 v[0:3], v[116:119], v[210:213], v[0:3]
	v_mfma_f32_16x16x32_bf16 v[8:11], v[124:127], v[210:213], v[8:11]
	s_setprio 0
	s_barrier
; #define PG8_STAGE(bufoff, gbase, voff) do { _Pragma("unroll") for (int _i = 0; _i < 2; ++_i) \
;         __builtin_amdgcn_global_load_lds((const unsigned*)((const char*)(gbase) + (voff)[_i]), (PG8_LAS unsigned*)(lds + (bufoff) + ldsw + _i * 8192), 16, 0, 0); } while (0)
; #define PG8_LDA(dst, b, h) do { _Pragma("unroll") for (int m = 0; m < 4; ++m) _Pragma("unroll") for (int k = 0; k < 2; ++k) dst[m][k] = *(const PG8_LAS bf16x8*)(lds + PG8_SA(b, h) + aoff + m * 2048 + k * 1024); } while (0)
; #define PG8_LDB(dst, b, h) do { _Pragma("unroll") for (int n = 0; n < 2; ++n) _Pragma("unroll") for (int k = 0; k < 2; ++k) dst[n][k] = *(const PG8_LAS bf16x8*)(lds + PG8_SB(b, h) + boff + n * 2048 + k * 1024); } while (0)
; #define PG8_MMA(ai, bj, At, Bt) do { __builtin_amdgcn_s_setprio(1); _Pragma("unroll") for (int m = 0; m < 4; ++m) _Pragma("unroll") for (int n = 0; n < 2; ++n) _Pragma("unroll") for (int k = 0; k < 2; ++k) \
;         acc[ai][bj][m][n] = __builtin_amdgcn_mfma_f32_16x16x32_bf16(Bt[n][k], At[m][k], acc[ai][bj][m][n], 0, 0, 0); __builtin_amdgcn_s_setprio(0); } while (0)
; #define PG8_WAIT_V(n) asm volatile("s_waitcnt vmcnt(" #n ")" ::: "memory")
; #define PG8_WAIT_L(n) asm volatile("s_waitcnt lgkmcnt(" #n ")" ::: "memory")
; #define PG8_BAR __builtin_amdgcn_s_barrier()
; #define PG8_SCHED __builtin_amdgcn_sched_barrier(0)
; template <class Epi, class Sched, bool ALIGN_EPI = false, bool SP2 = false>
; __device__ __forceinline__ void gemm_phase(PG8_LAS unsigned char* lds, const Gemm g, const Sched& S, const Epi& E, const int wave_in) {
;     ...
;             PG8_LDB(B0, 0, 0); PG8_LDB(B1, 0, 1); PG8_SCHED; PG8_LDA(At, 0, 0); PG8_STAGE(PG8_SA(1, 1), a1 + hstep, voffA);
;             PG8_WAIT_V(8); PG8_WAIT_L(0); PG8_BAR; PG8_MMA(0, 0, At, B0); PG8_MMA(0, 1, At, B1); PG8_BAR; PG8_SCHED;
;     ...
;             PG8_LDA(At, 1, 1); PG8_STAGE(PG8_SB(1, 0), b3, voffB); PG8_STAGE(PG8_SB(1, 1), b3 + hstep, voffB); PG8_STAGE(PG8_SA(1, 0), a3, voffA);
;             PG8_WAIT_V(8); PG8_WAIT_L(0); PG8_BAR; PG8_MMA(1, 0, At, B0); PG8_MMA(1, 1, At, B1); PG8_BAR; PG8_SCHED;
	s_add_i32 s28, s28, s35
	v_lshl_add_u64 v[214:215], v[214:215], 0, s[24:25]
	s_mov_b32 m0, s28
	ds_read_b128 v[182:185], v252 offset:49152
	ds_read_b128 v[186:189], v252 offset:50176
	ds_read_b128 v[190:193], v252 offset:51200
	ds_read_b128 v[194:197], v252 offset:52224
	ds_read_b128 v[198:201], v252 offset:53248
	ds_read_b128 v[202:205], v252 offset:54272
	ds_read_b128 v[206:209], v252 offset:55296
	ds_read_b128 v[210:213], v252 offset:56320
	global_load_lds_dwordx4 v[214:215], off
	v_lshl_add_u64 v[214:215], v[216:217], 0, s[24:25]
	s_add_i32 m0, s28, 0x2000
	s_add_i32 s28, s44, s35
	global_load_lds_dwordx4 v[214:215], off
	v_lshl_add_u64 v[214:215], v[218:219], 0, s[24:25]
	s_mov_b32 m0, s28
	s_nop 0
	global_load_lds_dwordx4 v[214:215], off
	v_lshl_add_u64 v[214:215], v[220:221], 0, s[24:25]
	s_add_i32 m0, s28, 0x2000
	s_nop 0
	global_load_lds_dwordx4 v[214:215], off
	v_lshl_add_u64 v[214:215], v[222:223], 0, s[24:25]
	s_mov_b32 m0, s87
	s_nop 0
	global_load_lds_dwordx4 v[214:215], off
	v_lshl_add_u64 v[214:215], v[224:225], 0, s[24:25]
	s_mov_b32 m0, s92
	s_nop 0
	global_load_lds_dwordx4 v[214:215], off
	s_waitcnt vmcnt(8)
	s_waitcnt lgkmcnt(0)
	s_barrier
	s_setprio 1
	s_waitcnt lgkmcnt(0)
	v_mfma_f32_16x16x32_bf16 v[92:95], v[96:99], v[182:185], v[92:95]
	v_mfma_f32_16x16x32_bf16 v[88:91], v[104:107], v[182:185], v[88:91]
	v_mfma_f32_16x16x32_bf16 v[76:79], v[96:99], v[190:193], v[76:79]
	v_mfma_f32_16x16x32_bf16 v[72:75], v[104:107], v[190:193], v[72:75]
	v_mfma_f32_16x16x32_bf16 v[48:51], v[96:99], v[198:201], v[48:51]
	v_mfma_f32_16x16x32_bf16 v[52:55], v[104:107], v[198:201], v[52:55]
	v_mfma_f32_16x16x32_bf16 v[32:35], v[96:99], v[206:209], v[32:35]
	v_mfma_f32_16x16x32_bf16 v[36:39], v[104:107], v[206:209], v[36:39]
	v_mfma_f32_16x16x32_bf16 v[92:95], v[100:103], v[186:189], v[92:95]
	v_mfma_f32_16x16x32_bf16 v[88:91], v[108:111], v[186:189], v[88:91]
	v_mfma_f32_16x16x32_bf16 v[76:79], v[100:103], v[194:197], v[76:79]
	v_mfma_f32_16x16x32_bf16 v[72:75], v[108:111], v[194:197], v[72:75]
	v_mfma_f32_16x16x32_bf16 v[48:51], v[100:103], v[202:205], v[48:51]
	v_mfma_f32_16x16x32_bf16 v[52:55], v[108:111], v[202:205], v[52:55]
	v_mfma_f32_16x16x32_bf16 v[32:35], v[100:103], v[210:213], v[32:35]
	v_mfma_f32_16x16x32_bf16 v[36:39], v[108:111], v[210:213], v[36:39]
	s_setprio 0
	s_setprio 1
	v_mfma_f32_16x16x32_bf16 v[84:87], v[112:115], v[182:185], v[84:87]
	v_mfma_f32_16x16x32_bf16 v[80:83], v[120:123], v[182:185], v[80:83]
	v_mfma_f32_16x16x32_bf16 v[68:71], v[112:115], v[190:193], v[68:71]
	v_mfma_f32_16x16x32_bf16 v[64:67], v[120:123], v[190:193], v[64:67]
	v_mfma_f32_16x16x32_bf16 v[56:59], v[112:115], v[198:201], v[56:59]
	v_mfma_f32_16x16x32_bf16 v[60:63], v[120:123], v[198:201], v[60:63]
	v_mfma_f32_16x16x32_bf16 v[40:43], v[112:115], v[206:209], v[40:43]
	v_mfma_f32_16x16x32_bf16 v[44:47], v[120:123], v[206:209], v[44:47]
	v_mfma_f32_16x16x32_bf16 v[84:87], v[116:119], v[186:189], v[84:87]
	v_mfma_f32_16x16x32_bf16 v[80:83], v[124:127], v[186:189], v[80:83]
	v_mfma_f32_16x16x32_bf16 v[68:71], v[116:119], v[194:197], v[68:71]
	v_mfma_f32_16x16x32_bf16 v[64:67], v[124:127], v[194:197], v[64:67]
	v_mfma_f32_16x16x32_bf16 v[56:59], v[116:119], v[202:205], v[56:59]
	v_mfma_f32_16x16x32_bf16 v[60:63], v[124:127], v[202:205], v[60:63]
	v_mfma_f32_16x16x32_bf16 v[40:43], v[116:119], v[210:213], v[40:43]
	v_mfma_f32_16x16x32_bf16 v[44:47], v[124:127], v[210:213], v[44:47]
	s_setprio 0
	s_barrier
	s_add_u32 s8, s8, 0x100
	s_addc_u32 s9, s9, 0
	s_add_u32 s46, s46, 0x100
	s_addc_u32 s64, s64, 0
	s_cmp_ge_i32 s29, s93
	s_mov_b32 s28, s29
	s_cbranch_scc1 .Lkz_exit_4
.LBB0_1364:
	ds_read_b128 v[96:99], v250
	ds_read_b128 v[100:103], v250 offset:1024
	ds_read_b128 v[104:107], v250 offset:2048
	ds_read_b128 v[108:111], v250 offset:3072
	ds_read_b128 v[112:115], v251
	ds_read_b128 v[116:119], v251 offset:1024
	ds_read_b128 v[120:123], v251 offset:2048
	ds_read_b128 v[124:127], v251 offset:3072
	s_add_i32 s29, s28, 2
	s_add_u32 s42, s8, 0x80
	s_addc_u32 s43, s9, 0
	s_cmp_eq_u32 s96, s28
	s_cselect_b32 s63, s59, s43
	s_cselect_b32 s62, s58, s42
	s_cselect_b32 s43, s61, s64
	s_cselect_b32 s42, s60, s46
	v_lshl_add_u64 v[214:215], s[8:9], 0, v[174:175]
	s_add_i32 m0, s57, 0xc000
	ds_read_b128 v[182:185], v252
	ds_read_b128 v[186:189], v252 offset:1024
	ds_read_b128 v[190:193], v252 offset:2048
	ds_read_b128 v[194:197], v252 offset:3072
	ds_read_b128 v[198:201], v252 offset:4096
	ds_read_b128 v[202:205], v252 offset:5120
	ds_read_b128 v[206:209], v252 offset:6144
	ds_read_b128 v[210:213], v252 offset:7168
	global_load_lds_dwordx4 v[214:215], off
	v_lshl_add_u64 v[214:215], s[8:9], 0, v[176:177]
	s_add_i32 m0, s57, 0xe000
	s_nop 0
	global_load_lds_dwordx4 v[214:215], off
	s_waitcnt vmcnt(8)
	s_waitcnt lgkmcnt(0)
	s_barrier
; #define PG8_STAGE(bufoff, gbase, voff) do { _Pragma("unroll") for (int _i = 0; _i < 2; ++_i) \
;         __builtin_amdgcn_global_load_lds((const unsigned*)((const char*)(gbase) + (voff)[_i]), (PG8_LAS unsigned*)(lds + (bufoff) + ldsw + _i * 8192), 16, 0, 0); } while (0)
; #define PG8_LDA(dst, b, h) do { _Pragma("unroll") for (int m = 0; m < 4; ++m) _Pragma("unroll") for (int k = 0; k < 2; ++k) dst[m][k] = *(const PG8_LAS bf16x8*)(lds + PG8_SA(b, h) + aoff + m * 2048 + k * 1024); } while (0)
; #define PG8_MMA(ai, bj, At, Bt) do { __builtin_amdgcn_s_setprio(1); _Pragma("unroll") for (int m = 0; m < 4; ++m) _Pragma("unroll") for (int n = 0; n < 2; ++n) _Pragma("unroll") for (int k = 0; k < 2; ++k) \
;         acc[ai][bj][m][n] = __builtin_amdgcn_mfma_f32_16x16x32_bf16(Bt[n][k], At[m][k], acc[ai][bj][m][n], 0, 0, 0); __builtin_amdgcn_s_setprio(0); } while (0)
; #define PG8_WAIT_V(n) asm volatile("s_waitcnt vmcnt(" #n ")" ::: "memory")
; #define PG8_WAIT_L(n) asm volatile("s_waitcnt lgkmcnt(" #n ")" ::: "memory")
; #define PG8_BAR __builtin_amdgcn_s_barrier()
; #define PG8_SCHED __builtin_amdgcn_sched_barrier(0)
; template <class Epi, class Sched, bool ALIGN_EPI = false, bool SP2 = false>
; __device__ __forceinline__ void gemm_phase(PG8_LAS unsigned char* lds, const Gemm g, const Sched& S, const Epi& E, const int wave_in) {
;     ...
;             PG8_WAIT_V(8); PG8_WAIT_L(0); PG8_BAR; PG8_MMA(0, 0, At, B0); PG8_MMA(0, 1, At, B1); PG8_BAR; PG8_SCHED;
;             PG8_LDA(At, 0, 1); PG8_STAGE(PG8_SB(0, 0), b2, voffB); PG8_STAGE(PG8_SB(0, 1), b2 + hstep, voffB); PG8_STAGE(PG8_SA(0, 0), a2, voffA);
;             PG8_WAIT_V(8); PG8_WAIT_L(0); PG8_BAR; PG8_MMA(1, 0, At, B0); PG8_MMA(1, 1, At, B1); PG8_BAR; PG8_SCHED;
	s_setprio 1
	s_waitcnt lgkmcnt(0)
	v_mfma_f32_16x16x32_bf16 v[156:159], v[96:99], v[182:185], v[156:159]
	v_mfma_f32_16x16x32_bf16 v[152:155], v[104:107], v[182:185], v[152:155]
	v_mfma_f32_16x16x32_bf16 v[140:143], v[96:99], v[190:193], v[140:143]
	v_mfma_f32_16x16x32_bf16 v[136:139], v[104:107], v[190:193], v[136:139]
	v_mfma_f32_16x16x32_bf16 v[20:23], v[96:99], v[198:201], v[20:23]
	v_mfma_f32_16x16x32_bf16 v[28:31], v[104:107], v[198:201], v[28:31]
	v_mfma_f32_16x16x32_bf16 v[4:7], v[96:99], v[206:209], v[4:7]
	v_mfma_f32_16x16x32_bf16 v[12:15], v[104:107], v[206:209], v[12:15]
	v_mfma_f32_16x16x32_bf16 v[156:159], v[100:103], v[186:189], v[156:159]
	v_mfma_f32_16x16x32_bf16 v[152:155], v[108:111], v[186:189], v[152:155]
	v_mfma_f32_16x16x32_bf16 v[140:143], v[100:103], v[194:197], v[140:143]
	v_mfma_f32_16x16x32_bf16 v[136:139], v[108:111], v[194:197], v[136:139]
	v_mfma_f32_16x16x32_bf16 v[20:23], v[100:103], v[202:205], v[20:23]
	v_mfma_f32_16x16x32_bf16 v[28:31], v[108:111], v[202:205], v[28:31]
	v_mfma_f32_16x16x32_bf16 v[4:7], v[100:103], v[210:213], v[4:7]
	v_mfma_f32_16x16x32_bf16 v[12:15], v[108:111], v[210:213], v[12:15]
	s_setprio 0
	s_setprio 1
	v_mfma_f32_16x16x32_bf16 v[148:151], v[112:115], v[182:185], v[148:151]
	v_mfma_f32_16x16x32_bf16 v[144:147], v[120:123], v[182:185], v[144:147]
	v_mfma_f32_16x16x32_bf16 v[132:135], v[112:115], v[190:193], v[132:135]
	v_mfma_f32_16x16x32_bf16 v[128:131], v[120:123], v[190:193], v[128:131]
	v_mfma_f32_16x16x32_bf16 v[16:19], v[112:115], v[198:201], v[16:19]
	v_mfma_f32_16x16x32_bf16 v[24:27], v[120:123], v[198:201], v[24:27]
	v_mfma_f32_16x16x32_bf16 v[0:3], v[112:115], v[206:209], v[0:3]
	v_mfma_f32_16x16x32_bf16 v[8:11], v[120:123], v[206:209], v[8:11]
	v_mfma_f32_16x16x32_bf16 v[148:151], v[116:119], v[186:189], v[148:151]
	v_mfma_f32_16x16x32_bf16 v[144:147], v[124:127], v[186:189], v[144:147]
	v_mfma_f32_16x16x32_bf16 v[132:135], v[116:119], v[194:197], v[132:135]
	v_mfma_f32_16x16x32_bf16 v[128:131], v[124:127], v[194:197], v[128:131]
	v_mfma_f32_16x16x32_bf16 v[16:19], v[116:119], v[202:205], v[16:19]
	v_mfma_f32_16x16x32_bf16 v[24:27], v[124:127], v[202:205], v[24:27]
	v_mfma_f32_16x16x32_bf16 v[0:3], v[116:119], v[210:213], v[0:3]
	v_mfma_f32_16x16x32_bf16 v[8:11], v[124:127], v[210:213], v[8:11]
	s_setprio 0
	s_barrier
	s_add_i32 s28, s17, s35
	v_lshl_add_u64 v[214:215], s[42:43], 0, v[162:163]
	s_mov_b32 m0, s28
	ds_read_b128 v[182:185], v252 offset:16384
	ds_read_b128 v[186:189], v252 offset:17408
	ds_read_b128 v[190:193], v252 offset:18432
	ds_read_b128 v[194:197], v252 offset:19456
	ds_read_b128 v[198:201], v252 offset:20480
	ds_read_b128 v[202:205], v252 offset:21504
	ds_read_b128 v[206:209], v252 offset:22528
	ds_read_b128 v[210:213], v252 offset:23552
	global_load_lds_dwordx4 v[214:215], off
	s_add_i32 m0, s28, 0x2000
	v_lshl_add_u64 v[216:217], s[42:43], 0, v[166:167]
	s_add_u32 s42, s42, s10
	s_addc_u32 s43, s43, s11
	s_add_i32 s28, s30, s35
	global_load_lds_dwordx4 v[216:217], off
	v_lshl_add_u64 v[218:219], s[42:43], 0, v[162:163]
	s_mov_b32 m0, s28
	v_lshl_add_u64 v[220:221], s[42:43], 0, v[166:167]
	global_load_lds_dwordx4 v[218:219], off
	s_add_i32 m0, s28, 0x2000
	v_lshl_add_u64 v[222:223], s[62:63], 0, v[160:161]
	global_load_lds_dwordx4 v[220:221], off
	s_mov_b32 m0, s57
	v_lshl_add_u64 v[224:225], s[62:63], 0, v[164:165]
	global_load_lds_dwordx4 v[222:223], off
	s_mov_b32 m0, s84
	s_nop 0
	global_load_lds_dwordx4 v[224:225], off
	s_waitcnt vmcnt(8)
	s_waitcnt lgkmcnt(0)
	s_barrier
	s_setprio 1
	s_waitcnt lgkmcnt(0)
	v_mfma_f32_16x16x32_bf16 v[92:95], v[96:99], v[182:185], v[92:95]
	v_mfma_f32_16x16x32_bf16 v[88:91], v[104:107], v[182:185], v[88:91]
	v_mfma_f32_16x16x32_bf16 v[76:79], v[96:99], v[190:193], v[76:79]
	v_mfma_f32_16x16x32_bf16 v[72:75], v[104:107], v[190:193], v[72:75]
	v_mfma_f32_16x16x32_bf16 v[48:51], v[96:99], v[198:201], v[48:51]
	v_mfma_f32_16x16x32_bf16 v[52:55], v[104:107], v[198:201], v[52:55]
	v_mfma_f32_16x16x32_bf16 v[32:35], v[96:99], v[206:209], v[32:35]
	v_mfma_f32_16x16x32_bf16 v[36:39], v[104:107], v[206:209], v[36:39]
	v_mfma_f32_16x16x32_bf16 v[92:95], v[100:103], v[186:189], v[92:95]
	v_mfma_f32_16x16x32_bf16 v[88:91], v[108:111], v[186:189], v[88:91]
	v_mfma_f32_16x16x32_bf16 v[76:79], v[100:103], v[194:197], v[76:79]
	v_mfma_f32_16x16x32_bf16 v[72:75], v[108:111], v[194:197], v[72:75]
	v_mfma_f32_16x16x32_bf16 v[48:51], v[100:103], v[202:205], v[48:51]
	v_mfma_f32_16x16x32_bf16 v[52:55], v[108:111], v[202:205], v[52:55]
	v_mfma_f32_16x16x32_bf16 v[32:35], v[100:103], v[210:213], v[32:35]
	v_mfma_f32_16x16x32_bf16 v[36:39], v[108:111], v[210:213], v[36:39]
	s_setprio 0
	s_setprio 1
	v_mfma_f32_16x16x32_bf16 v[84:87], v[112:115], v[182:185], v[84:87]
	v_mfma_f32_16x16x32_bf16 v[80:83], v[120:123], v[182:185], v[80:83]
	v_mfma_f32_16x16x32_bf16 v[68:71], v[112:115], v[190:193], v[68:71]
	v_mfma_f32_16x16x32_bf16 v[64:67], v[120:123], v[190:193], v[64:67]
	v_mfma_f32_16x16x32_bf16 v[56:59], v[112:115], v[198:201], v[56:59]
	v_mfma_f32_16x16x32_bf16 v[60:63], v[120:123], v[198:201], v[60:63]
	v_mfma_f32_16x16x32_bf16 v[40:43], v[112:115], v[206:209], v[40:43]
	v_mfma_f32_16x16x32_bf16 v[44:47], v[120:123], v[206:209], v[44:47]
	v_mfma_f32_16x16x32_bf16 v[84:87], v[116:119], v[186:189], v[84:87]
	v_mfma_f32_16x16x32_bf16 v[80:83], v[124:127], v[186:189], v[80:83]
	v_mfma_f32_16x16x32_bf16 v[68:71], v[116:119], v[194:197], v[68:71]
	v_mfma_f32_16x16x32_bf16 v[64:67], v[124:127], v[194:197], v[64:67]
	v_mfma_f32_16x16x32_bf16 v[56:59], v[116:119], v[202:205], v[56:59]
	v_mfma_f32_16x16x32_bf16 v[60:63], v[124:127], v[202:205], v[60:63]
	v_mfma_f32_16x16x32_bf16 v[40:43], v[116:119], v[210:213], v[40:43]
	v_mfma_f32_16x16x32_bf16 v[44:47], v[124:127], v[210:213], v[44:47]
	s_setprio 0
	s_barrier
; #define PG8_STAGE(bufoff, gbase, voff) do { _Pragma("unroll") for (int _i = 0; _i < 2; ++_i) \
;         __builtin_amdgcn_global_load_lds((const unsigned*)((const char*)(gbase) + (voff)[_i]), (PG8_LAS unsigned*)(lds + (bufoff) + ldsw + _i * 8192), 16, 0, 0); } while (0)
; #define PG8_LDA(dst, b, h) do { _Pragma("unroll") for (int m = 0; m < 4; ++m) _Pragma("unroll") for (int k = 0; k < 2; ++k) dst[m][k] = *(const PG8_LAS bf16x8*)(lds + PG8_SA(b, h) + aoff + m * 2048 + k * 1024); } while (0)
; #define PG8_LDB(dst, b, h) do { _Pragma("unroll") for (int n = 0; n < 2; ++n) _Pragma("unroll") for (int k = 0; k < 2; ++k) dst[n][k] = *(const PG8_LAS bf16x8*)(lds + PG8_SB(b, h) + boff + n * 2048 + k * 1024); } while (0)
; #define PG8_MMA(ai, bj, At, Bt) do { __builtin_amdgcn_s_setprio(1); _Pragma("unroll") for (int m = 0; m < 4; ++m) _Pragma("unroll") for (int n = 0; n < 2; ++n) _Pragma("unroll") for (int k = 0; k < 2; ++k) \
;         acc[ai][bj][m][n] = __builtin_amdgcn_mfma_f32_16x16x32_bf16(Bt[n][k], At[m][k], acc[ai][bj][m][n], 0, 0, 0); __builtin_amdgcn_s_setprio(0); } while (0)
; #define PG8_WAIT_V(n) asm volatile("s_waitcnt vmcnt(" #n ")" ::: "memory")
; #define PG8_WAIT_L(n) asm volatile("s_waitcnt lgkmcnt(" #n ")" ::: "memory")
; #define PG8_BAR __builtin_amdgcn_s_barrier()
; #define PG8_SCHED __builtin_amdgcn_sched_barrier(0)
; template <class Epi, class Sched, bool ALIGN_EPI = false, bool SP2 = false>
; __device__ __forceinline__ void gemm_phase(PG8_LAS unsigned char* lds, const Gemm g, const Sched& S, const Epi& E, const int wave_in) {
;     ...
;             PG8_LDB(B0, 1, 0); PG8_LDB(B1, 1, 1); PG8_SCHED; PG8_LDA(At, 1, 0); PG8_STAGE(PG8_SA(0, 1), a2 + hstep, voffA);
;             PG8_WAIT_V(8); PG8_WAIT_L(0); PG8_BAR; PG8_MMA(0, 0, At, B0); PG8_MMA(0, 1, At, B1); PG8_BAR; PG8_SCHED;
;             PG8_LDA(At, 1, 1); PG8_STAGE(PG8_SB(1, 0), b3, voffB); PG8_STAGE(PG8_SB(1, 1), b3 + hstep, voffB); PG8_STAGE(PG8_SA(1, 0), a3, voffA);
	s_add_i32 s28, 0, 0x18000
	s_add_i32 s44, 0, 0x1c000
	v_add_u32_e32 v108, s28, v249
	v_add_u32_e32 v124, s44, v249
	ds_read_b128 v[96:99], v108
	ds_read_b128 v[100:103], v108 offset:1024
	ds_read_b128 v[104:107], v108 offset:2048
	ds_read_b128 v[108:111], v108 offset:3072
	ds_read_b128 v[112:115], v124
	ds_read_b128 v[116:119], v124 offset:1024
	ds_read_b128 v[120:123], v124 offset:2048
	ds_read_b128 v[124:127], v124 offset:3072
	s_add_u32 s42, s62, s10
	s_addc_u32 s43, s63, s11
	s_mov_b32 m0, s85
	v_lshl_add_u64 v[226:227], s[42:43], 0, v[160:161]
	ds_read_b128 v[182:185], v252 offset:32768
	ds_read_b128 v[186:189], v252 offset:33792
	ds_read_b128 v[190:193], v252 offset:34816
	ds_read_b128 v[194:197], v252 offset:35840
	ds_read_b128 v[198:201], v252 offset:36864
	ds_read_b128 v[202:205], v252 offset:37888
	ds_read_b128 v[206:209], v252 offset:38912
	ds_read_b128 v[210:213], v252 offset:39936
	global_load_lds_dwordx4 v[226:227], off
	v_lshl_add_u64 v[226:227], s[42:43], 0, v[164:165]
	s_mov_b32 m0, s86
	s_nop 0
	global_load_lds_dwordx4 v[226:227], off
	s_waitcnt vmcnt(8)
	s_waitcnt lgkmcnt(0)
	s_barrier
	s_setprio 1
	s_waitcnt lgkmcnt(0)
	v_mfma_f32_16x16x32_bf16 v[156:159], v[96:99], v[182:185], v[156:159]
	v_mfma_f32_16x16x32_bf16 v[152:155], v[104:107], v[182:185], v[152:155]
	v_mfma_f32_16x16x32_bf16 v[140:143], v[96:99], v[190:193], v[140:143]
	v_mfma_f32_16x16x32_bf16 v[136:139], v[104:107], v[190:193], v[136:139]
	v_mfma_f32_16x16x32_bf16 v[20:23], v[96:99], v[198:201], v[20:23]
	v_mfma_f32_16x16x32_bf16 v[28:31], v[104:107], v[198:201], v[28:31]
	v_mfma_f32_16x16x32_bf16 v[4:7], v[96:99], v[206:209], v[4:7]
	v_mfma_f32_16x16x32_bf16 v[12:15], v[104:107], v[206:209], v[12:15]
	v_mfma_f32_16x16x32_bf16 v[156:159], v[100:103], v[186:189], v[156:159]
	v_mfma_f32_16x16x32_bf16 v[152:155], v[108:111], v[186:189], v[152:155]
	v_mfma_f32_16x16x32_bf16 v[140:143], v[100:103], v[194:197], v[140:143]
	v_mfma_f32_16x16x32_bf16 v[136:139], v[108:111], v[194:197], v[136:139]
	v_mfma_f32_16x16x32_bf16 v[20:23], v[100:103], v[202:205], v[20:23]
	v_mfma_f32_16x16x32_bf16 v[28:31], v[108:111], v[202:205], v[28:31]
	v_mfma_f32_16x16x32_bf16 v[4:7], v[100:103], v[210:213], v[4:7]
	v_mfma_f32_16x16x32_bf16 v[12:15], v[108:111], v[210:213], v[12:15]
	s_setprio 0
	s_setprio 1
	v_mfma_f32_16x16x32_bf16 v[148:151], v[112:115], v[182:185], v[148:151]
	v_mfma_f32_16x16x32_bf16 v[144:147], v[120:123], v[182:185], v[144:147]
	v_mfma_f32_16x16x32_bf16 v[132:135], v[112:115], v[190:193], v[132:135]
	v_mfma_f32_16x16x32_bf16 v[128:131], v[120:123], v[190:193], v[128:131]
	v_mfma_f32_16x16x32_bf16 v[16:19], v[112:115], v[198:201], v[16:19]
	v_mfma_f32_16x16x32_bf16 v[24:27], v[120:123], v[198:201], v[24:27]
	v_mfma_f32_16x16x32_bf16 v[0:3], v[112:115], v[206:209], v[0:3]
	v_mfma_f32_16x16x32_bf16 v[8:11], v[120:123], v[206:209], v[8:11]
	v_mfma_f32_16x16x32_bf16 v[148:151], v[116:119], v[186:189], v[148:151]
	v_mfma_f32_16x16x32_bf16 v[144:147], v[124:127], v[186:189], v[144:147]
	v_mfma_f32_16x16x32_bf16 v[132:135], v[116:119], v[194:197], v[132:135]
	v_mfma_f32_16x16x32_bf16 v[128:131], v[124:127], v[194:197], v[128:131]
	v_mfma_f32_16x16x32_bf16 v[16:19], v[116:119], v[202:205], v[16:19]
	v_mfma_f32_16x16x32_bf16 v[24:27], v[124:127], v[202:205], v[24:27]
	v_mfma_f32_16x16x32_bf16 v[0:3], v[116:119], v[210:213], v[0:3]
	v_mfma_f32_16x16x32_bf16 v[8:11], v[124:127], v[210:213], v[8:11]
	s_setprio 0
	s_barrier
	s_add_i32 s28, s28, s35
	v_lshl_add_u64 v[214:215], v[214:215], 0, s[24:25]
	s_mov_b32 m0, s28
	ds_read_b128 v[182:185], v252 offset:49152
	ds_read_b128 v[186:189], v252 offset:50176
	ds_read_b128 v[190:193], v252 offset:51200
	ds_read_b128 v[194:197], v252 offset:52224
	ds_read_b128 v[198:201], v252 offset:53248
	ds_read_b128 v[202:205], v252 offset:54272
	ds_read_b128 v[206:209], v252 offset:55296
	ds_read_b128 v[210:213], v252 offset:56320
	global_load_lds_dwordx4 v[214:215], off
	v_lshl_add_u64 v[214:215], v[216:217], 0, s[24:25]
	s_add_i32 m0, s28, 0x2000
	s_add_i32 s28, s44, s35
	global_load_lds_dwordx4 v[214:215], off
	v_lshl_add_u64 v[214:215], v[218:219], 0, s[24:25]
	s_mov_b32 m0, s28
	s_nop 0
	global_load_lds_dwordx4 v[214:215], off
	v_lshl_add_u64 v[214:215], v[220:221], 0, s[24:25]
	s_add_i32 m0, s28, 0x2000
	s_nop 0
	global_load_lds_dwordx4 v[214:215], off
	v_lshl_add_u64 v[214:215], v[222:223], 0, s[24:25]
	s_mov_b32 m0, s87
	s_nop 0
	global_load_lds_dwordx4 v[214:215], off
	v_lshl_add_u64 v[214:215], v[224:225], 0, s[24:25]
	s_mov_b32 m0, s92
	s_nop 0
	global_load_lds_dwordx4 v[214:215], off
	s_waitcnt vmcnt(8)
	s_waitcnt lgkmcnt(0)
	s_barrier
; #define PG8_STAGE(bufoff, gbase, voff) do { _Pragma("unroll") for (int _i = 0; _i < 2; ++_i) \
;         __builtin_amdgcn_global_load_lds((const unsigned*)((const char*)(gbase) + (voff)[_i]), (PG8_LAS unsigned*)(lds + (bufoff) + ldsw + _i * 8192), 16, 0, 0); } while (0)
; #define PG8_LDA(dst, b, h) do { _Pragma("unroll") for (int m = 0; m < 4; ++m) _Pragma("unroll") for (int k = 0; k < 2; ++k) dst[m][k] = *(const PG8_LAS bf16x8*)(lds + PG8_SA(b, h) + aoff + m * 2048 + k * 1024); } while (0)
; #define PG8_MMA(ai, bj, At, Bt) do { __builtin_amdgcn_s_setprio(1); _Pragma("unroll") for (int m = 0; m < 4; ++m) _Pragma("unroll") for (int n = 0; n < 2; ++n) _Pragma("unroll") for (int k = 0; k < 2; ++k) \
;         acc[ai][bj][m][n] = __builtin_amdgcn_mfma_f32_16x16x32_bf16(Bt[n][k], At[m][k], acc[ai][bj][m][n], 0, 0, 0); __builtin_amdgcn_s_setprio(0); } while (0)
; #define PG8_WAIT_V(n) asm volatile("s_waitcnt vmcnt(" #n ")" ::: "memory")
; #define PG8_WAIT_L(n) asm volatile("s_waitcnt lgkmcnt(" #n ")" ::: "memory")
; #define PG8_BAR __builtin_amdgcn_s_barrier()
; #define PG8_SCHED __builtin_amdgcn_sched_barrier(0)
; template <class Epi, class Sched, bool ALIGN_EPI = false, bool SP2 = false>
; __device__ __forceinline__ void gemm_phase(PG8_LAS unsigned char* lds, const Gemm g, const Sched& S, const Epi& E, const int wave_in) {
;     ...
;             PG8_LDA(At, 1, 1); PG8_STAGE(PG8_SB(1, 0), b3, voffB); PG8_STAGE(PG8_SB(1, 1), b3 + hstep, voffB); PG8_STAGE(PG8_SA(1, 0), a3, voffA);
;             PG8_WAIT_V(8); PG8_WAIT_L(0); PG8_BAR; PG8_MMA(1, 0, At, B0); PG8_MMA(1, 1, At, B1); PG8_BAR; PG8_SCHED;
;     ...
; #pragma unroll
;         for (int a = 0; a < 2; ++a)
; #pragma unroll
;             for (int b = 0; b < 2; ++b)
; #pragma unroll
;                 for (int m = 0; m < 4; ++m)
; #pragma unroll
;                     for (int n = 0; n < 2; ++n) acc[a][b][m][n] = (f32x4){0.f, 0.f, 0.f, 0.f};
	s_setprio 1
	s_waitcnt lgkmcnt(0)
	v_mfma_f32_16x16x32_bf16 v[92:95], v[96:99], v[182:185], v[92:95]
	v_mfma_f32_16x16x32_bf16 v[88:91], v[104:107], v[182:185], v[88:91]
	v_mfma_f32_16x16x32_bf16 v[76:79], v[96:99], v[190:193], v[76:79]
	v_mfma_f32_16x16x32_bf16 v[72:75], v[104:107], v[190:193], v[72:75]
	v_mfma_f32_16x16x32_bf16 v[48:51], v[96:99], v[198:201], v[48:51]
	v_mfma_f32_16x16x32_bf16 v[52:55], v[104:107], v[198:201], v[52:55]
	v_mfma_f32_16x16x32_bf16 v[32:35], v[96:99], v[206:209], v[32:35]
	v_mfma_f32_16x16x32_bf16 v[36:39], v[104:107], v[206:209], v[36:39]
	v_mfma_f32_16x16x32_bf16 v[92:95], v[100:103], v[186:189], v[92:95]
	v_mfma_f32_16x16x32_bf16 v[88:91], v[108:111], v[186:189], v[88:91]
	v_mfma_f32_16x16x32_bf16 v[76:79], v[100:103], v[194:197], v[76:79]
	v_mfma_f32_16x16x32_bf16 v[72:75], v[108:111], v[194:197], v[72:75]
	v_mfma_f32_16x16x32_bf16 v[48:51], v[100:103], v[202:205], v[48:51]
	v_mfma_f32_16x16x32_bf16 v[52:55], v[108:111], v[202:205], v[52:55]
	v_mfma_f32_16x16x32_bf16 v[32:35], v[100:103], v[210:213], v[32:35]
	v_mfma_f32_16x16x32_bf16 v[36:39], v[108:111], v[210:213], v[36:39]
	s_setprio 0
	s_setprio 1
	v_mfma_f32_16x16x32_bf16 v[84:87], v[112:115], v[182:185], v[84:87]
	v_mfma_f32_16x16x32_bf16 v[80:83], v[120:123], v[182:185], v[80:83]
	v_mfma_f32_16x16x32_bf16 v[68:71], v[112:115], v[190:193], v[68:71]
	v_mfma_f32_16x16x32_bf16 v[64:67], v[120:123], v[190:193], v[64:67]
	v_mfma_f32_16x16x32_bf16 v[56:59], v[112:115], v[198:201], v[56:59]
	v_mfma_f32_16x16x32_bf16 v[60:63], v[120:123], v[198:201], v[60:63]
	v_mfma_f32_16x16x32_bf16 v[40:43], v[112:115], v[206:209], v[40:43]
	v_mfma_f32_16x16x32_bf16 v[44:47], v[120:123], v[206:209], v[44:47]
	v_mfma_f32_16x16x32_bf16 v[84:87], v[116:119], v[186:189], v[84:87]
	v_mfma_f32_16x16x32_bf16 v[80:83], v[124:127], v[186:189], v[80:83]
	v_mfma_f32_16x16x32_bf16 v[68:71], v[116:119], v[194:197], v[68:71]
	v_mfma_f32_16x16x32_bf16 v[64:67], v[124:127], v[194:197], v[64:67]
	v_mfma_f32_16x16x32_bf16 v[56:59], v[116:119], v[202:205], v[56:59]
	v_mfma_f32_16x16x32_bf16 v[60:63], v[124:127], v[202:205], v[60:63]
	v_mfma_f32_16x16x32_bf16 v[40:43], v[116:119], v[210:213], v[40:43]
	v_mfma_f32_16x16x32_bf16 v[44:47], v[124:127], v[210:213], v[44:47]
	s_setprio 0
	s_barrier
	s_add_u32 s8, s8, 0x100
	s_addc_u32 s9, s9, 0
	s_add_u32 s46, s46, 0x100
	s_addc_u32 s64, s64, 0
	s_cmp_ge_i32 s29, s93
	s_mov_b32 s28, s29
	s_cbranch_scc0 .LBB0_1364
.Lkz_exit_4:
	s_branch .LBB0_1365
.Lkz_skip_4:
	v_mov_b32_e32 v159, 0
	v_mov_b32_e32 v158, v159
	v_mov_b32_e32 v157, v159
	v_mov_b32_e32 v156, v159
	v_mov_b32_e32 v155, v159
	v_mov_b32_e32 v154, v159
	v_mov_b32_e32 v153, v159
	v_mov_b32_e32 v152, v159
	v_mov_b32_e32 v143, v159
	v_mov_b32_e32 v142, v159
	v_mov_b32_e32 v141, v159
	v_mov_b32_e32 v140, v159
	v_mov_b32_e32 v139, v159
	v_mov_b32_e32 v138, v159
	v_mov_b32_e32 v137, v159
	v_mov_b32_e32 v136, v159
	v_mov_b32_e32 v23, v159
	v_mov_b32_e32 v22, v159
	v_mov_b32_e32 v21, v159
	v_mov_b32_e32 v20, v159
	v_mov_b32_e32 v31, v159
	v_mov_b32_e32 v30, v159
	v_mov_b32_e32 v29, v159
	v_mov_b32_e32 v28, v159
	v_mov_b32_e32 v7, v159
	v_mov_b32_e32 v6, v159
	v_mov_b32_e32 v5, v159
	v_mov_b32_e32 v4, v159
	v_mov_b32_e32 v15, v159
	v_mov_b32_e32 v14, v159
	v_mov_b32_e32 v13, v159
	v_mov_b32_e32 v12, v159
	v_mov_b32_e32 v151, v159
	v_mov_b32_e32 v150, v159
	v_mov_b32_e32 v149, v159
	v_mov_b32_e32 v148, v159
	v_mov_b32_e32 v147, v159
	v_mov_b32_e32 v146, v159
	v_mov_b32_e32 v145, v159
	v_mov_b32_e32 v144, v159
	v_mov_b32_e32 v135, v159
	v_mov_b32_e32 v134, v159
	v_mov_b32_e32 v133, v159
	v_mov_b32_e32 v132, v159
	v_mov_b32_e32 v131, v159
	v_mov_b32_e32 v130, v159
	v_mov_b32_e32 v129, v159
	v_mov_b32_e32 v128, v159
	v_mov_b32_e32 v19, v159
	v_mov_b32_e32 v18, v159
	v_mov_b32_e32 v17, v159
	v_mov_b32_e32 v16, v159
	v_mov_b32_e32 v27, v159
	v_mov_b32_e32 v26, v159
	v_mov_b32_e32 v25, v159
	v_mov_b32_e32 v24, v159
	v_mov_b32_e32 v3, v159
	v_mov_b32_e32 v2, v159
	v_mov_b32_e32 v1, v159
	v_mov_b32_e32 v0, v159
	v_mov_b32_e32 v11, v159
	v_mov_b32_e32 v10, v159
	v_mov_b32_e32 v9, v159
	v_mov_b32_e32 v8, v159
	v_mov_b32_e32 v95, v159
	v_mov_b32_e32 v94, v159
	v_mov_b32_e32 v93, v159
	v_mov_b32_e32 v92, v159
	v_mov_b32_e32 v91, v159
	v_mov_b32_e32 v90, v159
	v_mov_b32_e32 v89, v159
	v_mov_b32_e32 v88, v159
	v_mov_b32_e32 v79, v159
	v_mov_b32_e32 v78, v159
	v_mov_b32_e32 v77, v159
	v_mov_b32_e32 v76, v159
	v_mov_b32_e32 v75, v159
	v_mov_b32_e32 v74, v159
	v_mov_b32_e32 v73, v159
	v_mov_b32_e32 v72, v159
	v_mov_b32_e32 v51, v159
	v_mov_b32_e32 v50, v159
	v_mov_b32_e32 v49, v159
	v_mov_b32_e32 v48, v159
	v_mov_b32_e32 v55, v159
	v_mov_b32_e32 v54, v159
	v_mov_b32_e32 v53, v159
	v_mov_b32_e32 v52, v159
	v_mov_b32_e32 v35, v159
	v_mov_b32_e32 v34, v159
	v_mov_b32_e32 v33, v159
	v_mov_b32_e32 v32, v159
	v_mov_b32_e32 v39, v159
	v_mov_b32_e32 v38, v159
	v_mov_b32_e32 v37, v159
	v_mov_b32_e32 v36, v159
	v_mov_b32_e32 v87, v159
	v_mov_b32_e32 v86, v159
	v_mov_b32_e32 v85, v159
	v_mov_b32_e32 v84, v159
	v_mov_b32_e32 v83, v159
	v_mov_b32_e32 v82, v159
	v_mov_b32_e32 v81, v159
	v_mov_b32_e32 v80, v159
	v_mov_b32_e32 v71, v159
	v_mov_b32_e32 v70, v159
	v_mov_b32_e32 v69, v159
	v_mov_b32_e32 v68, v159
	v_mov_b32_e32 v67, v159
	v_mov_b32_e32 v66, v159
	v_mov_b32_e32 v65, v159
	v_mov_b32_e32 v64, v159
	v_mov_b32_e32 v59, v159
	v_mov_b32_e32 v58, v159
	v_mov_b32_e32 v57, v159
	v_mov_b32_e32 v56, v159
	v_mov_b32_e32 v63, v159
	v_mov_b32_e32 v62, v159
	v_mov_b32_e32 v61, v159
	v_mov_b32_e32 v60, v159
	v_mov_b32_e32 v43, v159
	v_mov_b32_e32 v42, v159
	v_mov_b32_e32 v41, v159
	v_mov_b32_e32 v40, v159
	v_mov_b32_e32 v47, v159
	v_mov_b32_e32 v46, v159
	v_mov_b32_e32 v45, v159
	v_mov_b32_e32 v44, v159

; #define PG8_STAGE(bufoff, gbase, voff) do { _Pragma("unroll") for (int _i = 0; _i < 2; ++_i) \
;         __builtin_amdgcn_global_load_lds((const unsigned*)((const char*)(gbase) + (voff)[_i]), (PG8_LAS unsigned*)(lds + (bufoff) + ldsw + _i * 8192), 16, 0, 0); } while (0)
; #define PG8_LDA(dst, b, h) do { _Pragma("unroll") for (int m = 0; m < 4; ++m) _Pragma("unroll") for (int k = 0; k < 2; ++k) dst[m][k] = *(const PG8_LAS bf16x8*)(lds + PG8_SA(b, h) + aoff + m * 2048 + k * 1024); } while (0)
; #define PG8_LDB(dst, b, h) do { _Pragma("unroll") for (int n = 0; n < 2; ++n) _Pragma("unroll") for (int k = 0; k < 2; ++k) dst[n][k] = *(const PG8_LAS bf16x8*)(lds + PG8_SB(b, h) + boff + n * 2048 + k * 1024); } while (0)
; #define PG8_MMA(ai, bj, At, Bt) do { __builtin_amdgcn_s_setprio(1); _Pragma("unroll") for (int m = 0; m < 4; ++m) _Pragma("unroll") for (int n = 0; n < 2; ++n) _Pragma("unroll") for (int k = 0; k < 2; ++k) \
;         acc[ai][bj][m][n] = __builtin_amdgcn_mfma_f32_16x16x32_bf16(Bt[n][k], At[m][k], acc[ai][bj][m][n], 0, 0, 0); __builtin_amdgcn_s_setprio(0); } while (0)
; template <class Epi, class Sched, bool ALIGN_EPI = false, bool SP2 = false>
; __device__ __forceinline__ void gemm_phase(PG8_LAS unsigned char* lds, const Gemm g, const Sched& S, const Epi& E, const int wave_in) {
;     ...
;         const bool has_next = S.next(ui + 1, nxt);
;         const char* nA = has_next ? (const char*)g.A + (size_t)nxt.pm * tstep : cA; const char* nB = has_next ? (const char*)g.Bt + (size_t)nxt.pn * tstep : cB;
;         for (int t = 0; t < nt; t += 2) {
;             const bool last = (t == nt - 2);
;             const char* a1 = cA + (size_t)(t + 1) * kstep;
;             const char* a2 = last ? nA : cA + (size_t)(t + 2) * kstep; const char* b2 = last ? nB : cB + (size_t)(t + 2) * kstep;
;             const char* a3 = a2 + kstep; const char* b3 = b2 + kstep;
;             if (last && has_next) S.a_ready(nxt);
;             if constexpr (SP2) {
;             PG8_LDB(B0, 0, 0); PG8_LDB(B1, 0, 1); PG8_SCHED; PG8_LDA(At, 0, 0); PG8_STAGE(PG8_SA(1, 1), a1 + hstep, voffA);
;             PG8_WAIT_V(8); PG8_WAIT_L(0); PG8_BAR; PG8_MMA(0, 0, At, B0); PG8_MMA(0, 1, At, B1); PG8_BAR; PG8_SCHED;
;             PG8_LDA(At, 0, 1); PG8_STAGE(PG8_SB(0, 0), b2, voffB); PG8_STAGE(PG8_SB(0, 1), b2 + hstep, voffB); PG8_STAGE(PG8_SA(0, 0), a2, voffA);
.LBB0_1619:
	s_andn2_b64 vcc, exec, s[22:23]
	s_waitcnt vmcnt(0)
	s_cbranch_vccnz .Lkz_skip_5
	s_add_u32 s40, s40, 0x80
	s_addc_u32 s41, s41, 0
	s_add_u32 s60, s46, 0x100
	s_addc_u32 s61, s47, 0
	s_mov_b32 s28, 0
	ds_read_b128 v[96:99], v183
	ds_read_b128 v[100:103], v183 offset:1024
	ds_read_b128 v[104:107], v183 offset:2048
	ds_read_b128 v[108:111], v183 offset:3072
	ds_read_b128 v[112:115], v184
	ds_read_b128 v[116:119], v184 offset:1024
	ds_read_b128 v[120:123], v184 offset:2048
	ds_read_b128 v[124:127], v184 offset:3072
	s_add_i32 s29, s28, 2
	s_add_u32 s42, s40, 0x80
	s_addc_u32 s43, s41, 0
	s_cmp_eq_u32 s51, s28
	s_cselect_b32 s47, s3, s43
	s_cselect_b32 s46, s2, s42
	s_cselect_b32 s43, s39, s61
	s_cselect_b32 s42, s38, s60
	v_lshl_add_u64 v[214:215], s[40:41], 0, v[168:169]
	s_add_i32 m0, s31, 0xc000
	ds_read_b128 v[176:179], v185
	ds_read_b128 v[186:189], v185 offset:1024
	ds_read_b128 v[190:193], v185 offset:2048
	ds_read_b128 v[194:197], v185 offset:3072
	ds_read_b128 v[198:201], v185 offset:4096
	ds_read_b128 v[202:205], v185 offset:5120
	ds_read_b128 v[206:209], v185 offset:6144
	ds_read_b128 v[210:213], v185 offset:7168
	global_load_lds_dwordx4 v[214:215], off
	v_lshl_add_u64 v[214:215], s[40:41], 0, v[170:171]
	s_add_i32 m0, s31, 0xe000
	s_nop 0
	global_load_lds_dwordx4 v[214:215], off
	s_waitcnt vmcnt(8)
	s_waitcnt lgkmcnt(0)
	s_barrier
	s_setprio 1
	s_waitcnt lgkmcnt(0)
	v_mfma_f32_16x16x32_bf16 v[152:155], v[96:99], v[176:179], 0
	v_mfma_f32_16x16x32_bf16 v[156:159], v[104:107], v[176:179], 0
	v_mfma_f32_16x16x32_bf16 v[140:143], v[96:99], v[190:193], 0
	v_mfma_f32_16x16x32_bf16 v[136:139], v[104:107], v[190:193], 0
	v_mfma_f32_16x16x32_bf16 v[92:95], v[96:99], v[198:201], 0
	v_mfma_f32_16x16x32_bf16 v[88:91], v[104:107], v[198:201], 0
	v_mfma_f32_16x16x32_bf16 v[76:79], v[96:99], v[206:209], 0
	v_mfma_f32_16x16x32_bf16 v[72:75], v[104:107], v[206:209], 0
	v_mfma_f32_16x16x32_bf16 v[152:155], v[100:103], v[186:189], v[152:155]
	v_mfma_f32_16x16x32_bf16 v[156:159], v[108:111], v[186:189], v[156:159]
	v_mfma_f32_16x16x32_bf16 v[140:143], v[100:103], v[194:197], v[140:143]
	v_mfma_f32_16x16x32_bf16 v[136:139], v[108:111], v[194:197], v[136:139]
	v_mfma_f32_16x16x32_bf16 v[92:95], v[100:103], v[202:205], v[92:95]
	v_mfma_f32_16x16x32_bf16 v[88:91], v[108:111], v[202:205], v[88:91]
	v_mfma_f32_16x16x32_bf16 v[76:79], v[100:103], v[210:213], v[76:79]
	v_mfma_f32_16x16x32_bf16 v[72:75], v[108:111], v[210:213], v[72:75]
	s_setprio 0
	s_setprio 1
	v_mfma_f32_16x16x32_bf16 v[148:151], v[112:115], v[176:179], 0
	v_mfma_f32_16x16x32_bf16 v[144:147], v[120:123], v[176:179], 0
	v_mfma_f32_16x16x32_bf16 v[132:135], v[112:115], v[190:193], 0
	v_mfma_f32_16x16x32_bf16 v[128:131], v[120:123], v[190:193], 0
	v_mfma_f32_16x16x32_bf16 v[84:87], v[112:115], v[198:201], 0
	v_mfma_f32_16x16x32_bf16 v[80:83], v[120:123], v[198:201], 0
	v_mfma_f32_16x16x32_bf16 v[68:71], v[112:115], v[206:209], 0
	v_mfma_f32_16x16x32_bf16 v[64:67], v[120:123], v[206:209], 0
	v_mfma_f32_16x16x32_bf16 v[148:151], v[116:119], v[186:189], v[148:151]
	v_mfma_f32_16x16x32_bf16 v[144:147], v[124:127], v[186:189], v[144:147]
	v_mfma_f32_16x16x32_bf16 v[132:135], v[116:119], v[194:197], v[132:135]
	v_mfma_f32_16x16x32_bf16 v[128:131], v[124:127], v[194:197], v[128:131]
	v_mfma_f32_16x16x32_bf16 v[84:87], v[116:119], v[202:205], v[84:87]
	v_mfma_f32_16x16x32_bf16 v[80:83], v[124:127], v[202:205], v[80:83]
	v_mfma_f32_16x16x32_bf16 v[68:71], v[116:119], v[210:213], v[68:71]
	v_mfma_f32_16x16x32_bf16 v[64:67], v[124:127], v[210:213], v[64:67]
	s_setprio 0
	s_barrier
	s_add_i32 s28, s53, s30
	v_lshl_add_u64 v[214:215], s[42:43], 0, v[162:163]
	s_mov_b32 m0, s28
	ds_read_b128 v[176:179], v185 offset:16384
	ds_read_b128 v[186:189], v185 offset:17408
	ds_read_b128 v[190:193], v185 offset:18432
	ds_read_b128 v[194:197], v185 offset:19456
	ds_read_b128 v[198:201], v185 offset:20480
	ds_read_b128 v[202:205], v185 offset:21504
	ds_read_b128 v[206:209], v185 offset:22528
	ds_read_b128 v[210:213], v185 offset:23552
	global_load_lds_dwordx4 v[214:215], off
	s_add_i32 m0, s28, 0x2000
	v_lshl_add_u64 v[216:217], s[42:43], 0, v[166:167]
	s_add_u32 s42, s42, s14
	s_addc_u32 s43, s43, s15
	s_add_i32 s28, s54, s30
	global_load_lds_dwordx4 v[216:217], off
	v_lshl_add_u64 v[218:219], s[42:43], 0, v[162:163]
	s_mov_b32 m0, s28
	v_lshl_add_u64 v[220:221], s[42:43], 0, v[166:167]
	global_load_lds_dwordx4 v[218:219], off
	s_add_i32 m0, s28, 0x2000
	v_lshl_add_u64 v[222:223], s[46:47], 0, v[160:161]
	global_load_lds_dwordx4 v[220:221], off
	s_mov_b32 m0, s31
	v_lshl_add_u64 v[224:225], s[46:47], 0, v[164:165]
	global_load_lds_dwordx4 v[222:223], off
	s_mov_b32 m0, s33
	s_nop 0
	global_load_lds_dwordx4 v[224:225], off
	s_waitcnt vmcnt(8)
	s_waitcnt lgkmcnt(0)
	s_barrier
; #define PG8_STAGE(bufoff, gbase, voff) do { _Pragma("unroll") for (int _i = 0; _i < 2; ++_i) \
;         __builtin_amdgcn_global_load_lds((const unsigned*)((const char*)(gbase) + (voff)[_i]), (PG8_LAS unsigned*)(lds + (bufoff) + ldsw + _i * 8192), 16, 0, 0); } while (0)
; #define PG8_LDA(dst, b, h) do { _Pragma("unroll") for (int m = 0; m < 4; ++m) _Pragma("unroll") for (int k = 0; k < 2; ++k) dst[m][k] = *(const PG8_LAS bf16x8*)(lds + PG8_SA(b, h) + aoff + m * 2048 + k * 1024); } while (0)
; #define PG8_LDB(dst, b, h) do { _Pragma("unroll") for (int n = 0; n < 2; ++n) _Pragma("unroll") for (int k = 0; k < 2; ++k) dst[n][k] = *(const PG8_LAS bf16x8*)(lds + PG8_SB(b, h) + boff + n * 2048 + k * 1024); } while (0)
; #define PG8_MMA(ai, bj, At, Bt) do { __builtin_amdgcn_s_setprio(1); _Pragma("unroll") for (int m = 0; m < 4; ++m) _Pragma("unroll") for (int n = 0; n < 2; ++n) _Pragma("unroll") for (int k = 0; k < 2; ++k) \
;         acc[ai][bj][m][n] = __builtin_amdgcn_mfma_f32_16x16x32_bf16(Bt[n][k], At[m][k], acc[ai][bj][m][n], 0, 0, 0); __builtin_amdgcn_s_setprio(0); } while (0)
; #define PG8_WAIT_V(n) asm volatile("s_waitcnt vmcnt(" #n ")" ::: "memory")
; #define PG8_WAIT_L(n) asm volatile("s_waitcnt lgkmcnt(" #n ")" ::: "memory")
; #define PG8_BAR __builtin_amdgcn_s_barrier()
; #define PG8_SCHED __builtin_amdgcn_sched_barrier(0)
; template <class Epi, class Sched, bool ALIGN_EPI = false, bool SP2 = false>
; __device__ __forceinline__ void gemm_phase(PG8_LAS unsigned char* lds, const Gemm g, const Sched& S, const Epi& E, const int wave_in) {
;     ...
;             PG8_WAIT_V(8); PG8_WAIT_L(0); PG8_BAR; PG8_MMA(1, 0, At, B0); PG8_MMA(1, 1, At, B1); PG8_BAR; PG8_SCHED;
;             PG8_LDB(B0, 1, 0); PG8_LDB(B1, 1, 1); PG8_SCHED; PG8_LDA(At, 1, 0); PG8_STAGE(PG8_SA(0, 1), a2 + hstep, voffA);
;             PG8_WAIT_V(8); PG8_WAIT_L(0); PG8_BAR; PG8_MMA(0, 0, At, B0); PG8_MMA(0, 1, At, B1); PG8_BAR; PG8_SCHED;
	s_setprio 1
	s_waitcnt lgkmcnt(0)
	v_mfma_f32_16x16x32_bf16 v[60:63], v[96:99], v[176:179], 0
	v_mfma_f32_16x16x32_bf16 v[56:59], v[104:107], v[176:179], 0
	v_mfma_f32_16x16x32_bf16 v[44:47], v[96:99], v[190:193], 0
	v_mfma_f32_16x16x32_bf16 v[40:43], v[104:107], v[190:193], 0
	v_mfma_f32_16x16x32_bf16 v[28:31], v[96:99], v[198:201], 0
	v_mfma_f32_16x16x32_bf16 v[24:27], v[104:107], v[198:201], 0
	v_mfma_f32_16x16x32_bf16 v[12:15], v[96:99], v[206:209], 0
	v_mfma_f32_16x16x32_bf16 v[8:11], v[104:107], v[206:209], 0
	v_mfma_f32_16x16x32_bf16 v[60:63], v[100:103], v[186:189], v[60:63]
	v_mfma_f32_16x16x32_bf16 v[56:59], v[108:111], v[186:189], v[56:59]
	v_mfma_f32_16x16x32_bf16 v[44:47], v[100:103], v[194:197], v[44:47]
	v_mfma_f32_16x16x32_bf16 v[40:43], v[108:111], v[194:197], v[40:43]
	v_mfma_f32_16x16x32_bf16 v[28:31], v[100:103], v[202:205], v[28:31]
	v_mfma_f32_16x16x32_bf16 v[24:27], v[108:111], v[202:205], v[24:27]
	v_mfma_f32_16x16x32_bf16 v[12:15], v[100:103], v[210:213], v[12:15]
	v_mfma_f32_16x16x32_bf16 v[8:11], v[108:111], v[210:213], v[8:11]
	s_setprio 0
	s_setprio 1
	v_mfma_f32_16x16x32_bf16 v[52:55], v[112:115], v[176:179], 0
	v_mfma_f32_16x16x32_bf16 v[48:51], v[120:123], v[176:179], 0
	v_mfma_f32_16x16x32_bf16 v[36:39], v[112:115], v[190:193], 0
	v_mfma_f32_16x16x32_bf16 v[32:35], v[120:123], v[190:193], 0
	v_mfma_f32_16x16x32_bf16 v[20:23], v[112:115], v[198:201], 0
	v_mfma_f32_16x16x32_bf16 v[16:19], v[120:123], v[198:201], 0
	v_mfma_f32_16x16x32_bf16 v[4:7], v[112:115], v[206:209], 0
	v_mfma_f32_16x16x32_bf16 v[0:3], v[120:123], v[206:209], 0
	v_mfma_f32_16x16x32_bf16 v[52:55], v[116:119], v[186:189], v[52:55]
	v_mfma_f32_16x16x32_bf16 v[48:51], v[124:127], v[186:189], v[48:51]
	v_mfma_f32_16x16x32_bf16 v[36:39], v[116:119], v[194:197], v[36:39]
	v_mfma_f32_16x16x32_bf16 v[32:35], v[124:127], v[194:197], v[32:35]
	v_mfma_f32_16x16x32_bf16 v[20:23], v[116:119], v[202:205], v[20:23]
	v_mfma_f32_16x16x32_bf16 v[16:19], v[124:127], v[202:205], v[16:19]
	v_mfma_f32_16x16x32_bf16 v[4:7], v[116:119], v[210:213], v[4:7]
	v_mfma_f32_16x16x32_bf16 v[0:3], v[124:127], v[210:213], v[0:3]
	s_setprio 0
	s_barrier
	s_add_i32 s28, 0, 0x18000
	s_add_i32 s44, 0, 0x1c000
	v_add_u32_e32 v108, s28, v181
	v_add_u32_e32 v124, s44, v181
	ds_read_b128 v[96:99], v108
	ds_read_b128 v[100:103], v108 offset:1024
	ds_read_b128 v[104:107], v108 offset:2048
	ds_read_b128 v[108:111], v108 offset:3072
	ds_read_b128 v[112:115], v124
	ds_read_b128 v[116:119], v124 offset:1024
	ds_read_b128 v[120:123], v124 offset:2048
	ds_read_b128 v[124:127], v124 offset:3072
	s_add_u32 s42, s46, s14
	s_addc_u32 s43, s47, s15
	s_mov_b32 m0, s34
	v_lshl_add_u64 v[226:227], s[42:43], 0, v[160:161]
	ds_read_b128 v[176:179], v185 offset:32768
	ds_read_b128 v[186:189], v185 offset:33792
	ds_read_b128 v[190:193], v185 offset:34816
	ds_read_b128 v[194:197], v185 offset:35840
	ds_read_b128 v[198:201], v185 offset:36864
	ds_read_b128 v[202:205], v185 offset:37888
	ds_read_b128 v[206:209], v185 offset:38912
	ds_read_b128 v[210:213], v185 offset:39936
	global_load_lds_dwordx4 v[226:227], off
	v_lshl_add_u64 v[226:227], s[42:43], 0, v[164:165]
	s_mov_b32 m0, s35
	s_nop 0
	global_load_lds_dwordx4 v[226:227], off
	s_waitcnt vmcnt(8)
	s_waitcnt lgkmcnt(0)
	s_barrier
	s_setprio 1
	s_waitcnt lgkmcnt(0)
	v_mfma_f32_16x16x32_bf16 v[152:155], v[96:99], v[176:179], v[152:155]
	v_mfma_f32_16x16x32_bf16 v[156:159], v[104:107], v[176:179], v[156:159]
	v_mfma_f32_16x16x32_bf16 v[140:143], v[96:99], v[190:193], v[140:143]
	v_mfma_f32_16x16x32_bf16 v[136:139], v[104:107], v[190:193], v[136:139]
	v_mfma_f32_16x16x32_bf16 v[92:95], v[96:99], v[198:201], v[92:95]
	v_mfma_f32_16x16x32_bf16 v[88:91], v[104:107], v[198:201], v[88:91]
	v_mfma_f32_16x16x32_bf16 v[76:79], v[96:99], v[206:209], v[76:79]
	v_mfma_f32_16x16x32_bf16 v[72:75], v[104:107], v[206:209], v[72:75]
	v_mfma_f32_16x16x32_bf16 v[152:155], v[100:103], v[186:189], v[152:155]
	v_mfma_f32_16x16x32_bf16 v[156:159], v[108:111], v[186:189], v[156:159]
	v_mfma_f32_16x16x32_bf16 v[140:143], v[100:103], v[194:197], v[140:143]
	v_mfma_f32_16x16x32_bf16 v[136:139], v[108:111], v[194:197], v[136:139]
	v_mfma_f32_16x16x32_bf16 v[92:95], v[100:103], v[202:205], v[92:95]
	v_mfma_f32_16x16x32_bf16 v[88:91], v[108:111], v[202:205], v[88:91]
	v_mfma_f32_16x16x32_bf16 v[76:79], v[100:103], v[210:213], v[76:79]
	v_mfma_f32_16x16x32_bf16 v[72:75], v[108:111], v[210:213], v[72:75]
	s_setprio 0
	s_setprio 1
	v_mfma_f32_16x16x32_bf16 v[148:151], v[112:115], v[176:179], v[148:151]
	v_mfma_f32_16x16x32_bf16 v[144:147], v[120:123], v[176:179], v[144:147]
	v_mfma_f32_16x16x32_bf16 v[132:135], v[112:115], v[190:193], v[132:135]
	v_mfma_f32_16x16x32_bf16 v[128:131], v[120:123], v[190:193], v[128:131]
	v_mfma_f32_16x16x32_bf16 v[84:87], v[112:115], v[198:201], v[84:87]
	v_mfma_f32_16x16x32_bf16 v[80:83], v[120:123], v[198:201], v[80:83]
	v_mfma_f32_16x16x32_bf16 v[68:71], v[112:115], v[206:209], v[68:71]
	v_mfma_f32_16x16x32_bf16 v[64:67], v[120:123], v[206:209], v[64:67]
	v_mfma_f32_16x16x32_bf16 v[148:151], v[116:119], v[186:189], v[148:151]
	v_mfma_f32_16x16x32_bf16 v[144:147], v[124:127], v[186:189], v[144:147]
	v_mfma_f32_16x16x32_bf16 v[132:135], v[116:119], v[194:197], v[132:135]
	v_mfma_f32_16x16x32_bf16 v[128:131], v[124:127], v[194:197], v[128:131]
	v_mfma_f32_16x16x32_bf16 v[84:87], v[116:119], v[202:205], v[84:87]
	v_mfma_f32_16x16x32_bf16 v[80:83], v[124:127], v[202:205], v[80:83]
	v_mfma_f32_16x16x32_bf16 v[68:71], v[116:119], v[210:213], v[68:71]
	v_mfma_f32_16x16x32_bf16 v[64:67], v[124:127], v[210:213], v[64:67]
	s_setprio 0
	s_barrier
; #define PG8_STAGE(bufoff, gbase, voff) do { _Pragma("unroll") for (int _i = 0; _i < 2; ++_i) \
;         __builtin_amdgcn_global_load_lds((const unsigned*)((const char*)(gbase) + (voff)[_i]), (PG8_LAS unsigned*)(lds + (bufoff) + ldsw + _i * 8192), 16, 0, 0); } while (0)
; #define PG8_LDA(dst, b, h) do { _Pragma("unroll") for (int m = 0; m < 4; ++m) _Pragma("unroll") for (int k = 0; k < 2; ++k) dst[m][k] = *(const PG8_LAS bf16x8*)(lds + PG8_SA(b, h) + aoff + m * 2048 + k * 1024); } while (0)
; #define PG8_LDB(dst, b, h) do { _Pragma("unroll") for (int n = 0; n < 2; ++n) _Pragma("unroll") for (int k = 0; k < 2; ++k) dst[n][k] = *(const PG8_LAS bf16x8*)(lds + PG8_SB(b, h) + boff + n * 2048 + k * 1024); } while (0)
; #define PG8_MMA(ai, bj, At, Bt) do { __builtin_amdgcn_s_setprio(1); _Pragma("unroll") for (int m = 0; m < 4; ++m) _Pragma("unroll") for (int n = 0; n < 2; ++n) _Pragma("unroll") for (int k = 0; k < 2; ++k) \
;         acc[ai][bj][m][n] = __builtin_amdgcn_mfma_f32_16x16x32_bf16(Bt[n][k], At[m][k], acc[ai][bj][m][n], 0, 0, 0); __builtin_amdgcn_s_setprio(0); } while (0)
; #define PG8_WAIT_V(n) asm volatile("s_waitcnt vmcnt(" #n ")" ::: "memory")
; #define PG8_WAIT_L(n) asm volatile("s_waitcnt lgkmcnt(" #n ")" ::: "memory")
; #define PG8_BAR __builtin_amdgcn_s_barrier()
; #define PG8_SCHED __builtin_amdgcn_sched_barrier(0)
; template <class Epi, class Sched, bool ALIGN_EPI = false, bool SP2 = false>
; __device__ __forceinline__ void gemm_phase(PG8_LAS unsigned char* lds, const Gemm g, const Sched& S, const Epi& E, const int wave_in) {
;     ...
;             PG8_LDB(B0, 0, 0); PG8_LDB(B1, 0, 1); PG8_SCHED; PG8_LDA(At, 0, 0); PG8_STAGE(PG8_SA(1, 1), a1 + hstep, voffA);
;             PG8_WAIT_V(8); PG8_WAIT_L(0); PG8_BAR; PG8_MMA(0, 0, At, B0); PG8_MMA(0, 1, At, B1); PG8_BAR; PG8_SCHED;
;     ...
;             PG8_LDA(At, 1, 1); PG8_STAGE(PG8_SB(1, 0), b3, voffB); PG8_STAGE(PG8_SB(1, 1), b3 + hstep, voffB); PG8_STAGE(PG8_SA(1, 0), a3, voffA);
;             PG8_WAIT_V(8); PG8_WAIT_L(0); PG8_BAR; PG8_MMA(1, 0, At, B0); PG8_MMA(1, 1, At, B1); PG8_BAR; PG8_SCHED;
	s_add_i32 s28, s28, s30
	v_lshl_add_u64 v[214:215], v[214:215], 0, s[20:21]
	s_mov_b32 m0, s28
	ds_read_b128 v[176:179], v185 offset:49152
	ds_read_b128 v[186:189], v185 offset:50176
	ds_read_b128 v[190:193], v185 offset:51200
	ds_read_b128 v[194:197], v185 offset:52224
	ds_read_b128 v[198:201], v185 offset:53248
	ds_read_b128 v[202:205], v185 offset:54272
	ds_read_b128 v[206:209], v185 offset:55296
	ds_read_b128 v[210:213], v185 offset:56320
	global_load_lds_dwordx4 v[214:215], off
	v_lshl_add_u64 v[214:215], v[216:217], 0, s[20:21]
	s_add_i32 m0, s28, 0x2000
	s_add_i32 s28, s44, s30
	global_load_lds_dwordx4 v[214:215], off
	v_lshl_add_u64 v[214:215], v[218:219], 0, s[20:21]
	s_mov_b32 m0, s28
	s_nop 0
	global_load_lds_dwordx4 v[214:215], off
	v_lshl_add_u64 v[214:215], v[220:221], 0, s[20:21]
	s_add_i32 m0, s28, 0x2000
	s_nop 0
	global_load_lds_dwordx4 v[214:215], off
	v_lshl_add_u64 v[214:215], v[222:223], 0, s[20:21]
	s_mov_b32 m0, s48
	s_nop 0
	global_load_lds_dwordx4 v[214:215], off
	v_lshl_add_u64 v[214:215], v[224:225], 0, s[20:21]
	s_mov_b32 m0, s49
	s_nop 0
	global_load_lds_dwordx4 v[214:215], off
	s_waitcnt vmcnt(8)
	s_waitcnt lgkmcnt(0)
	s_barrier
	s_setprio 1
	s_waitcnt lgkmcnt(0)
	v_mfma_f32_16x16x32_bf16 v[60:63], v[96:99], v[176:179], v[60:63]
	v_mfma_f32_16x16x32_bf16 v[56:59], v[104:107], v[176:179], v[56:59]
	v_mfma_f32_16x16x32_bf16 v[44:47], v[96:99], v[190:193], v[44:47]
	v_mfma_f32_16x16x32_bf16 v[40:43], v[104:107], v[190:193], v[40:43]
	v_mfma_f32_16x16x32_bf16 v[28:31], v[96:99], v[198:201], v[28:31]
	v_mfma_f32_16x16x32_bf16 v[24:27], v[104:107], v[198:201], v[24:27]
	v_mfma_f32_16x16x32_bf16 v[12:15], v[96:99], v[206:209], v[12:15]
	v_mfma_f32_16x16x32_bf16 v[8:11], v[104:107], v[206:209], v[8:11]
	v_mfma_f32_16x16x32_bf16 v[60:63], v[100:103], v[186:189], v[60:63]
	v_mfma_f32_16x16x32_bf16 v[56:59], v[108:111], v[186:189], v[56:59]
	v_mfma_f32_16x16x32_bf16 v[44:47], v[100:103], v[194:197], v[44:47]
	v_mfma_f32_16x16x32_bf16 v[40:43], v[108:111], v[194:197], v[40:43]
	v_mfma_f32_16x16x32_bf16 v[28:31], v[100:103], v[202:205], v[28:31]
	v_mfma_f32_16x16x32_bf16 v[24:27], v[108:111], v[202:205], v[24:27]
	v_mfma_f32_16x16x32_bf16 v[12:15], v[100:103], v[210:213], v[12:15]
	v_mfma_f32_16x16x32_bf16 v[8:11], v[108:111], v[210:213], v[8:11]
	s_setprio 0
	s_setprio 1
	v_mfma_f32_16x16x32_bf16 v[52:55], v[112:115], v[176:179], v[52:55]
	v_mfma_f32_16x16x32_bf16 v[48:51], v[120:123], v[176:179], v[48:51]
	v_mfma_f32_16x16x32_bf16 v[36:39], v[112:115], v[190:193], v[36:39]
	v_mfma_f32_16x16x32_bf16 v[32:35], v[120:123], v[190:193], v[32:35]
	v_mfma_f32_16x16x32_bf16 v[20:23], v[112:115], v[198:201], v[20:23]
	v_mfma_f32_16x16x32_bf16 v[16:19], v[120:123], v[198:201], v[16:19]
	v_mfma_f32_16x16x32_bf16 v[4:7], v[112:115], v[206:209], v[4:7]
	v_mfma_f32_16x16x32_bf16 v[0:3], v[120:123], v[206:209], v[0:3]
	v_mfma_f32_16x16x32_bf16 v[52:55], v[116:119], v[186:189], v[52:55]
	v_mfma_f32_16x16x32_bf16 v[48:51], v[124:127], v[186:189], v[48:51]
	v_mfma_f32_16x16x32_bf16 v[36:39], v[116:119], v[194:197], v[36:39]
	v_mfma_f32_16x16x32_bf16 v[32:35], v[124:127], v[194:197], v[32:35]
	v_mfma_f32_16x16x32_bf16 v[20:23], v[116:119], v[202:205], v[20:23]
	v_mfma_f32_16x16x32_bf16 v[16:19], v[124:127], v[202:205], v[16:19]
	v_mfma_f32_16x16x32_bf16 v[4:7], v[116:119], v[210:213], v[4:7]
	v_mfma_f32_16x16x32_bf16 v[0:3], v[124:127], v[210:213], v[0:3]
	s_setprio 0
	s_barrier
	s_add_u32 s40, s40, 0x100
	s_addc_u32 s41, s41, 0
	s_add_u32 s60, s60, 0x100
	s_addc_u32 s61, s61, 0
	s_cmp_ge_i32 s29, s50
	s_mov_b32 s28, s29
	s_cbranch_scc1 .Lkz_exit_5
.LBB0_1621:
	ds_read_b128 v[96:99], v183
	ds_read_b128 v[100:103], v183 offset:1024
	ds_read_b128 v[104:107], v183 offset:2048
	ds_read_b128 v[108:111], v183 offset:3072
	ds_read_b128 v[112:115], v184
	ds_read_b128 v[116:119], v184 offset:1024
	ds_read_b128 v[120:123], v184 offset:2048
	ds_read_b128 v[124:127], v184 offset:3072
	s_add_i32 s29, s28, 2
	s_add_u32 s42, s40, 0x80
	s_addc_u32 s43, s41, 0
	s_cmp_eq_u32 s51, s28
	s_cselect_b32 s47, s3, s43
	s_cselect_b32 s46, s2, s42
	s_cselect_b32 s43, s39, s61
	s_cselect_b32 s42, s38, s60
	v_lshl_add_u64 v[214:215], s[40:41], 0, v[168:169]
	s_add_i32 m0, s31, 0xc000
	ds_read_b128 v[176:179], v185
	ds_read_b128 v[186:189], v185 offset:1024
	ds_read_b128 v[190:193], v185 offset:2048
	ds_read_b128 v[194:197], v185 offset:3072
	ds_read_b128 v[198:201], v185 offset:4096
	ds_read_b128 v[202:205], v185 offset:5120
	ds_read_b128 v[206:209], v185 offset:6144
	ds_read_b128 v[210:213], v185 offset:7168
	global_load_lds_dwordx4 v[214:215], off
	v_lshl_add_u64 v[214:215], s[40:41], 0, v[170:171]
	s_add_i32 m0, s31, 0xe000
	s_nop 0
	global_load_lds_dwordx4 v[214:215], off
	s_waitcnt vmcnt(8)
	s_waitcnt lgkmcnt(0)
	s_barrier
; #define PG8_STAGE(bufoff, gbase, voff) do { _Pragma("unroll") for (int _i = 0; _i < 2; ++_i) \
;         __builtin_amdgcn_global_load_lds((const unsigned*)((const char*)(gbase) + (voff)[_i]), (PG8_LAS unsigned*)(lds + (bufoff) + ldsw + _i * 8192), 16, 0, 0); } while (0)
; #define PG8_LDA(dst, b, h) do { _Pragma("unroll") for (int m = 0; m < 4; ++m) _Pragma("unroll") for (int k = 0; k < 2; ++k) dst[m][k] = *(const PG8_LAS bf16x8*)(lds + PG8_SA(b, h) + aoff + m * 2048 + k * 1024); } while (0)
; #define PG8_MMA(ai, bj, At, Bt) do { __builtin_amdgcn_s_setprio(1); _Pragma("unroll") for (int m = 0; m < 4; ++m) _Pragma("unroll") for (int n = 0; n < 2; ++n) _Pragma("unroll") for (int k = 0; k < 2; ++k) \
;         acc[ai][bj][m][n] = __builtin_amdgcn_mfma_f32_16x16x32_bf16(Bt[n][k], At[m][k], acc[ai][bj][m][n], 0, 0, 0); __builtin_amdgcn_s_setprio(0); } while (0)
; #define PG8_WAIT_V(n) asm volatile("s_waitcnt vmcnt(" #n ")" ::: "memory")
; #define PG8_WAIT_L(n) asm volatile("s_waitcnt lgkmcnt(" #n ")" ::: "memory")
; #define PG8_BAR __builtin_amdgcn_s_barrier()
; #define PG8_SCHED __builtin_amdgcn_sched_barrier(0)
; template <class Epi, class Sched, bool ALIGN_EPI = false, bool SP2 = false>
; __device__ __forceinline__ void gemm_phase(PG8_LAS unsigned char* lds, const Gemm g, const Sched& S, const Epi& E, const int wave_in) {
;     ...
;             PG8_WAIT_V(8); PG8_WAIT_L(0); PG8_BAR; PG8_MMA(0, 0, At, B0); PG8_MMA(0, 1, At, B1); PG8_BAR; PG8_SCHED;
;             PG8_LDA(At, 0, 1); PG8_STAGE(PG8_SB(0, 0), b2, voffB); PG8_STAGE(PG8_SB(0, 1), b2 + hstep, voffB); PG8_STAGE(PG8_SA(0, 0), a2, voffA);
;             PG8_WAIT_V(8); PG8_WAIT_L(0); PG8_BAR; PG8_MMA(1, 0, At, B0); PG8_MMA(1, 1, At, B1); PG8_BAR; PG8_SCHED;
	s_setprio 1
	s_waitcnt lgkmcnt(0)
	v_mfma_f32_16x16x32_bf16 v[152:155], v[96:99], v[176:179], v[152:155]
	v_mfma_f32_16x16x32_bf16 v[156:159], v[104:107], v[176:179], v[156:159]
	v_mfma_f32_16x16x32_bf16 v[140:143], v[96:99], v[190:193], v[140:143]
	v_mfma_f32_16x16x32_bf16 v[136:139], v[104:107], v[190:193], v[136:139]
	v_mfma_f32_16x16x32_bf16 v[92:95], v[96:99], v[198:201], v[92:95]
	v_mfma_f32_16x16x32_bf16 v[88:91], v[104:107], v[198:201], v[88:91]
	v_mfma_f32_16x16x32_bf16 v[76:79], v[96:99], v[206:209], v[76:79]
	v_mfma_f32_16x16x32_bf16 v[72:75], v[104:107], v[206:209], v[72:75]
	v_mfma_f32_16x16x32_bf16 v[152:155], v[100:103], v[186:189], v[152:155]
	v_mfma_f32_16x16x32_bf16 v[156:159], v[108:111], v[186:189], v[156:159]
	v_mfma_f32_16x16x32_bf16 v[140:143], v[100:103], v[194:197], v[140:143]
	v_mfma_f32_16x16x32_bf16 v[136:139], v[108:111], v[194:197], v[136:139]
	v_mfma_f32_16x16x32_bf16 v[92:95], v[100:103], v[202:205], v[92:95]
	v_mfma_f32_16x16x32_bf16 v[88:91], v[108:111], v[202:205], v[88:91]
	v_mfma_f32_16x16x32_bf16 v[76:79], v[100:103], v[210:213], v[76:79]
	v_mfma_f32_16x16x32_bf16 v[72:75], v[108:111], v[210:213], v[72:75]
	s_setprio 0
	s_setprio 1
	v_mfma_f32_16x16x32_bf16 v[148:151], v[112:115], v[176:179], v[148:151]
	v_mfma_f32_16x16x32_bf16 v[144:147], v[120:123], v[176:179], v[144:147]
	v_mfma_f32_16x16x32_bf16 v[132:135], v[112:115], v[190:193], v[132:135]
	v_mfma_f32_16x16x32_bf16 v[128:131], v[120:123], v[190:193], v[128:131]
	v_mfma_f32_16x16x32_bf16 v[84:87], v[112:115], v[198:201], v[84:87]
	v_mfma_f32_16x16x32_bf16 v[80:83], v[120:123], v[198:201], v[80:83]
	v_mfma_f32_16x16x32_bf16 v[68:71], v[112:115], v[206:209], v[68:71]
	v_mfma_f32_16x16x32_bf16 v[64:67], v[120:123], v[206:209], v[64:67]
	v_mfma_f32_16x16x32_bf16 v[148:151], v[116:119], v[186:189], v[148:151]
	v_mfma_f32_16x16x32_bf16 v[144:147], v[124:127], v[186:189], v[144:147]
	v_mfma_f32_16x16x32_bf16 v[132:135], v[116:119], v[194:197], v[132:135]
	v_mfma_f32_16x16x32_bf16 v[128:131], v[124:127], v[194:197], v[128:131]
	v_mfma_f32_16x16x32_bf16 v[84:87], v[116:119], v[202:205], v[84:87]
	v_mfma_f32_16x16x32_bf16 v[80:83], v[124:127], v[202:205], v[80:83]
	v_mfma_f32_16x16x32_bf16 v[68:71], v[116:119], v[210:213], v[68:71]
	v_mfma_f32_16x16x32_bf16 v[64:67], v[124:127], v[210:213], v[64:67]
	s_setprio 0
	s_barrier
	s_add_i32 s28, s53, s30
	v_lshl_add_u64 v[214:215], s[42:43], 0, v[162:163]
	s_mov_b32 m0, s28
	ds_read_b128 v[176:179], v185 offset:16384
	ds_read_b128 v[186:189], v185 offset:17408
	ds_read_b128 v[190:193], v185 offset:18432
	ds_read_b128 v[194:197], v185 offset:19456
	ds_read_b128 v[198:201], v185 offset:20480
	ds_read_b128 v[202:205], v185 offset:21504
	ds_read_b128 v[206:209], v185 offset:22528
	ds_read_b128 v[210:213], v185 offset:23552
	global_load_lds_dwordx4 v[214:215], off
	s_add_i32 m0, s28, 0x2000
	v_lshl_add_u64 v[216:217], s[42:43], 0, v[166:167]
	s_add_u32 s42, s42, s14
	s_addc_u32 s43, s43, s15
	s_add_i32 s28, s54, s30
	global_load_lds_dwordx4 v[216:217], off
	v_lshl_add_u64 v[218:219], s[42:43], 0, v[162:163]
	s_mov_b32 m0, s28
	v_lshl_add_u64 v[220:221], s[42:43], 0, v[166:167]
	global_load_lds_dwordx4 v[218:219], off
	s_add_i32 m0, s28, 0x2000
	v_lshl_add_u64 v[222:223], s[46:47], 0, v[160:161]
	global_load_lds_dwordx4 v[220:221], off
	s_mov_b32 m0, s31
	v_lshl_add_u64 v[224:225], s[46:47], 0, v[164:165]
	global_load_lds_dwordx4 v[222:223], off
	s_mov_b32 m0, s33
	s_nop 0
	global_load_lds_dwordx4 v[224:225], off
	s_waitcnt vmcnt(8)
	s_waitcnt lgkmcnt(0)
	s_barrier
	s_setprio 1
	s_waitcnt lgkmcnt(0)
	v_mfma_f32_16x16x32_bf16 v[60:63], v[96:99], v[176:179], v[60:63]
	v_mfma_f32_16x16x32_bf16 v[56:59], v[104:107], v[176:179], v[56:59]
	v_mfma_f32_16x16x32_bf16 v[44:47], v[96:99], v[190:193], v[44:47]
	v_mfma_f32_16x16x32_bf16 v[40:43], v[104:107], v[190:193], v[40:43]
	v_mfma_f32_16x16x32_bf16 v[28:31], v[96:99], v[198:201], v[28:31]
	v_mfma_f32_16x16x32_bf16 v[24:27], v[104:107], v[198:201], v[24:27]
	v_mfma_f32_16x16x32_bf16 v[12:15], v[96:99], v[206:209], v[12:15]
	v_mfma_f32_16x16x32_bf16 v[8:11], v[104:107], v[206:209], v[8:11]
	v_mfma_f32_16x16x32_bf16 v[60:63], v[100:103], v[186:189], v[60:63]
	v_mfma_f32_16x16x32_bf16 v[56:59], v[108:111], v[186:189], v[56:59]
	v_mfma_f32_16x16x32_bf16 v[44:47], v[100:103], v[194:197], v[44:47]
	v_mfma_f32_16x16x32_bf16 v[40:43], v[108:111], v[194:197], v[40:43]
	v_mfma_f32_16x16x32_bf16 v[28:31], v[100:103], v[202:205], v[28:31]
	v_mfma_f32_16x16x32_bf16 v[24:27], v[108:111], v[202:205], v[24:27]
	v_mfma_f32_16x16x32_bf16 v[12:15], v[100:103], v[210:213], v[12:15]
	v_mfma_f32_16x16x32_bf16 v[8:11], v[108:111], v[210:213], v[8:11]
	s_setprio 0
	s_setprio 1
	v_mfma_f32_16x16x32_bf16 v[52:55], v[112:115], v[176:179], v[52:55]
	v_mfma_f32_16x16x32_bf16 v[48:51], v[120:123], v[176:179], v[48:51]
	v_mfma_f32_16x16x32_bf16 v[36:39], v[112:115], v[190:193], v[36:39]
	v_mfma_f32_16x16x32_bf16 v[32:35], v[120:123], v[190:193], v[32:35]
	v_mfma_f32_16x16x32_bf16 v[20:23], v[112:115], v[198:201], v[20:23]
	v_mfma_f32_16x16x32_bf16 v[16:19], v[120:123], v[198:201], v[16:19]
	v_mfma_f32_16x16x32_bf16 v[4:7], v[112:115], v[206:209], v[4:7]
	v_mfma_f32_16x16x32_bf16 v[0:3], v[120:123], v[206:209], v[0:3]
	v_mfma_f32_16x16x32_bf16 v[52:55], v[116:119], v[186:189], v[52:55]
	v_mfma_f32_16x16x32_bf16 v[48:51], v[124:127], v[186:189], v[48:51]
	v_mfma_f32_16x16x32_bf16 v[36:39], v[116:119], v[194:197], v[36:39]
	v_mfma_f32_16x16x32_bf16 v[32:35], v[124:127], v[194:197], v[32:35]
	v_mfma_f32_16x16x32_bf16 v[20:23], v[116:119], v[202:205], v[20:23]
	v_mfma_f32_16x16x32_bf16 v[16:19], v[124:127], v[202:205], v[16:19]
	v_mfma_f32_16x16x32_bf16 v[4:7], v[116:119], v[210:213], v[4:7]
	v_mfma_f32_16x16x32_bf16 v[0:3], v[124:127], v[210:213], v[0:3]
	s_setprio 0
	s_barrier
; #define PG8_STAGE(bufoff, gbase, voff) do { _Pragma("unroll") for (int _i = 0; _i < 2; ++_i) \
;         __builtin_amdgcn_global_load_lds((const unsigned*)((const char*)(gbase) + (voff)[_i]), (PG8_LAS unsigned*)(lds + (bufoff) + ldsw + _i * 8192), 16, 0, 0); } while (0)
; #define PG8_LDA(dst, b, h) do { _Pragma("unroll") for (int m = 0; m < 4; ++m) _Pragma("unroll") for (int k = 0; k < 2; ++k) dst[m][k] = *(const PG8_LAS bf16x8*)(lds + PG8_SA(b, h) + aoff + m * 2048 + k * 1024); } while (0)
; #define PG8_LDB(dst, b, h) do { _Pragma("unroll") for (int n = 0; n < 2; ++n) _Pragma("unroll") for (int k = 0; k < 2; ++k) dst[n][k] = *(const PG8_LAS bf16x8*)(lds + PG8_SB(b, h) + boff + n * 2048 + k * 1024); } while (0)
; #define PG8_MMA(ai, bj, At, Bt) do { __builtin_amdgcn_s_setprio(1); _Pragma("unroll") for (int m = 0; m < 4; ++m) _Pragma("unroll") for (int n = 0; n < 2; ++n) _Pragma("unroll") for (int k = 0; k < 2; ++k) \
;         acc[ai][bj][m][n] = __builtin_amdgcn_mfma_f32_16x16x32_bf16(Bt[n][k], At[m][k], acc[ai][bj][m][n], 0, 0, 0); __builtin_amdgcn_s_setprio(0); } while (0)
; #define PG8_WAIT_V(n) asm volatile("s_waitcnt vmcnt(" #n ")" ::: "memory")
; #define PG8_WAIT_L(n) asm volatile("s_waitcnt lgkmcnt(" #n ")" ::: "memory")
; #define PG8_BAR __builtin_amdgcn_s_barrier()
; #define PG8_SCHED __builtin_amdgcn_sched_barrier(0)
; template <class Epi, class Sched, bool ALIGN_EPI = false, bool SP2 = false>
; __device__ __forceinline__ void gemm_phase(PG8_LAS unsigned char* lds, const Gemm g, const Sched& S, const Epi& E, const int wave_in) {
;     ...
;             PG8_LDB(B0, 1, 0); PG8_LDB(B1, 1, 1); PG8_SCHED; PG8_LDA(At, 1, 0); PG8_STAGE(PG8_SA(0, 1), a2 + hstep, voffA);
;             PG8_WAIT_V(8); PG8_WAIT_L(0); PG8_BAR; PG8_MMA(0, 0, At, B0); PG8_MMA(0, 1, At, B1); PG8_BAR; PG8_SCHED;
;             PG8_LDA(At, 1, 1); PG8_STAGE(PG8_SB(1, 0), b3, voffB); PG8_STAGE(PG8_SB(1, 1), b3 + hstep, voffB); PG8_STAGE(PG8_SA(1, 0), a3, voffA);
	s_add_i32 s28, 0, 0x18000
	s_add_i32 s44, 0, 0x1c000
	v_add_u32_e32 v108, s28, v181
	v_add_u32_e32 v124, s44, v181
	ds_read_b128 v[96:99], v108
	ds_read_b128 v[100:103], v108 offset:1024
	ds_read_b128 v[104:107], v108 offset:2048
	ds_read_b128 v[108:111], v108 offset:3072
	ds_read_b128 v[112:115], v124
	ds_read_b128 v[116:119], v124 offset:1024
	ds_read_b128 v[120:123], v124 offset:2048
	ds_read_b128 v[124:127], v124 offset:3072
	s_add_u32 s42, s46, s14
	s_addc_u32 s43, s47, s15
	s_mov_b32 m0, s34
	v_lshl_add_u64 v[226:227], s[42:43], 0, v[160:161]
	ds_read_b128 v[176:179], v185 offset:32768
	ds_read_b128 v[186:189], v185 offset:33792
	ds_read_b128 v[190:193], v185 offset:34816
	ds_read_b128 v[194:197], v185 offset:35840
	ds_read_b128 v[198:201], v185 offset:36864
	ds_read_b128 v[202:205], v185 offset:37888
	ds_read_b128 v[206:209], v185 offset:38912
	ds_read_b128 v[210:213], v185 offset:39936
	global_load_lds_dwordx4 v[226:227], off
	v_lshl_add_u64 v[226:227], s[42:43], 0, v[164:165]
	s_mov_b32 m0, s35
	s_nop 0
	global_load_lds_dwordx4 v[226:227], off
	s_waitcnt vmcnt(8)
	s_waitcnt lgkmcnt(0)
	s_barrier
	s_setprio 1
	s_waitcnt lgkmcnt(0)
	v_mfma_f32_16x16x32_bf16 v[152:155], v[96:99], v[176:179], v[152:155]
	v_mfma_f32_16x16x32_bf16 v[156:159], v[104:107], v[176:179], v[156:159]
	v_mfma_f32_16x16x32_bf16 v[140:143], v[96:99], v[190:193], v[140:143]
	v_mfma_f32_16x16x32_bf16 v[136:139], v[104:107], v[190:193], v[136:139]
	v_mfma_f32_16x16x32_bf16 v[92:95], v[96:99], v[198:201], v[92:95]
	v_mfma_f32_16x16x32_bf16 v[88:91], v[104:107], v[198:201], v[88:91]
	v_mfma_f32_16x16x32_bf16 v[76:79], v[96:99], v[206:209], v[76:79]
	v_mfma_f32_16x16x32_bf16 v[72:75], v[104:107], v[206:209], v[72:75]
	v_mfma_f32_16x16x32_bf16 v[152:155], v[100:103], v[186:189], v[152:155]
	v_mfma_f32_16x16x32_bf16 v[156:159], v[108:111], v[186:189], v[156:159]
	v_mfma_f32_16x16x32_bf16 v[140:143], v[100:103], v[194:197], v[140:143]
	v_mfma_f32_16x16x32_bf16 v[136:139], v[108:111], v[194:197], v[136:139]
	v_mfma_f32_16x16x32_bf16 v[92:95], v[100:103], v[202:205], v[92:95]
	v_mfma_f32_16x16x32_bf16 v[88:91], v[108:111], v[202:205], v[88:91]
	v_mfma_f32_16x16x32_bf16 v[76:79], v[100:103], v[210:213], v[76:79]
	v_mfma_f32_16x16x32_bf16 v[72:75], v[108:111], v[210:213], v[72:75]
	s_setprio 0
	s_setprio 1
	v_mfma_f32_16x16x32_bf16 v[148:151], v[112:115], v[176:179], v[148:151]
	v_mfma_f32_16x16x32_bf16 v[144:147], v[120:123], v[176:179], v[144:147]
	v_mfma_f32_16x16x32_bf16 v[132:135], v[112:115], v[190:193], v[132:135]
	v_mfma_f32_16x16x32_bf16 v[128:131], v[120:123], v[190:193], v[128:131]
	v_mfma_f32_16x16x32_bf16 v[84:87], v[112:115], v[198:201], v[84:87]
	v_mfma_f32_16x16x32_bf16 v[80:83], v[120:123], v[198:201], v[80:83]
	v_mfma_f32_16x16x32_bf16 v[68:71], v[112:115], v[206:209], v[68:71]
	v_mfma_f32_16x16x32_bf16 v[64:67], v[120:123], v[206:209], v[64:67]
	v_mfma_f32_16x16x32_bf16 v[148:151], v[116:119], v[186:189], v[148:151]
	v_mfma_f32_16x16x32_bf16 v[144:147], v[124:127], v[186:189], v[144:147]
	v_mfma_f32_16x16x32_bf16 v[132:135], v[116:119], v[194:197], v[132:135]
	v_mfma_f32_16x16x32_bf16 v[128:131], v[124:127], v[194:197], v[128:131]
	v_mfma_f32_16x16x32_bf16 v[84:87], v[116:119], v[202:205], v[84:87]
	v_mfma_f32_16x16x32_bf16 v[80:83], v[124:127], v[202:205], v[80:83]
	v_mfma_f32_16x16x32_bf16 v[68:71], v[116:119], v[210:213], v[68:71]
	v_mfma_f32_16x16x32_bf16 v[64:67], v[124:127], v[210:213], v[64:67]
	s_setprio 0
	s_barrier
	s_add_i32 s28, s28, s30
	v_lshl_add_u64 v[214:215], v[214:215], 0, s[20:21]
	s_mov_b32 m0, s28
	ds_read_b128 v[176:179], v185 offset:49152
	ds_read_b128 v[186:189], v185 offset:50176
	ds_read_b128 v[190:193], v185 offset:51200
	ds_read_b128 v[194:197], v185 offset:52224
	ds_read_b128 v[198:201], v185 offset:53248
	ds_read_b128 v[202:205], v185 offset:54272
	ds_read_b128 v[206:209], v185 offset:55296
	ds_read_b128 v[210:213], v185 offset:56320
	global_load_lds_dwordx4 v[214:215], off
	v_lshl_add_u64 v[214:215], v[216:217], 0, s[20:21]
	s_add_i32 m0, s28, 0x2000
	s_add_i32 s28, s44, s30
	global_load_lds_dwordx4 v[214:215], off
	v_lshl_add_u64 v[214:215], v[218:219], 0, s[20:21]
	s_mov_b32 m0, s28
	s_nop 0
	global_load_lds_dwordx4 v[214:215], off
	v_lshl_add_u64 v[214:215], v[220:221], 0, s[20:21]
	s_add_i32 m0, s28, 0x2000
	s_nop 0
	global_load_lds_dwordx4 v[214:215], off
	v_lshl_add_u64 v[214:215], v[222:223], 0, s[20:21]
	s_mov_b32 m0, s48
	s_nop 0
	global_load_lds_dwordx4 v[214:215], off
	v_lshl_add_u64 v[214:215], v[224:225], 0, s[20:21]
	s_mov_b32 m0, s49
	s_nop 0
	global_load_lds_dwordx4 v[214:215], off
	s_waitcnt vmcnt(8)
	s_waitcnt lgkmcnt(0)
	s_barrier
; #define PG8_STAGE(bufoff, gbase, voff) do { _Pragma("unroll") for (int _i = 0; _i < 2; ++_i) \
;         __builtin_amdgcn_global_load_lds((const unsigned*)((const char*)(gbase) + (voff)[_i]), (PG8_LAS unsigned*)(lds + (bufoff) + ldsw + _i * 8192), 16, 0, 0); } while (0)
; #define PG8_LDA(dst, b, h) do { _Pragma("unroll") for (int m = 0; m < 4; ++m) _Pragma("unroll") for (int k = 0; k < 2; ++k) dst[m][k] = *(const PG8_LAS bf16x8*)(lds + PG8_SA(b, h) + aoff + m * 2048 + k * 1024); } while (0)
; #define PG8_MMA(ai, bj, At, Bt) do { __builtin_amdgcn_s_setprio(1); _Pragma("unroll") for (int m = 0; m < 4; ++m) _Pragma("unroll") for (int n = 0; n < 2; ++n) _Pragma("unroll") for (int k = 0; k < 2; ++k) \
;         acc[ai][bj][m][n] = __builtin_amdgcn_mfma_f32_16x16x32_bf16(Bt[n][k], At[m][k], acc[ai][bj][m][n], 0, 0, 0); __builtin_amdgcn_s_setprio(0); } while (0)
; #define PG8_WAIT_V(n) asm volatile("s_waitcnt vmcnt(" #n ")" ::: "memory")
; #define PG8_WAIT_L(n) asm volatile("s_waitcnt lgkmcnt(" #n ")" ::: "memory")
; #define PG8_BAR __builtin_amdgcn_s_barrier()
; #define PG8_SCHED __builtin_amdgcn_sched_barrier(0)
; template <class Epi, class Sched, bool ALIGN_EPI = false, bool SP2 = false>
; __device__ __forceinline__ void gemm_phase(PG8_LAS unsigned char* lds, const Gemm g, const Sched& S, const Epi& E, const int wave_in) {
;     ...
;             PG8_LDA(At, 1, 1); PG8_STAGE(PG8_SB(1, 0), b3, voffB); PG8_STAGE(PG8_SB(1, 1), b3 + hstep, voffB); PG8_STAGE(PG8_SA(1, 0), a3, voffA);
;             PG8_WAIT_V(8); PG8_WAIT_L(0); PG8_BAR; PG8_MMA(1, 0, At, B0); PG8_MMA(1, 1, At, B1); PG8_BAR; PG8_SCHED;
;     ...
; #pragma unroll
;         for (int a = 0; a < 2; ++a)
; #pragma unroll
;             for (int b = 0; b < 2; ++b)
; #pragma unroll
;                 for (int m = 0; m < 4; ++m)
; #pragma unroll
;                     for (int n = 0; n < 2; ++n) acc[a][b][m][n] = (f32x4){0.f, 0.f, 0.f, 0.f};
	s_setprio 1
	s_waitcnt lgkmcnt(0)
	v_mfma_f32_16x16x32_bf16 v[60:63], v[96:99], v[176:179], v[60:63]
	v_mfma_f32_16x16x32_bf16 v[56:59], v[104:107], v[176:179], v[56:59]
	v_mfma_f32_16x16x32_bf16 v[44:47], v[96:99], v[190:193], v[44:47]
	v_mfma_f32_16x16x32_bf16 v[40:43], v[104:107], v[190:193], v[40:43]
	v_mfma_f32_16x16x32_bf16 v[28:31], v[96:99], v[198:201], v[28:31]
	v_mfma_f32_16x16x32_bf16 v[24:27], v[104:107], v[198:201], v[24:27]
	v_mfma_f32_16x16x32_bf16 v[12:15], v[96:99], v[206:209], v[12:15]
	v_mfma_f32_16x16x32_bf16 v[8:11], v[104:107], v[206:209], v[8:11]
	v_mfma_f32_16x16x32_bf16 v[60:63], v[100:103], v[186:189], v[60:63]
	v_mfma_f32_16x16x32_bf16 v[56:59], v[108:111], v[186:189], v[56:59]
	v_mfma_f32_16x16x32_bf16 v[44:47], v[100:103], v[194:197], v[44:47]
	v_mfma_f32_16x16x32_bf16 v[40:43], v[108:111], v[194:197], v[40:43]
	v_mfma_f32_16x16x32_bf16 v[28:31], v[100:103], v[202:205], v[28:31]
	v_mfma_f32_16x16x32_bf16 v[24:27], v[108:111], v[202:205], v[24:27]
	v_mfma_f32_16x16x32_bf16 v[12:15], v[100:103], v[210:213], v[12:15]
	v_mfma_f32_16x16x32_bf16 v[8:11], v[108:111], v[210:213], v[8:11]
	s_setprio 0
	s_setprio 1
	v_mfma_f32_16x16x32_bf16 v[52:55], v[112:115], v[176:179], v[52:55]
	v_mfma_f32_16x16x32_bf16 v[48:51], v[120:123], v[176:179], v[48:51]
	v_mfma_f32_16x16x32_bf16 v[36:39], v[112:115], v[190:193], v[36:39]
	v_mfma_f32_16x16x32_bf16 v[32:35], v[120:123], v[190:193], v[32:35]
	v_mfma_f32_16x16x32_bf16 v[20:23], v[112:115], v[198:201], v[20:23]
	v_mfma_f32_16x16x32_bf16 v[16:19], v[120:123], v[198:201], v[16:19]
	v_mfma_f32_16x16x32_bf16 v[4:7], v[112:115], v[206:209], v[4:7]
	v_mfma_f32_16x16x32_bf16 v[0:3], v[120:123], v[206:209], v[0:3]
	v_mfma_f32_16x16x32_bf16 v[52:55], v[116:119], v[186:189], v[52:55]
	v_mfma_f32_16x16x32_bf16 v[48:51], v[124:127], v[186:189], v[48:51]
	v_mfma_f32_16x16x32_bf16 v[36:39], v[116:119], v[194:197], v[36:39]
	v_mfma_f32_16x16x32_bf16 v[32:35], v[124:127], v[194:197], v[32:35]
	v_mfma_f32_16x16x32_bf16 v[20:23], v[116:119], v[202:205], v[20:23]
	v_mfma_f32_16x16x32_bf16 v[16:19], v[124:127], v[202:205], v[16:19]
	v_mfma_f32_16x16x32_bf16 v[4:7], v[116:119], v[210:213], v[4:7]
	v_mfma_f32_16x16x32_bf16 v[0:3], v[124:127], v[210:213], v[0:3]
	s_setprio 0
	s_barrier
	s_add_u32 s40, s40, 0x100
	s_addc_u32 s41, s41, 0
	s_add_u32 s60, s60, 0x100
	s_addc_u32 s61, s61, 0
	s_cmp_ge_i32 s29, s50
	s_mov_b32 s28, s29
	s_cbranch_scc0 .LBB0_1621
.Lkz_exit_5:
	s_branch .LBB0_1622
.Lkz_skip_5:
	v_mov_b32_e32 v155, 0
	v_mov_b32_e32 v154, v155
	v_mov_b32_e32 v153, v155
	v_mov_b32_e32 v152, v155
	v_mov_b32_e32 v159, v155
	v_mov_b32_e32 v158, v155
	v_mov_b32_e32 v157, v155
	v_mov_b32_e32 v156, v155
	v_mov_b32_e32 v143, v155
	v_mov_b32_e32 v142, v155
	v_mov_b32_e32 v141, v155
	v_mov_b32_e32 v140, v155
	v_mov_b32_e32 v139, v155
	v_mov_b32_e32 v138, v155
	v_mov_b32_e32 v137, v155
	v_mov_b32_e32 v136, v155
	v_mov_b32_e32 v95, v155
	v_mov_b32_e32 v94, v155
	v_mov_b32_e32 v93, v155
	v_mov_b32_e32 v92, v155
	v_mov_b32_e32 v91, v155
	v_mov_b32_e32 v90, v155
	v_mov_b32_e32 v89, v155
	v_mov_b32_e32 v88, v155
	v_mov_b32_e32 v79, v155
	v_mov_b32_e32 v78, v155
	v_mov_b32_e32 v77, v155
	v_mov_b32_e32 v76, v155
	v_mov_b32_e32 v75, v155
	v_mov_b32_e32 v74, v155
	v_mov_b32_e32 v73, v155
	v_mov_b32_e32 v72, v155
	v_mov_b32_e32 v151, v155
	v_mov_b32_e32 v150, v155
	v_mov_b32_e32 v149, v155
	v_mov_b32_e32 v148, v155
	v_mov_b32_e32 v147, v155
	v_mov_b32_e32 v146, v155
	v_mov_b32_e32 v145, v155
	v_mov_b32_e32 v144, v155
	v_mov_b32_e32 v135, v155
	v_mov_b32_e32 v134, v155
	v_mov_b32_e32 v133, v155
	v_mov_b32_e32 v132, v155
	v_mov_b32_e32 v131, v155
	v_mov_b32_e32 v130, v155
	v_mov_b32_e32 v129, v155
	v_mov_b32_e32 v128, v155
	v_mov_b32_e32 v87, v155
	v_mov_b32_e32 v86, v155
	v_mov_b32_e32 v85, v155
	v_mov_b32_e32 v84, v155
	v_mov_b32_e32 v83, v155
	v_mov_b32_e32 v82, v155
	v_mov_b32_e32 v81, v155
	v_mov_b32_e32 v80, v155
	v_mov_b32_e32 v71, v155
	v_mov_b32_e32 v70, v155
	v_mov_b32_e32 v69, v155
	v_mov_b32_e32 v68, v155
	v_mov_b32_e32 v67, v155
	v_mov_b32_e32 v66, v155
	v_mov_b32_e32 v65, v155
	v_mov_b32_e32 v64, v155
	v_mov_b32_e32 v63, v155
	v_mov_b32_e32 v62, v155
	v_mov_b32_e32 v61, v155
	v_mov_b32_e32 v60, v155
	v_mov_b32_e32 v59, v155
	v_mov_b32_e32 v58, v155
	v_mov_b32_e32 v57, v155
	v_mov_b32_e32 v56, v155
	v_mov_b32_e32 v47, v155
	v_mov_b32_e32 v46, v155
	v_mov_b32_e32 v45, v155
	v_mov_b32_e32 v44, v155
	v_mov_b32_e32 v43, v155
	v_mov_b32_e32 v42, v155
	v_mov_b32_e32 v41, v155
	v_mov_b32_e32 v40, v155
	v_mov_b32_e32 v31, v155
	v_mov_b32_e32 v30, v155
	v_mov_b32_e32 v29, v155
	v_mov_b32_e32 v28, v155
	v_mov_b32_e32 v27, v155
	v_mov_b32_e32 v26, v155
	v_mov_b32_e32 v25, v155
	v_mov_b32_e32 v24, v155
	v_mov_b32_e32 v15, v155
	v_mov_b32_e32 v14, v155
	v_mov_b32_e32 v13, v155
	v_mov_b32_e32 v12, v155
	v_mov_b32_e32 v11, v155
	v_mov_b32_e32 v10, v155
	v_mov_b32_e32 v9, v155
	v_mov_b32_e32 v8, v155
	v_mov_b32_e32 v55, v155
	v_mov_b32_e32 v54, v155
	v_mov_b32_e32 v53, v155
	v_mov_b32_e32 v52, v155
	v_mov_b32_e32 v51, v155
	v_mov_b32_e32 v50, v155
	v_mov_b32_e32 v49, v155
	v_mov_b32_e32 v48, v155
	v_mov_b32_e32 v39, v155
	v_mov_b32_e32 v38, v155
	v_mov_b32_e32 v37, v155
	v_mov_b32_e32 v36, v155
	v_mov_b32_e32 v35, v155
	v_mov_b32_e32 v34, v155
	v_mov_b32_e32 v33, v155
	v_mov_b32_e32 v32, v155
	v_mov_b32_e32 v23, v155
	v_mov_b32_e32 v22, v155
	v_mov_b32_e32 v21, v155
	v_mov_b32_e32 v20, v155
	v_mov_b32_e32 v19, v155
	v_mov_b32_e32 v18, v155
	v_mov_b32_e32 v17, v155
	v_mov_b32_e32 v16, v155
	v_mov_b32_e32 v7, v155
	v_mov_b32_e32 v6, v155
	v_mov_b32_e32 v5, v155
	v_mov_b32_e32 v4, v155
	v_mov_b32_e32 v3, v155
	v_mov_b32_e32 v2, v155
	v_mov_b32_e32 v1, v155
	v_mov_b32_e32 v0, v155
